# residual epilogues: the two cross-row LDS shuffles (ds_bpermute xor 16 / xor 32) per row group replaced by v_permlane16_swap / v_permlane32_swap (same pairwise sums, no LDS round trip)
# baseline (speedup 1.0000x reference)
;     __device__ __forceinline__ void operator()(const f32x4 (&acc)[2][2][4][2], const Unit& u, int wr, int wc, int fr, int fq, PG8_LAS unsigned char* lds, int wid) const {
;         const int row0 = u.pm * BM + wr * 64 + fr, col0 = u.pn * BM + wc * 32 + 8 * fq;
;         constexpr float alpha = HALF_ALPHA ? 0.5f : 1.0f;
; #pragma unroll
;         for (int ai = 0; ai < 2; ++ai)
; #pragma unroll
;             for (int m = 0; m < 4; ++m) {
;                 float s = 0.f;
; #pragma unroll
;                 for (int bj = 0; bj < 2; ++bj) {
;                     const size_t off = (size_t)(row0 + ai * HALF + m * 16) * 1024 + col0 + bj * HALF;
;                     f32x4 b0, b1;
;                     if (FIRST) { b0 = *(const f32x4*)(base32 + off); b1 = *(const f32x4*)(base32 + off + 4); }
;                     else { const u32x4 r = *(const u32x4*)(xn + off);
;                         b0 = (f32x4){__uint_as_float(r.x << 16), __uint_as_float(r.x & 0xffff0000u), __uint_as_float(r.y << 16), __uint_as_float(r.y & 0xffff0000u)};
;                         b1 = (f32x4){__uint_as_float(r.z << 16), __uint_as_float(r.z & 0xffff0000u), __uint_as_float(r.w << 16), __uint_as_float(r.w & 0xffff0000u)}; }
;                     const f32x4 v0 = b0 + alpha * acc[ai][bj][m][0], v1 = b1 + alpha * acc[ai][bj][m][1];
;                     if (LAST) { *(f32x4*)(out32 + off) = v0; *(f32x4*)(out32 + off + 4) = v1; }
;                     else {
;                         u32x4 w; w.x = pk_bf16(v0[0], v0[1]); w.y = pk_bf16(v0[2], v0[3]); w.z = pk_bf16(v1[0], v1[1]); w.w = pk_bf16(v1[2], v1[3]);
;                         *(u32x4*)(xn + off) = w;
;                         const float r0 = __uint_as_float(w.x << 16), r1 = __uint_as_float(w.x & 0xffff0000u), r2 = __uint_as_float(w.y << 16), r3 = __uint_as_float(w.y & 0xffff0000u);
;                         const float r4 = __uint_as_float(w.z << 16), r5 = __uint_as_float(w.z & 0xffff0000u), r6 = __uint_as_float(w.w << 16), r7 = __uint_as_float(w.w & 0xffff0000u);
;                         s += (r0 * r0 + r1 * r1) + (r2 * r2 + r3 * r3) + (r4 * r4 + r5 * r5) + (r6 * r6 + r7 * r7);
;                     }
;                 }
;                 if (!LAST) { s += __shfl_xor(s, 16); s += __shfl_xor(s, 32);
;                     if (fq == 0) *(PG8_LAS float*)(lds + PRE_SLOT + 4096 + ((wr * 64 + fr + ai * HALF + m * 16) * 4 + wc) * 4) = s; }
.LBB0_332:
	s_lshl_b32 s28, s77, 8
	v_add_u32_e32 v142, s28, v144
	v_ashrrev_i32_e32 v143, 31, v142
	v_lshl_or_b32 v140, s76, 8, v146
	v_lshlrev_b64 v[160:161], 11, v[142:143]
	v_ashrrev_i32_e32 v141, 31, v140
	v_lshl_add_u64 v[160:161], s[48:49], 0, v[160:161]
	v_lshl_add_u64 v[168:169], v[140:141], 1, v[160:161]
	global_load_dwordx4 v[160:163], v[168:169], off
	global_load_dwordx4 v[164:167], v[168:169], off offset:256
	v_and_b32_e32 v170, 64, v150
	v_add_u32_e32 v178, 64, v170
	v_xor_b32_e32 v159, 16, v150
	v_cmp_lt_i32_e32 vcc, v159, v178
	s_waitcnt vmcnt(0)
	v_lshlrev_b32_e32 v170, 16, v160
	v_and_b32_e32 v171, 0xffff0000, v160
	v_lshlrev_b32_e32 v160, 16, v161
	v_and_b32_e32 v161, 0xffff0000, v161
	v_lshlrev_b32_e32 v172, 16, v162
	v_and_b32_e32 v173, 0xffff0000, v162
	v_lshlrev_b32_e32 v162, 16, v163
	v_and_b32_e32 v163, 0xffff0000, v163
	v_lshlrev_b32_e32 v174, 16, v164
	v_and_b32_e32 v175, 0xffff0000, v164
	v_lshlrev_b32_e32 v164, 16, v165
	v_and_b32_e32 v165, 0xffff0000, v165
	v_lshlrev_b32_e32 v176, 16, v166
	v_and_b32_e32 v177, 0xffff0000, v166
	v_lshlrev_b32_e32 v166, 16, v167
	v_and_b32_e32 v167, 0xffff0000, v167
	v_pk_fma_f32 v[126:127], v[126:127], 0.5, v[160:161] op_sel_hi:[1,0,1]
	v_pk_fma_f32 v[124:125], v[124:125], 0.5, v[170:171] op_sel_hi:[1,0,1]
	v_pk_fma_f32 v[122:123], v[122:123], 0.5, v[162:163] op_sel_hi:[1,0,1]
	v_pk_fma_f32 v[120:121], v[120:121], 0.5, v[172:173] op_sel_hi:[1,0,1]
	v_pk_fma_f32 v[160:161], v[118:119], 0.5, v[164:165] op_sel_hi:[1,0,1]
	v_pk_fma_f32 v[162:163], v[116:117], 0.5, v[174:175] op_sel_hi:[1,0,1]
	v_pk_fma_f32 v[114:115], v[114:115], 0.5, v[166:167] op_sel_hi:[1,0,1]
	v_pk_fma_f32 v[112:113], v[112:113], 0.5, v[176:177] op_sel_hi:[1,0,1]
	v_cvt_pk_bf16_f32 v116, v124, v125
	v_cvt_pk_bf16_f32 v117, v126, v127
	v_cvt_pk_bf16_f32 v118, v120, v121
	v_cvt_pk_bf16_f32 v120, v162, v163
	v_cvt_pk_bf16_f32 v121, v160, v161
	v_cvt_pk_bf16_f32 v119, v122, v123
	v_cvt_pk_bf16_f32 v122, v112, v113
	v_cvt_pk_bf16_f32 v123, v114, v115
	v_and_b32_e32 v113, 0xffff0000, v116
	v_and_b32_e32 v115, 0xffff0000, v117
	v_and_b32_e32 v161, 0xffff0000, v120
	v_and_b32_e32 v163, 0xffff0000, v121
	v_lshlrev_b32_e32 v112, 16, v116
	v_lshlrev_b32_e32 v114, 16, v117
	v_and_b32_e32 v125, 0xffff0000, v118
	v_lshlrev_b32_e32 v160, 16, v120
	v_lshlrev_b32_e32 v162, 16, v121
	v_and_b32_e32 v165, 0xffff0000, v122
	v_mul_f32_e32 v113, v113, v113
	v_mul_f32_e32 v115, v115, v115
	v_mul_f32_e32 v161, v161, v161
	v_mul_f32_e32 v163, v163, v163
	v_lshlrev_b32_e32 v124, 16, v118
	v_and_b32_e32 v127, 0xffff0000, v119
	v_lshlrev_b32_e32 v164, 16, v122
	v_and_b32_e32 v167, 0xffff0000, v123
	v_mul_f32_e32 v125, v125, v125
	v_mul_f32_e32 v165, v165, v165
	v_fmac_f32_e32 v113, v112, v112
	v_fmac_f32_e32 v115, v114, v114
	v_fmac_f32_e32 v161, v160, v160
	v_fmac_f32_e32 v163, v162, v162
	v_lshlrev_b32_e32 v126, 16, v119
	v_lshlrev_b32_e32 v166, 16, v123
	v_mul_f32_e32 v127, v127, v127
	v_mul_f32_e32 v167, v167, v167
	v_fmac_f32_e32 v125, v124, v124
	v_fmac_f32_e32 v165, v164, v164
	v_add_f32_e32 v112, v113, v115
	v_add_f32_e32 v113, v161, v163
	v_fmac_f32_e32 v127, v126, v126
	v_fmac_f32_e32 v167, v166, v166
	v_add_f32_e32 v112, v125, v112
	v_add_f32_e32 v113, v165, v113
	v_cndmask_b32_e32 v159, v150, v159, vcc
	v_add_f32_e32 v112, v127, v112
	v_add_f32_e32 v113, v167, v113
	v_lshlrev_b32_e32 v159, 2, v159
	v_add_f32_e32 v113, v112, v113
	v_mov_b32_e32 v114, v113
	v_mov_b32_e32 v159, v113
	s_nop 1
	v_permlane16_swap_b32_e32 v114, v159
	v_xor_b32_e32 v112, 32, v150
	v_cmp_lt_i32_e32 vcc, v112, v178
	global_store_dwordx4 v[168:169], v[116:119], off
	global_store_dwordx4 v[168:169], v[120:123], off offset:256
	v_cndmask_b32_e32 v112, v150, v112, vcc
	v_lshlrev_b32_e32 v112, 2, v112
	s_waitcnt lgkmcnt(0)
	v_add_f32_e32 v113, v159, v114
	v_mov_b32_e32 v114, v113
	v_mov_b32_e32 v112, v113
	s_nop 1
	v_permlane32_swap_b32_e32 v114, v112
	s_and_saveexec_b64 s[30:31], s[6:7]
	s_cbranch_execz .LBB0_334
	s_waitcnt lgkmcnt(0)
	v_add_f32_e32 v113, v112, v114
	ds_write_b32 v151, v113
.LBB0_334:
	s_or_b64 exec, exec, s[30:31]
	s_waitcnt lgkmcnt(0)
	v_or_b32_e32 v114, 16, v142
	v_ashrrev_i32_e32 v115, 31, v114
	v_lshlrev_b64 v[114:115], 11, v[114:115]
	v_lshl_add_u64 v[114:115], s[48:49], 0, v[114:115]
	v_lshl_add_u64 v[122:123], v[140:141], 1, v[114:115]
	global_load_dwordx4 v[114:117], v[122:123], off
	global_load_dwordx4 v[118:121], v[122:123], off offset:256
	s_waitcnt vmcnt(1)
	v_lshlrev_b32_e32 v124, 16, v114
	v_and_b32_e32 v125, 0xffff0000, v114
	v_lshlrev_b32_e32 v114, 16, v115
	v_and_b32_e32 v115, 0xffff0000, v115
	s_waitcnt vmcnt(0)
; #define PG8_LAS __attribute__((address_space(3)))
;     __device__ __forceinline__ void operator()(const f32x4 (&acc)[2][2][4][2], const Unit& u, int wr, int wc, int fr, int fq, PG8_LAS unsigned char* lds, int wid) const {
;     ...
;                 float s = 0.f;
; #pragma unroll
;                 for (int bj = 0; bj < 2; ++bj) {
;                     const size_t off = (size_t)(row0 + ai * HALF + m * 16) * 1024 + col0 + bj * HALF;
;                     f32x4 b0, b1;
;                     if (FIRST) { b0 = *(const f32x4*)(base32 + off); b1 = *(const f32x4*)(base32 + off + 4); }
;                     else { const u32x4 r = *(const u32x4*)(xn + off);
;                         b0 = (f32x4){__uint_as_float(r.x << 16), __uint_as_float(r.x & 0xffff0000u), __uint_as_float(r.y << 16), __uint_as_float(r.y & 0xffff0000u)};
;                         b1 = (f32x4){__uint_as_float(r.z << 16), __uint_as_float(r.z & 0xffff0000u), __uint_as_float(r.w << 16), __uint_as_float(r.w & 0xffff0000u)}; }
;                     const f32x4 v0 = b0 + alpha * acc[ai][bj][m][0], v1 = b1 + alpha * acc[ai][bj][m][1];
;                     if (LAST) { *(f32x4*)(out32 + off) = v0; *(f32x4*)(out32 + off + 4) = v1; }
;                     else {
;                         u32x4 w; w.x = pk_bf16(v0[0], v0[1]); w.y = pk_bf16(v0[2], v0[3]); w.z = pk_bf16(v1[0], v1[1]); w.w = pk_bf16(v1[2], v1[3]);
;                         *(u32x4*)(xn + off) = w;
;                         const float r0 = __uint_as_float(w.x << 16), r1 = __uint_as_float(w.x & 0xffff0000u), r2 = __uint_as_float(w.y << 16), r3 = __uint_as_float(w.y & 0xffff0000u);
;                         const float r4 = __uint_as_float(w.z << 16), r5 = __uint_as_float(w.z & 0xffff0000u), r6 = __uint_as_float(w.w << 16), r7 = __uint_as_float(w.w & 0xffff0000u);
;                         s += (r0 * r0 + r1 * r1) + (r2 * r2 + r3 * r3) + (r4 * r4 + r5 * r5) + (r6 * r6 + r7 * r7);
;                     }
;                 }
;                 if (!LAST) { s += __shfl_xor(s, 16); s += __shfl_xor(s, 32);
;                     if (fq == 0) *(PG8_LAS float*)(lds + PRE_SLOT + 4096 + ((wr * 64 + fr + ai * HALF + m * 16) * 4 + wc) * 4) = s; }
	v_lshlrev_b32_e32 v160, 16, v118
	v_and_b32_e32 v161, 0xffff0000, v118
	v_lshlrev_b32_e32 v118, 16, v119
	v_and_b32_e32 v119, 0xffff0000, v119
	v_lshlrev_b32_e32 v126, 16, v116
	v_and_b32_e32 v127, 0xffff0000, v116
	v_lshlrev_b32_e32 v116, 16, v117
	v_and_b32_e32 v117, 0xffff0000, v117
	v_lshlrev_b32_e32 v162, 16, v120
	v_and_b32_e32 v163, 0xffff0000, v120
	v_lshlrev_b32_e32 v120, 16, v121
	v_and_b32_e32 v121, 0xffff0000, v121
	v_pk_fma_f32 v[110:111], v[110:111], 0.5, v[114:115] op_sel_hi:[1,0,1]
	v_pk_fma_f32 v[108:109], v[108:109], 0.5, v[124:125] op_sel_hi:[1,0,1]
	v_pk_fma_f32 v[114:115], v[102:103], 0.5, v[118:119] op_sel_hi:[1,0,1]
	v_pk_fma_f32 v[102:103], v[100:101], 0.5, v[160:161] op_sel_hi:[1,0,1]
	v_pk_fma_f32 v[106:107], v[106:107], 0.5, v[116:117] op_sel_hi:[1,0,1]
	v_pk_fma_f32 v[104:105], v[104:105], 0.5, v[126:127] op_sel_hi:[1,0,1]
	v_pk_fma_f32 v[116:117], v[98:99], 0.5, v[120:121] op_sel_hi:[1,0,1]
	v_pk_fma_f32 v[96:97], v[96:97], 0.5, v[162:163] op_sel_hi:[1,0,1]
	v_cvt_pk_bf16_f32 v98, v108, v109
	v_cvt_pk_bf16_f32 v99, v110, v111
	v_cvt_pk_bf16_f32 v102, v102, v103
	v_cvt_pk_bf16_f32 v103, v114, v115
	v_cvt_pk_bf16_f32 v100, v104, v105
	v_cvt_pk_bf16_f32 v101, v106, v107
	v_cvt_pk_bf16_f32 v104, v96, v97
	v_cvt_pk_bf16_f32 v105, v116, v117
	v_and_b32_e32 v97, 0xffff0000, v98
	v_and_b32_e32 v107, 0xffff0000, v99
	v_and_b32_e32 v114, 0xffff0000, v102
	v_and_b32_e32 v116, 0xffff0000, v103
	v_lshlrev_b32_e32 v96, 16, v98
	v_lshlrev_b32_e32 v106, 16, v99
	v_and_b32_e32 v109, 0xffff0000, v100
	v_lshlrev_b32_e32 v113, 16, v102
	v_lshlrev_b32_e32 v115, 16, v103
	v_and_b32_e32 v118, 0xffff0000, v104
	v_mul_f32_e32 v97, v97, v97
	v_mul_f32_e32 v107, v107, v107
	v_mul_f32_e32 v114, v114, v114
	v_mul_f32_e32 v116, v116, v116
	v_lshlrev_b32_e32 v108, 16, v100
	v_and_b32_e32 v111, 0xffff0000, v101
	v_lshlrev_b32_e32 v117, 16, v104
	v_and_b32_e32 v120, 0xffff0000, v105
	v_mul_f32_e32 v109, v109, v109
	v_mul_f32_e32 v118, v118, v118
	v_fmac_f32_e32 v97, v96, v96
	v_fmac_f32_e32 v107, v106, v106
	v_fmac_f32_e32 v114, v113, v113
	v_fmac_f32_e32 v116, v115, v115
	v_lshlrev_b32_e32 v110, 16, v101
	v_lshlrev_b32_e32 v119, 16, v105
	v_mul_f32_e32 v111, v111, v111
	v_mul_f32_e32 v120, v120, v120
	v_fmac_f32_e32 v109, v108, v108
	v_fmac_f32_e32 v118, v117, v117
	v_add_f32_e32 v96, v97, v107
	v_add_f32_e32 v97, v114, v116
	v_fmac_f32_e32 v111, v110, v110
	v_fmac_f32_e32 v120, v119, v119
	v_add_f32_e32 v96, v109, v96
	v_add_f32_e32 v97, v118, v97
	v_add_f32_e32 v96, v111, v96
	v_add_f32_e32 v97, v120, v97
	v_add_f32_e32 v96, v96, v97
	v_mov_b32_e32 v97, v96
	v_mov_b32_e32 v159, v96
	s_nop 1
	v_permlane16_swap_b32_e32 v97, v159
	global_store_dwordx4 v[122:123], v[98:101], off
	global_store_dwordx4 v[122:123], v[102:105], off offset:256
	s_waitcnt lgkmcnt(0)
	v_add_f32_e32 v96, v159, v97
	v_mov_b32_e32 v97, v96
	v_mov_b32_e32 v112, v96
	s_nop 1
	v_permlane32_swap_b32_e32 v97, v112
	s_and_saveexec_b64 s[30:31], s[6:7]
	s_cbranch_execz .LBB0_336
	s_waitcnt lgkmcnt(0)
	v_add_f32_e32 v96, v112, v97
	ds_write_b32 v152, v96
.LBB0_336:
	s_or_b64 exec, exec, s[30:31]
	v_or_b32_e32 v96, 32, v142
	s_waitcnt lgkmcnt(0)
	v_ashrrev_i32_e32 v97, 31, v96
	v_lshlrev_b64 v[96:97], 11, v[96:97]
	v_lshl_add_u64 v[96:97], s[48:49], 0, v[96:97]
	v_lshl_add_u64 v[104:105], v[140:141], 1, v[96:97]
	global_load_dwordx4 v[96:99], v[104:105], off
	global_load_dwordx4 v[100:103], v[104:105], off offset:256
	s_waitcnt vmcnt(1)
	v_lshlrev_b32_e32 v106, 16, v96
	v_and_b32_e32 v107, 0xffff0000, v96
	v_lshlrev_b32_e32 v96, 16, v97
	v_and_b32_e32 v97, 0xffff0000, v97
	s_waitcnt vmcnt(0)
	v_lshlrev_b32_e32 v110, 16, v100
	v_and_b32_e32 v111, 0xffff0000, v100
	v_lshlrev_b32_e32 v100, 16, v101
	v_and_b32_e32 v101, 0xffff0000, v101
	v_lshlrev_b32_e32 v108, 16, v98
	v_and_b32_e32 v109, 0xffff0000, v98
	v_lshlrev_b32_e32 v98, 16, v99
	v_and_b32_e32 v99, 0xffff0000, v99
	v_lshlrev_b32_e32 v114, 16, v102
	v_and_b32_e32 v115, 0xffff0000, v102
	v_lshlrev_b32_e32 v102, 16, v103
	v_and_b32_e32 v103, 0xffff0000, v103
	v_pk_fma_f32 v[94:95], v[94:95], 0.5, v[96:97] op_sel_hi:[1,0,1]
	v_pk_fma_f32 v[92:93], v[92:93], 0.5, v[106:107] op_sel_hi:[1,0,1]
	v_pk_fma_f32 v[96:97], v[86:87], 0.5, v[100:101] op_sel_hi:[1,0,1]
	v_pk_fma_f32 v[86:87], v[84:85], 0.5, v[110:111] op_sel_hi:[1,0,1]
	v_pk_fma_f32 v[90:91], v[90:91], 0.5, v[98:99] op_sel_hi:[1,0,1]
	v_pk_fma_f32 v[88:89], v[88:89], 0.5, v[108:109] op_sel_hi:[1,0,1]
	v_pk_fma_f32 v[98:99], v[82:83], 0.5, v[102:103] op_sel_hi:[1,0,1]
	v_pk_fma_f32 v[80:81], v[80:81], 0.5, v[114:115] op_sel_hi:[1,0,1]
	v_cvt_pk_bf16_f32 v82, v92, v93
	v_cvt_pk_bf16_f32 v83, v94, v95
	v_cvt_pk_bf16_f32 v86, v86, v87
	v_cvt_pk_bf16_f32 v87, v96, v97
	v_cvt_pk_bf16_f32 v84, v88, v89
	v_cvt_pk_bf16_f32 v85, v90, v91
	v_cvt_pk_bf16_f32 v88, v80, v81
	v_cvt_pk_bf16_f32 v89, v98, v99
	v_and_b32_e32 v81, 0xffff0000, v82
	v_and_b32_e32 v91, 0xffff0000, v83
	v_and_b32_e32 v97, 0xffff0000, v86
	v_and_b32_e32 v99, 0xffff0000, v87
	v_lshlrev_b32_e32 v80, 16, v82
	v_lshlrev_b32_e32 v90, 16, v83
	v_and_b32_e32 v93, 0xffff0000, v84
	v_lshlrev_b32_e32 v96, 16, v86
	v_lshlrev_b32_e32 v98, 16, v87
	v_and_b32_e32 v101, 0xffff0000, v88
	v_mul_f32_e32 v81, v81, v81
	v_mul_f32_e32 v91, v91, v91
	v_mul_f32_e32 v97, v97, v97
	v_mul_f32_e32 v99, v99, v99
	v_lshlrev_b32_e32 v92, 16, v84
	v_and_b32_e32 v95, 0xffff0000, v85
	v_lshlrev_b32_e32 v100, 16, v88
	v_and_b32_e32 v103, 0xffff0000, v89
	v_mul_f32_e32 v93, v93, v93
	v_mul_f32_e32 v101, v101, v101
	v_fmac_f32_e32 v81, v80, v80
	v_fmac_f32_e32 v91, v90, v90
	v_fmac_f32_e32 v97, v96, v96
	v_fmac_f32_e32 v99, v98, v98
	v_lshlrev_b32_e32 v94, 16, v85
	v_lshlrev_b32_e32 v102, 16, v89
	v_mul_f32_e32 v95, v95, v95
	v_mul_f32_e32 v103, v103, v103
	v_fmac_f32_e32 v93, v92, v92
	v_fmac_f32_e32 v101, v100, v100
	v_add_f32_e32 v80, v81, v91
	v_add_f32_e32 v81, v97, v99
	v_fmac_f32_e32 v95, v94, v94
	v_fmac_f32_e32 v103, v102, v102
	v_add_f32_e32 v80, v93, v80
	v_add_f32_e32 v81, v101, v81
	v_add_f32_e32 v80, v95, v80
	v_add_f32_e32 v81, v103, v81
	v_add_f32_e32 v80, v80, v81
	v_mov_b32_e32 v81, v80
	v_mov_b32_e32 v159, v80
	s_nop 1
	v_permlane16_swap_b32_e32 v81, v159
	global_store_dwordx4 v[104:105], v[82:85], off
	global_store_dwordx4 v[104:105], v[86:89], off offset:256
	s_waitcnt lgkmcnt(0)
	v_add_f32_e32 v80, v159, v81
	v_mov_b32_e32 v81, v80
	v_mov_b32_e32 v112, v80
	s_nop 1
	v_permlane32_swap_b32_e32 v81, v112
	s_and_saveexec_b64 s[30:31], s[6:7]
	s_cbranch_execz .LBB0_338
	s_waitcnt lgkmcnt(0)
	v_add_f32_e32 v80, v112, v81
	ds_write_b32 v153, v80
; #define PG8_LAS __attribute__((address_space(3)))
;     __device__ __forceinline__ void operator()(const f32x4 (&acc)[2][2][4][2], const Unit& u, int wr, int wc, int fr, int fq, PG8_LAS unsigned char* lds, int wid) const {
;     ...
;                 float s = 0.f;
; #pragma unroll
;                 for (int bj = 0; bj < 2; ++bj) {
;                     const size_t off = (size_t)(row0 + ai * HALF + m * 16) * 1024 + col0 + bj * HALF;
;                     f32x4 b0, b1;
;                     if (FIRST) { b0 = *(const f32x4*)(base32 + off); b1 = *(const f32x4*)(base32 + off + 4); }
;                     else { const u32x4 r = *(const u32x4*)(xn + off);
;                         b0 = (f32x4){__uint_as_float(r.x << 16), __uint_as_float(r.x & 0xffff0000u), __uint_as_float(r.y << 16), __uint_as_float(r.y & 0xffff0000u)};
;                         b1 = (f32x4){__uint_as_float(r.z << 16), __uint_as_float(r.z & 0xffff0000u), __uint_as_float(r.w << 16), __uint_as_float(r.w & 0xffff0000u)}; }
;                     const f32x4 v0 = b0 + alpha * acc[ai][bj][m][0], v1 = b1 + alpha * acc[ai][bj][m][1];
;                     if (LAST) { *(f32x4*)(out32 + off) = v0; *(f32x4*)(out32 + off + 4) = v1; }
;                     else {
;                         u32x4 w; w.x = pk_bf16(v0[0], v0[1]); w.y = pk_bf16(v0[2], v0[3]); w.z = pk_bf16(v1[0], v1[1]); w.w = pk_bf16(v1[2], v1[3]);
;                         *(u32x4*)(xn + off) = w;
;                         const float r0 = __uint_as_float(w.x << 16), r1 = __uint_as_float(w.x & 0xffff0000u), r2 = __uint_as_float(w.y << 16), r3 = __uint_as_float(w.y & 0xffff0000u);
;                         const float r4 = __uint_as_float(w.z << 16), r5 = __uint_as_float(w.z & 0xffff0000u), r6 = __uint_as_float(w.w << 16), r7 = __uint_as_float(w.w & 0xffff0000u);
;                         s += (r0 * r0 + r1 * r1) + (r2 * r2 + r3 * r3) + (r4 * r4 + r5 * r5) + (r6 * r6 + r7 * r7);
;                     }
;                 }
;                 if (!LAST) { s += __shfl_xor(s, 16); s += __shfl_xor(s, 32);
;                     if (fq == 0) *(PG8_LAS float*)(lds + PRE_SLOT + 4096 + ((wr * 64 + fr + ai * HALF + m * 16) * 4 + wc) * 4) = s; }
.LBB0_338:
	s_or_b64 exec, exec, s[30:31]
	v_or_b32_e32 v80, 48, v142
	s_waitcnt lgkmcnt(0)
	v_ashrrev_i32_e32 v81, 31, v80
	v_lshlrev_b64 v[80:81], 11, v[80:81]
	v_lshl_add_u64 v[80:81], s[48:49], 0, v[80:81]
	v_lshl_add_u64 v[88:89], v[140:141], 1, v[80:81]
	global_load_dwordx4 v[80:83], v[88:89], off
	global_load_dwordx4 v[84:87], v[88:89], off offset:256
	s_waitcnt vmcnt(1)
	v_lshlrev_b32_e32 v90, 16, v80
	v_and_b32_e32 v91, 0xffff0000, v80
	v_lshlrev_b32_e32 v80, 16, v81
	v_and_b32_e32 v81, 0xffff0000, v81
	s_waitcnt vmcnt(0)
	v_lshlrev_b32_e32 v94, 16, v84
	v_and_b32_e32 v95, 0xffff0000, v84
	v_lshlrev_b32_e32 v84, 16, v85
	v_and_b32_e32 v85, 0xffff0000, v85
	v_lshlrev_b32_e32 v92, 16, v82
	v_and_b32_e32 v93, 0xffff0000, v82
	v_lshlrev_b32_e32 v82, 16, v83
	v_and_b32_e32 v83, 0xffff0000, v83
	v_lshlrev_b32_e32 v96, 16, v86
	v_and_b32_e32 v97, 0xffff0000, v86
	v_lshlrev_b32_e32 v86, 16, v87
	v_and_b32_e32 v87, 0xffff0000, v87
	v_pk_fma_f32 v[78:79], v[78:79], 0.5, v[80:81] op_sel_hi:[1,0,1]
	v_pk_fma_f32 v[76:77], v[76:77], 0.5, v[90:91] op_sel_hi:[1,0,1]
	v_pk_fma_f32 v[80:81], v[70:71], 0.5, v[84:85] op_sel_hi:[1,0,1]
	v_pk_fma_f32 v[70:71], v[68:69], 0.5, v[94:95] op_sel_hi:[1,0,1]
	v_pk_fma_f32 v[74:75], v[74:75], 0.5, v[82:83] op_sel_hi:[1,0,1]
	v_pk_fma_f32 v[72:73], v[72:73], 0.5, v[92:93] op_sel_hi:[1,0,1]
	v_pk_fma_f32 v[82:83], v[66:67], 0.5, v[86:87] op_sel_hi:[1,0,1]
	v_pk_fma_f32 v[64:65], v[64:65], 0.5, v[96:97] op_sel_hi:[1,0,1]
	v_cvt_pk_bf16_f32 v66, v76, v77
	v_cvt_pk_bf16_f32 v67, v78, v79
	v_cvt_pk_bf16_f32 v70, v70, v71
	v_cvt_pk_bf16_f32 v71, v80, v81
	v_cvt_pk_bf16_f32 v68, v72, v73
	v_cvt_pk_bf16_f32 v69, v74, v75
	v_cvt_pk_bf16_f32 v72, v64, v65
	v_cvt_pk_bf16_f32 v73, v82, v83
	v_and_b32_e32 v65, 0xffff0000, v66
	v_and_b32_e32 v75, 0xffff0000, v67
	v_and_b32_e32 v81, 0xffff0000, v70
	v_and_b32_e32 v83, 0xffff0000, v71
	v_lshlrev_b32_e32 v64, 16, v66
	v_lshlrev_b32_e32 v74, 16, v67
	v_and_b32_e32 v77, 0xffff0000, v68
	v_lshlrev_b32_e32 v80, 16, v70
	v_lshlrev_b32_e32 v82, 16, v71
	v_and_b32_e32 v85, 0xffff0000, v72
	v_mul_f32_e32 v65, v65, v65
	v_mul_f32_e32 v75, v75, v75
	v_mul_f32_e32 v81, v81, v81
	v_mul_f32_e32 v83, v83, v83
	v_lshlrev_b32_e32 v76, 16, v68
	v_and_b32_e32 v79, 0xffff0000, v69
	v_lshlrev_b32_e32 v84, 16, v72
	v_and_b32_e32 v87, 0xffff0000, v73
	v_mul_f32_e32 v77, v77, v77
	v_mul_f32_e32 v85, v85, v85
	v_fmac_f32_e32 v65, v64, v64
	v_fmac_f32_e32 v75, v74, v74
	v_fmac_f32_e32 v81, v80, v80
	v_fmac_f32_e32 v83, v82, v82
	v_lshlrev_b32_e32 v78, 16, v69
	v_lshlrev_b32_e32 v86, 16, v73
	v_mul_f32_e32 v79, v79, v79
	v_mul_f32_e32 v87, v87, v87
	v_fmac_f32_e32 v77, v76, v76
	v_fmac_f32_e32 v85, v84, v84
	v_add_f32_e32 v64, v65, v75
	v_add_f32_e32 v65, v81, v83
	v_fmac_f32_e32 v79, v78, v78
	v_fmac_f32_e32 v87, v86, v86
	v_add_f32_e32 v64, v77, v64
	v_add_f32_e32 v65, v85, v65
	v_add_f32_e32 v64, v79, v64
	v_add_f32_e32 v65, v87, v65
	v_add_f32_e32 v64, v64, v65
	v_mov_b32_e32 v65, v64
	v_mov_b32_e32 v159, v64
	s_nop 1
	v_permlane16_swap_b32_e32 v65, v159
	global_store_dwordx4 v[88:89], v[66:69], off
	global_store_dwordx4 v[88:89], v[70:73], off offset:256
	s_waitcnt lgkmcnt(0)
	v_add_f32_e32 v64, v159, v65
	v_mov_b32_e32 v65, v64
	v_mov_b32_e32 v112, v64
	s_nop 1
	v_permlane32_swap_b32_e32 v65, v112
	s_and_saveexec_b64 s[30:31], s[6:7]
	s_cbranch_execz .LBB0_340
	s_waitcnt lgkmcnt(0)
	v_add_f32_e32 v64, v112, v65
	ds_write_b32 v154, v64
.LBB0_340:
	s_or_b64 exec, exec, s[30:31]
	s_waitcnt lgkmcnt(0)
	v_lshlrev_b64 v[64:65], 11, v[142:143]
	v_lshl_add_u64 v[64:65], s[48:49], 0, v[64:65]
	v_lshl_add_u64 v[64:65], v[140:141], 1, v[64:65]
	v_add_co_u32_e32 v74, vcc, 0x40000, v64
	v_lshl_add_u64 v[76:77], v[64:65], 0, s[18:19]
	s_nop 0
	v_addc_co_u32_e32 v75, vcc, 0, v65, vcc
	global_load_dwordx4 v[66:69], v[74:75], off
	global_load_dwordx4 v[70:73], v[76:77], off offset:256
	s_waitcnt vmcnt(1)
	v_lshlrev_b32_e32 v78, 16, v66
	v_and_b32_e32 v79, 0xffff0000, v66
	v_lshlrev_b32_e32 v66, 16, v67
	v_and_b32_e32 v67, 0xffff0000, v67
	s_waitcnt vmcnt(0)
	v_lshlrev_b32_e32 v82, 16, v70
	v_and_b32_e32 v83, 0xffff0000, v70
	v_lshlrev_b32_e32 v70, 16, v71
	v_and_b32_e32 v71, 0xffff0000, v71
	v_lshlrev_b32_e32 v80, 16, v68
	v_and_b32_e32 v81, 0xffff0000, v68
	v_lshlrev_b32_e32 v68, 16, v69
	v_and_b32_e32 v69, 0xffff0000, v69
	v_lshlrev_b32_e32 v84, 16, v72
	v_and_b32_e32 v85, 0xffff0000, v72
	v_lshlrev_b32_e32 v72, 16, v73
	v_and_b32_e32 v73, 0xffff0000, v73
	v_pk_fma_f32 v[62:63], v[62:63], 0.5, v[66:67] op_sel_hi:[1,0,1]
	v_pk_fma_f32 v[60:61], v[60:61], 0.5, v[78:79] op_sel_hi:[1,0,1]
	v_pk_fma_f32 v[66:67], v[54:55], 0.5, v[70:71] op_sel_hi:[1,0,1]
	v_pk_fma_f32 v[54:55], v[52:53], 0.5, v[82:83] op_sel_hi:[1,0,1]
	v_pk_fma_f32 v[58:59], v[58:59], 0.5, v[68:69] op_sel_hi:[1,0,1]
	v_pk_fma_f32 v[56:57], v[56:57], 0.5, v[80:81] op_sel_hi:[1,0,1]
	v_pk_fma_f32 v[68:69], v[50:51], 0.5, v[72:73] op_sel_hi:[1,0,1]
	v_pk_fma_f32 v[48:49], v[48:49], 0.5, v[84:85] op_sel_hi:[1,0,1]
	v_cvt_pk_bf16_f32 v50, v60, v61
	v_cvt_pk_bf16_f32 v51, v62, v63
	v_cvt_pk_bf16_f32 v54, v54, v55
	v_cvt_pk_bf16_f32 v55, v66, v67
	v_cvt_pk_bf16_f32 v52, v56, v57
	v_cvt_pk_bf16_f32 v53, v58, v59
	v_cvt_pk_bf16_f32 v56, v48, v49
	v_cvt_pk_bf16_f32 v57, v68, v69
	v_and_b32_e32 v49, 0xffff0000, v50
	v_and_b32_e32 v59, 0xffff0000, v51
	v_and_b32_e32 v67, 0xffff0000, v54
	v_and_b32_e32 v69, 0xffff0000, v55
	v_lshlrev_b32_e32 v48, 16, v50
	v_lshlrev_b32_e32 v58, 16, v51
	v_and_b32_e32 v61, 0xffff0000, v52
	v_lshlrev_b32_e32 v66, 16, v54
	v_lshlrev_b32_e32 v68, 16, v55
	v_and_b32_e32 v71, 0xffff0000, v56
	v_mul_f32_e32 v49, v49, v49
	v_mul_f32_e32 v59, v59, v59
	v_mul_f32_e32 v67, v67, v67
	v_mul_f32_e32 v69, v69, v69
	v_lshlrev_b32_e32 v60, 16, v52
	v_and_b32_e32 v63, 0xffff0000, v53
	v_lshlrev_b32_e32 v70, 16, v56
	v_and_b32_e32 v73, 0xffff0000, v57
	v_mul_f32_e32 v61, v61, v61
	v_mul_f32_e32 v71, v71, v71
	v_fmac_f32_e32 v49, v48, v48
	v_fmac_f32_e32 v59, v58, v58
	v_fmac_f32_e32 v67, v66, v66
	v_fmac_f32_e32 v69, v68, v68
	v_lshlrev_b32_e32 v62, 16, v53
	v_lshlrev_b32_e32 v72, 16, v57
	v_mul_f32_e32 v63, v63, v63
	v_mul_f32_e32 v73, v73, v73
	v_fmac_f32_e32 v61, v60, v60
	v_fmac_f32_e32 v71, v70, v70
	v_add_f32_e32 v48, v49, v59
	v_add_f32_e32 v49, v67, v69
	v_fmac_f32_e32 v63, v62, v62
	v_fmac_f32_e32 v73, v72, v72
	v_add_f32_e32 v48, v61, v48
	v_add_f32_e32 v49, v71, v49
	v_add_f32_e32 v48, v63, v48
	v_add_f32_e32 v49, v73, v49
	v_add_f32_e32 v48, v48, v49
	v_mov_b32_e32 v49, v48
	v_mov_b32_e32 v159, v48
	s_nop 1
	v_permlane16_swap_b32_e32 v49, v159
	global_store_dwordx4 v[74:75], v[50:53], off
	global_store_dwordx4 v[76:77], v[54:57], off offset:256
	s_waitcnt lgkmcnt(0)
	v_add_f32_e32 v48, v159, v49
	v_mov_b32_e32 v49, v48
	v_mov_b32_e32 v112, v48
	s_nop 1
	v_permlane32_swap_b32_e32 v49, v112
	s_and_saveexec_b64 s[30:31], s[6:7]
	s_cbranch_execz .LBB0_342
	s_waitcnt lgkmcnt(0)
	v_add_f32_e32 v48, v112, v49
	ds_write_b32 v155, v48
; #define PG8_LAS __attribute__((address_space(3)))
;     __device__ __forceinline__ void operator()(const f32x4 (&acc)[2][2][4][2], const Unit& u, int wr, int wc, int fr, int fq, PG8_LAS unsigned char* lds, int wid) const {
;     ...
;                 float s = 0.f;
; #pragma unroll
;                 for (int bj = 0; bj < 2; ++bj) {
;                     const size_t off = (size_t)(row0 + ai * HALF + m * 16) * 1024 + col0 + bj * HALF;
;                     f32x4 b0, b1;
;                     if (FIRST) { b0 = *(const f32x4*)(base32 + off); b1 = *(const f32x4*)(base32 + off + 4); }
;                     else { const u32x4 r = *(const u32x4*)(xn + off);
;                         b0 = (f32x4){__uint_as_float(r.x << 16), __uint_as_float(r.x & 0xffff0000u), __uint_as_float(r.y << 16), __uint_as_float(r.y & 0xffff0000u)};
;                         b1 = (f32x4){__uint_as_float(r.z << 16), __uint_as_float(r.z & 0xffff0000u), __uint_as_float(r.w << 16), __uint_as_float(r.w & 0xffff0000u)}; }
;                     const f32x4 v0 = b0 + alpha * acc[ai][bj][m][0], v1 = b1 + alpha * acc[ai][bj][m][1];
;                     if (LAST) { *(f32x4*)(out32 + off) = v0; *(f32x4*)(out32 + off + 4) = v1; }
;                     else {
;                         u32x4 w; w.x = pk_bf16(v0[0], v0[1]); w.y = pk_bf16(v0[2], v0[3]); w.z = pk_bf16(v1[0], v1[1]); w.w = pk_bf16(v1[2], v1[3]);
;                         *(u32x4*)(xn + off) = w;
;                         const float r0 = __uint_as_float(w.x << 16), r1 = __uint_as_float(w.x & 0xffff0000u), r2 = __uint_as_float(w.y << 16), r3 = __uint_as_float(w.y & 0xffff0000u);
;                         const float r4 = __uint_as_float(w.z << 16), r5 = __uint_as_float(w.z & 0xffff0000u), r6 = __uint_as_float(w.w << 16), r7 = __uint_as_float(w.w & 0xffff0000u);
;                         s += (r0 * r0 + r1 * r1) + (r2 * r2 + r3 * r3) + (r4 * r4 + r5 * r5) + (r6 * r6 + r7 * r7);
;                     }
;                 }
;                 if (!LAST) { s += __shfl_xor(s, 16); s += __shfl_xor(s, 32);
;                     if (fq == 0) *(PG8_LAS float*)(lds + PRE_SLOT + 4096 + ((wr * 64 + fr + ai * HALF + m * 16) * 4 + wc) * 4) = s; }
.LBB0_342:
	s_or_b64 exec, exec, s[30:31]
	v_add_co_u32_e32 v56, vcc, 0x48000, v64
	v_lshl_add_u64 v[58:59], v[64:65], 0, s[20:21]
	s_nop 0
	v_addc_co_u32_e32 v57, vcc, 0, v65, vcc
	s_waitcnt lgkmcnt(0)
	global_load_dwordx4 v[48:51], v[56:57], off
	global_load_dwordx4 v[52:55], v[58:59], off offset:256
	s_waitcnt vmcnt(1)
	v_lshlrev_b32_e32 v60, 16, v48
	v_and_b32_e32 v61, 0xffff0000, v48
	v_lshlrev_b32_e32 v48, 16, v49
	v_and_b32_e32 v49, 0xffff0000, v49
	s_waitcnt vmcnt(0)
	v_lshlrev_b32_e32 v64, 16, v52
	v_and_b32_e32 v65, 0xffff0000, v52
	v_lshlrev_b32_e32 v52, 16, v53
	v_and_b32_e32 v53, 0xffff0000, v53
	v_lshlrev_b32_e32 v62, 16, v50
	v_and_b32_e32 v63, 0xffff0000, v50
	v_lshlrev_b32_e32 v50, 16, v51
	v_and_b32_e32 v51, 0xffff0000, v51
	v_lshlrev_b32_e32 v66, 16, v54
	v_and_b32_e32 v67, 0xffff0000, v54
	v_lshlrev_b32_e32 v54, 16, v55
	v_and_b32_e32 v55, 0xffff0000, v55
	v_pk_fma_f32 v[46:47], v[46:47], 0.5, v[48:49] op_sel_hi:[1,0,1]
	v_pk_fma_f32 v[44:45], v[44:45], 0.5, v[60:61] op_sel_hi:[1,0,1]
	v_pk_fma_f32 v[48:49], v[38:39], 0.5, v[52:53] op_sel_hi:[1,0,1]
	v_pk_fma_f32 v[38:39], v[36:37], 0.5, v[64:65] op_sel_hi:[1,0,1]
	v_pk_fma_f32 v[42:43], v[42:43], 0.5, v[50:51] op_sel_hi:[1,0,1]
	v_pk_fma_f32 v[40:41], v[40:41], 0.5, v[62:63] op_sel_hi:[1,0,1]
	v_pk_fma_f32 v[50:51], v[34:35], 0.5, v[54:55] op_sel_hi:[1,0,1]
	v_pk_fma_f32 v[32:33], v[32:33], 0.5, v[66:67] op_sel_hi:[1,0,1]
	v_cvt_pk_bf16_f32 v34, v44, v45
	v_cvt_pk_bf16_f32 v35, v46, v47
	v_cvt_pk_bf16_f32 v38, v38, v39
	v_cvt_pk_bf16_f32 v39, v48, v49
	v_cvt_pk_bf16_f32 v36, v40, v41
	v_cvt_pk_bf16_f32 v37, v42, v43
	v_cvt_pk_bf16_f32 v40, v32, v33
	v_cvt_pk_bf16_f32 v41, v50, v51
	v_and_b32_e32 v33, 0xffff0000, v34
	v_and_b32_e32 v43, 0xffff0000, v35
	v_and_b32_e32 v49, 0xffff0000, v38
	v_and_b32_e32 v51, 0xffff0000, v39
	v_lshlrev_b32_e32 v32, 16, v34
	v_lshlrev_b32_e32 v42, 16, v35
	v_and_b32_e32 v45, 0xffff0000, v36
	v_lshlrev_b32_e32 v48, 16, v38
	v_lshlrev_b32_e32 v50, 16, v39
	v_and_b32_e32 v53, 0xffff0000, v40
	v_mul_f32_e32 v33, v33, v33
	v_mul_f32_e32 v43, v43, v43
	v_mul_f32_e32 v49, v49, v49
	v_mul_f32_e32 v51, v51, v51
	v_lshlrev_b32_e32 v44, 16, v36
	v_and_b32_e32 v47, 0xffff0000, v37
	v_lshlrev_b32_e32 v52, 16, v40
	v_and_b32_e32 v55, 0xffff0000, v41
	v_mul_f32_e32 v45, v45, v45
	v_mul_f32_e32 v53, v53, v53
	v_fmac_f32_e32 v33, v32, v32
	v_fmac_f32_e32 v43, v42, v42
	v_fmac_f32_e32 v49, v48, v48
	v_fmac_f32_e32 v51, v50, v50
	v_lshlrev_b32_e32 v46, 16, v37
	v_lshlrev_b32_e32 v54, 16, v41
	v_mul_f32_e32 v47, v47, v47
	v_mul_f32_e32 v55, v55, v55
	v_fmac_f32_e32 v45, v44, v44
	v_fmac_f32_e32 v53, v52, v52
	v_add_f32_e32 v32, v33, v43
	v_add_f32_e32 v33, v49, v51
	v_fmac_f32_e32 v47, v46, v46
	v_fmac_f32_e32 v55, v54, v54
	v_add_f32_e32 v32, v45, v32
	v_add_f32_e32 v33, v53, v33
	v_add_f32_e32 v32, v47, v32
	v_add_f32_e32 v33, v55, v33
	v_add_f32_e32 v32, v32, v33
	v_mov_b32_e32 v33, v32
	v_mov_b32_e32 v159, v32
	s_nop 1
	v_permlane16_swap_b32_e32 v33, v159
	global_store_dwordx4 v[56:57], v[34:37], off
	global_store_dwordx4 v[58:59], v[38:41], off offset:256
	s_waitcnt lgkmcnt(0)
	v_add_f32_e32 v32, v159, v33
	v_mov_b32_e32 v33, v32
	v_mov_b32_e32 v112, v32
	s_nop 1
	v_permlane32_swap_b32_e32 v33, v112
	s_and_saveexec_b64 s[30:31], s[6:7]
	s_cbranch_execz .LBB0_344
	s_waitcnt lgkmcnt(0)
	v_add_f32_e32 v32, v112, v33
	ds_write_b32 v156, v32
; #define PG8_LAS __attribute__((address_space(3)))
;     __device__ __forceinline__ void operator()(const f32x4 (&acc)[2][2][4][2], const Unit& u, int wr, int wc, int fr, int fq, PG8_LAS unsigned char* lds, int wid) const {
;     ...
;                 float s = 0.f;
; #pragma unroll
;                 for (int bj = 0; bj < 2; ++bj) {
;                     const size_t off = (size_t)(row0 + ai * HALF + m * 16) * 1024 + col0 + bj * HALF;
;                     f32x4 b0, b1;
;                     if (FIRST) { b0 = *(const f32x4*)(base32 + off); b1 = *(const f32x4*)(base32 + off + 4); }
;                     else { const u32x4 r = *(const u32x4*)(xn + off);
;                         b0 = (f32x4){__uint_as_float(r.x << 16), __uint_as_float(r.x & 0xffff0000u), __uint_as_float(r.y << 16), __uint_as_float(r.y & 0xffff0000u)};
;                         b1 = (f32x4){__uint_as_float(r.z << 16), __uint_as_float(r.z & 0xffff0000u), __uint_as_float(r.w << 16), __uint_as_float(r.w & 0xffff0000u)}; }
;                     const f32x4 v0 = b0 + alpha * acc[ai][bj][m][0], v1 = b1 + alpha * acc[ai][bj][m][1];
;                     if (LAST) { *(f32x4*)(out32 + off) = v0; *(f32x4*)(out32 + off + 4) = v1; }
;                     else {
;                         u32x4 w; w.x = pk_bf16(v0[0], v0[1]); w.y = pk_bf16(v0[2], v0[3]); w.z = pk_bf16(v1[0], v1[1]); w.w = pk_bf16(v1[2], v1[3]);
;                         *(u32x4*)(xn + off) = w;
;                         const float r0 = __uint_as_float(w.x << 16), r1 = __uint_as_float(w.x & 0xffff0000u), r2 = __uint_as_float(w.y << 16), r3 = __uint_as_float(w.y & 0xffff0000u);
;                         const float r4 = __uint_as_float(w.z << 16), r5 = __uint_as_float(w.z & 0xffff0000u), r6 = __uint_as_float(w.w << 16), r7 = __uint_as_float(w.w & 0xffff0000u);
;                         s += (r0 * r0 + r1 * r1) + (r2 * r2 + r3 * r3) + (r4 * r4 + r5 * r5) + (r6 * r6 + r7 * r7);
;                     }
;                 }
;                 if (!LAST) { s += __shfl_xor(s, 16); s += __shfl_xor(s, 32);
;                     if (fq == 0) *(PG8_LAS float*)(lds + PRE_SLOT + 4096 + ((wr * 64 + fr + ai * HALF + m * 16) * 4 + wc) * 4) = s; }
.LBB0_344:
	s_or_b64 exec, exec, s[30:31]
	s_waitcnt lgkmcnt(0)
	v_lshlrev_b64 v[32:33], 11, v[142:143]
	v_lshl_add_u64 v[32:33], s[48:49], 0, v[32:33]
	v_lshl_add_u64 v[32:33], v[140:141], 1, v[32:33]
	v_add_co_u32_e32 v42, vcc, 0x50000, v32
	v_lshl_add_u64 v[44:45], v[32:33], 0, s[22:23]
	s_nop 0
	v_addc_co_u32_e32 v43, vcc, 0, v33, vcc
	global_load_dwordx4 v[34:37], v[42:43], off
	global_load_dwordx4 v[38:41], v[44:45], off offset:256
	s_waitcnt vmcnt(1)
	v_lshlrev_b32_e32 v46, 16, v34
	v_and_b32_e32 v47, 0xffff0000, v34
	v_lshlrev_b32_e32 v34, 16, v35
	v_and_b32_e32 v35, 0xffff0000, v35
	s_waitcnt vmcnt(0)
	v_lshlrev_b32_e32 v50, 16, v38
	v_and_b32_e32 v51, 0xffff0000, v38
	v_lshlrev_b32_e32 v38, 16, v39
	v_and_b32_e32 v39, 0xffff0000, v39
	v_lshlrev_b32_e32 v48, 16, v36
	v_and_b32_e32 v49, 0xffff0000, v36
	v_lshlrev_b32_e32 v36, 16, v37
	v_and_b32_e32 v37, 0xffff0000, v37
	v_lshlrev_b32_e32 v52, 16, v40
	v_and_b32_e32 v53, 0xffff0000, v40
	v_lshlrev_b32_e32 v40, 16, v41
	v_and_b32_e32 v41, 0xffff0000, v41
	v_pk_fma_f32 v[30:31], v[30:31], 0.5, v[34:35] op_sel_hi:[1,0,1]
	v_pk_fma_f32 v[28:29], v[28:29], 0.5, v[46:47] op_sel_hi:[1,0,1]
	v_pk_fma_f32 v[34:35], v[22:23], 0.5, v[38:39] op_sel_hi:[1,0,1]
	v_pk_fma_f32 v[22:23], v[20:21], 0.5, v[50:51] op_sel_hi:[1,0,1]
	v_pk_fma_f32 v[26:27], v[26:27], 0.5, v[36:37] op_sel_hi:[1,0,1]
	v_pk_fma_f32 v[24:25], v[24:25], 0.5, v[48:49] op_sel_hi:[1,0,1]
	v_pk_fma_f32 v[36:37], v[18:19], 0.5, v[40:41] op_sel_hi:[1,0,1]
	v_pk_fma_f32 v[16:17], v[16:17], 0.5, v[52:53] op_sel_hi:[1,0,1]
	v_cvt_pk_bf16_f32 v18, v28, v29
	v_cvt_pk_bf16_f32 v19, v30, v31
	v_cvt_pk_bf16_f32 v22, v22, v23
	v_cvt_pk_bf16_f32 v23, v34, v35
	v_cvt_pk_bf16_f32 v20, v24, v25
	v_cvt_pk_bf16_f32 v21, v26, v27
	v_cvt_pk_bf16_f32 v24, v16, v17
	v_cvt_pk_bf16_f32 v25, v36, v37
	v_and_b32_e32 v17, 0xffff0000, v18
	v_and_b32_e32 v27, 0xffff0000, v19
	v_and_b32_e32 v35, 0xffff0000, v22
	v_and_b32_e32 v37, 0xffff0000, v23
	v_lshlrev_b32_e32 v16, 16, v18
	v_lshlrev_b32_e32 v26, 16, v19
	v_and_b32_e32 v29, 0xffff0000, v20
	v_lshlrev_b32_e32 v34, 16, v22
	v_lshlrev_b32_e32 v36, 16, v23
	v_and_b32_e32 v39, 0xffff0000, v24
	v_mul_f32_e32 v17, v17, v17
	v_mul_f32_e32 v27, v27, v27
	v_mul_f32_e32 v35, v35, v35
	v_mul_f32_e32 v37, v37, v37
	v_lshlrev_b32_e32 v28, 16, v20
	v_and_b32_e32 v31, 0xffff0000, v21
	v_lshlrev_b32_e32 v38, 16, v24
	v_and_b32_e32 v41, 0xffff0000, v25
	v_mul_f32_e32 v29, v29, v29
	v_mul_f32_e32 v39, v39, v39
	v_fmac_f32_e32 v17, v16, v16
	v_fmac_f32_e32 v27, v26, v26
	v_fmac_f32_e32 v35, v34, v34
	v_fmac_f32_e32 v37, v36, v36
	v_lshlrev_b32_e32 v30, 16, v21
	v_lshlrev_b32_e32 v40, 16, v25
	v_mul_f32_e32 v31, v31, v31
	v_mul_f32_e32 v41, v41, v41
	v_fmac_f32_e32 v29, v28, v28
	v_fmac_f32_e32 v39, v38, v38
	v_add_f32_e32 v16, v17, v27
	v_add_f32_e32 v17, v35, v37
	v_fmac_f32_e32 v31, v30, v30
	v_fmac_f32_e32 v41, v40, v40
	v_add_f32_e32 v16, v29, v16
	v_add_f32_e32 v17, v39, v17
	v_add_f32_e32 v16, v31, v16
	v_add_f32_e32 v17, v41, v17
	v_add_f32_e32 v16, v16, v17
	v_mov_b32_e32 v17, v16
	v_mov_b32_e32 v159, v16
	s_nop 1
	v_permlane16_swap_b32_e32 v17, v159
	global_store_dwordx4 v[42:43], v[18:21], off
	global_store_dwordx4 v[44:45], v[22:25], off offset:256
	s_waitcnt lgkmcnt(0)
	v_add_f32_e32 v16, v159, v17
	v_mov_b32_e32 v17, v16
	v_mov_b32_e32 v112, v16
	s_nop 1
	v_permlane32_swap_b32_e32 v17, v112
	s_and_saveexec_b64 s[30:31], s[6:7]
	s_cbranch_execz .LBB0_346
	s_waitcnt lgkmcnt(0)
	v_add_f32_e32 v16, v112, v17
	ds_write_b32 v157, v16
.LBB0_346:
	s_or_b64 exec, exec, s[30:31]
	v_add_co_u32_e32 v24, vcc, 0x58000, v32
	v_lshl_add_u64 v[26:27], v[32:33], 0, s[24:25]
	s_nop 0
	v_addc_co_u32_e32 v25, vcc, 0, v33, vcc
	s_waitcnt lgkmcnt(0)
	global_load_dwordx4 v[16:19], v[24:25], off
	global_load_dwordx4 v[20:23], v[26:27], off offset:256
	s_waitcnt vmcnt(1)
	v_lshlrev_b32_e32 v28, 16, v16
	v_and_b32_e32 v29, 0xffff0000, v16
	v_lshlrev_b32_e32 v16, 16, v17
	v_and_b32_e32 v17, 0xffff0000, v17
	s_waitcnt vmcnt(0)
	v_lshlrev_b32_e32 v32, 16, v20
	v_and_b32_e32 v33, 0xffff0000, v20
	v_lshlrev_b32_e32 v20, 16, v21
	v_and_b32_e32 v21, 0xffff0000, v21
	v_lshlrev_b32_e32 v30, 16, v18
	v_and_b32_e32 v31, 0xffff0000, v18
	v_lshlrev_b32_e32 v18, 16, v19
	v_and_b32_e32 v19, 0xffff0000, v19
	v_lshlrev_b32_e32 v34, 16, v22
	v_and_b32_e32 v35, 0xffff0000, v22
	v_lshlrev_b32_e32 v22, 16, v23
	v_and_b32_e32 v23, 0xffff0000, v23
	v_pk_fma_f32 v[14:15], v[14:15], 0.5, v[16:17] op_sel_hi:[1,0,1]
	v_pk_fma_f32 v[12:13], v[12:13], 0.5, v[28:29] op_sel_hi:[1,0,1]
	v_pk_fma_f32 v[16:17], v[6:7], 0.5, v[20:21] op_sel_hi:[1,0,1]
	v_pk_fma_f32 v[6:7], v[4:5], 0.5, v[32:33] op_sel_hi:[1,0,1]
	v_pk_fma_f32 v[10:11], v[10:11], 0.5, v[18:19] op_sel_hi:[1,0,1]
	v_pk_fma_f32 v[8:9], v[8:9], 0.5, v[30:31] op_sel_hi:[1,0,1]
	v_pk_fma_f32 v[18:19], v[2:3], 0.5, v[22:23] op_sel_hi:[1,0,1]
	v_pk_fma_f32 v[0:1], v[0:1], 0.5, v[34:35] op_sel_hi:[1,0,1]
	v_cvt_pk_bf16_f32 v2, v12, v13
	v_cvt_pk_bf16_f32 v3, v14, v15
	v_cvt_pk_bf16_f32 v6, v6, v7
	v_cvt_pk_bf16_f32 v7, v16, v17
	v_cvt_pk_bf16_f32 v4, v8, v9
	v_cvt_pk_bf16_f32 v5, v10, v11
	v_cvt_pk_bf16_f32 v8, v0, v1
	v_cvt_pk_bf16_f32 v9, v18, v19
	v_and_b32_e32 v1, 0xffff0000, v2
	v_and_b32_e32 v11, 0xffff0000, v3
	v_and_b32_e32 v17, 0xffff0000, v6
	v_and_b32_e32 v19, 0xffff0000, v7
	v_lshlrev_b32_e32 v0, 16, v2
	v_lshlrev_b32_e32 v10, 16, v3
	v_and_b32_e32 v13, 0xffff0000, v4
	v_lshlrev_b32_e32 v16, 16, v6
	v_lshlrev_b32_e32 v18, 16, v7
	v_and_b32_e32 v21, 0xffff0000, v8
	v_mul_f32_e32 v1, v1, v1
	v_mul_f32_e32 v11, v11, v11
	v_mul_f32_e32 v17, v17, v17
	v_mul_f32_e32 v19, v19, v19
	v_lshlrev_b32_e32 v12, 16, v4
	v_and_b32_e32 v15, 0xffff0000, v5
	v_lshlrev_b32_e32 v20, 16, v8
	v_and_b32_e32 v23, 0xffff0000, v9
	v_mul_f32_e32 v13, v13, v13
	v_mul_f32_e32 v21, v21, v21
	v_fmac_f32_e32 v1, v0, v0
	v_fmac_f32_e32 v11, v10, v10
	v_fmac_f32_e32 v17, v16, v16
	v_fmac_f32_e32 v19, v18, v18
	v_lshlrev_b32_e32 v14, 16, v5
	v_lshlrev_b32_e32 v22, 16, v9
	v_mul_f32_e32 v15, v15, v15
	v_mul_f32_e32 v23, v23, v23
	v_fmac_f32_e32 v13, v12, v12
	v_fmac_f32_e32 v21, v20, v20
	v_add_f32_e32 v0, v1, v11
	v_add_f32_e32 v1, v17, v19
	v_fmac_f32_e32 v15, v14, v14
	v_fmac_f32_e32 v23, v22, v22
	v_add_f32_e32 v0, v13, v0
	v_add_f32_e32 v1, v21, v1
	v_add_f32_e32 v0, v15, v0
	v_add_f32_e32 v1, v23, v1
	v_add_f32_e32 v0, v0, v1
	v_mov_b32_e32 v1, v0
	v_mov_b32_e32 v159, v0
	s_nop 1
	v_permlane16_swap_b32_e32 v1, v159
	global_store_dwordx4 v[24:25], v[2:5], off
	global_store_dwordx4 v[26:27], v[6:9], off offset:256
	s_waitcnt lgkmcnt(0)
	v_add_f32_e32 v0, v159, v1
	v_mov_b32_e32 v1, v0
	v_mov_b32_e32 v112, v0
	s_nop 1
	v_permlane32_swap_b32_e32 v1, v112
	s_and_saveexec_b64 s[30:31], s[6:7]
	s_cbranch_execz .LBB0_348
	s_waitcnt lgkmcnt(0)
	v_add_f32_e32 v0, v112, v1
	ds_write_b32 v158, v0

;     __device__ __forceinline__ void operator()(const f32x4 (&acc)[2][2][4][2], const Unit& u, int wr, int wc, int fr, int fq, PG8_LAS unsigned char* lds, int wid) const {
;         const int row0 = u.pm * BM + wr * 64 + fr, col0 = u.pn * BM + wc * 32 + 8 * fq;
;         constexpr float alpha = HALF_ALPHA ? 0.5f : 1.0f;
; #pragma unroll
;         for (int ai = 0; ai < 2; ++ai)
; #pragma unroll
;             for (int m = 0; m < 4; ++m) {
;                 float s = 0.f;
; #pragma unroll
;                 for (int bj = 0; bj < 2; ++bj) {
;                     const size_t off = (size_t)(row0 + ai * HALF + m * 16) * 1024 + col0 + bj * HALF;
;                     f32x4 b0, b1;
;                     if (FIRST) { b0 = *(const f32x4*)(base32 + off); b1 = *(const f32x4*)(base32 + off + 4); }
;                     else { const u32x4 r = *(const u32x4*)(xn + off);
;                         b0 = (f32x4){__uint_as_float(r.x << 16), __uint_as_float(r.x & 0xffff0000u), __uint_as_float(r.y << 16), __uint_as_float(r.y & 0xffff0000u)};
;                         b1 = (f32x4){__uint_as_float(r.z << 16), __uint_as_float(r.z & 0xffff0000u), __uint_as_float(r.w << 16), __uint_as_float(r.w & 0xffff0000u)}; }
;                     const f32x4 v0 = b0 + alpha * acc[ai][bj][m][0], v1 = b1 + alpha * acc[ai][bj][m][1];
;                     if (LAST) { *(f32x4*)(out32 + off) = v0; *(f32x4*)(out32 + off + 4) = v1; }
;                     else {
;                         u32x4 w; w.x = pk_bf16(v0[0], v0[1]); w.y = pk_bf16(v0[2], v0[3]); w.z = pk_bf16(v1[0], v1[1]); w.w = pk_bf16(v1[2], v1[3]);
;                         *(u32x4*)(xn + off) = w;
;                         const float r0 = __uint_as_float(w.x << 16), r1 = __uint_as_float(w.x & 0xffff0000u), r2 = __uint_as_float(w.y << 16), r3 = __uint_as_float(w.y & 0xffff0000u);
;                         const float r4 = __uint_as_float(w.z << 16), r5 = __uint_as_float(w.z & 0xffff0000u), r6 = __uint_as_float(w.w << 16), r7 = __uint_as_float(w.w & 0xffff0000u);
;                         s += (r0 * r0 + r1 * r1) + (r2 * r2 + r3 * r3) + (r4 * r4 + r5 * r5) + (r6 * r6 + r7 * r7);
;                     }
;                 }
;                 if (!LAST) { s += __shfl_xor(s, 16); s += __shfl_xor(s, 32);
;                     if (fq == 0) *(PG8_LAS float*)(lds + PRE_SLOT + 4096 + ((wr * 64 + fr + ai * HALF + m * 16) * 4 + wc) * 4) = s; }
.LBB0_825:
	s_lshl_b32 s38, s38, 8
	v_add_u32_e32 v142, s38, v144
	v_ashrrev_i32_e32 v143, 31, v142
	v_lshl_or_b32 v140, s36, 8, v146
	v_lshlrev_b64 v[160:161], 11, v[142:143]
	v_ashrrev_i32_e32 v141, 31, v140
	v_lshl_add_u64 v[160:161], s[48:49], 0, v[160:161]
	v_lshl_add_u64 v[168:169], v[140:141], 1, v[160:161]
	global_load_dwordx4 v[160:163], v[168:169], off
	global_load_dwordx4 v[164:167], v[168:169], off offset:256
	v_and_b32_e32 v170, 64, v150
	v_add_u32_e32 v178, 64, v170
	v_xor_b32_e32 v159, 16, v150
	v_cmp_lt_i32_e32 vcc, v159, v178
	s_waitcnt vmcnt(0)
	v_lshlrev_b32_e32 v170, 16, v160
	v_and_b32_e32 v171, 0xffff0000, v160
	v_lshlrev_b32_e32 v160, 16, v161
	v_and_b32_e32 v161, 0xffff0000, v161
	v_lshlrev_b32_e32 v172, 16, v162
	v_and_b32_e32 v173, 0xffff0000, v162
	v_lshlrev_b32_e32 v162, 16, v163
	v_and_b32_e32 v163, 0xffff0000, v163
	v_lshlrev_b32_e32 v174, 16, v164
	v_and_b32_e32 v175, 0xffff0000, v164
	v_lshlrev_b32_e32 v164, 16, v165
	v_and_b32_e32 v165, 0xffff0000, v165
	v_lshlrev_b32_e32 v176, 16, v166
	v_and_b32_e32 v177, 0xffff0000, v166
	v_lshlrev_b32_e32 v166, 16, v167
	v_and_b32_e32 v167, 0xffff0000, v167
	v_pk_add_f32 v[126:127], v[126:127], v[160:161]
	v_pk_add_f32 v[124:125], v[124:125], v[170:171]
	v_pk_add_f32 v[122:123], v[122:123], v[162:163]
	v_pk_add_f32 v[120:121], v[120:121], v[172:173]
	v_pk_add_f32 v[160:161], v[118:119], v[164:165]
	v_pk_add_f32 v[162:163], v[116:117], v[174:175]
	v_pk_add_f32 v[114:115], v[114:115], v[166:167]
	v_pk_add_f32 v[112:113], v[112:113], v[176:177]
	v_cvt_pk_bf16_f32 v116, v124, v125
	v_cvt_pk_bf16_f32 v117, v126, v127
	v_cvt_pk_bf16_f32 v118, v120, v121
	v_cvt_pk_bf16_f32 v120, v162, v163
	v_cvt_pk_bf16_f32 v121, v160, v161
	v_cvt_pk_bf16_f32 v119, v122, v123
	v_cvt_pk_bf16_f32 v122, v112, v113
	v_cvt_pk_bf16_f32 v123, v114, v115
	v_and_b32_e32 v113, 0xffff0000, v116
	v_and_b32_e32 v115, 0xffff0000, v117
	v_and_b32_e32 v161, 0xffff0000, v120
	v_and_b32_e32 v163, 0xffff0000, v121
	v_lshlrev_b32_e32 v112, 16, v116
	v_lshlrev_b32_e32 v114, 16, v117
	v_and_b32_e32 v125, 0xffff0000, v118
	v_lshlrev_b32_e32 v160, 16, v120
	v_lshlrev_b32_e32 v162, 16, v121
	v_and_b32_e32 v165, 0xffff0000, v122
	v_mul_f32_e32 v113, v113, v113
	v_mul_f32_e32 v115, v115, v115
	v_mul_f32_e32 v161, v161, v161
	v_mul_f32_e32 v163, v163, v163
	v_lshlrev_b32_e32 v124, 16, v118
	v_and_b32_e32 v127, 0xffff0000, v119
	v_lshlrev_b32_e32 v164, 16, v122
	v_and_b32_e32 v167, 0xffff0000, v123
	v_mul_f32_e32 v125, v125, v125
	v_mul_f32_e32 v165, v165, v165
	v_fmac_f32_e32 v113, v112, v112
	v_fmac_f32_e32 v115, v114, v114
	v_fmac_f32_e32 v161, v160, v160
	v_fmac_f32_e32 v163, v162, v162
	v_lshlrev_b32_e32 v126, 16, v119
	v_lshlrev_b32_e32 v166, 16, v123
	v_mul_f32_e32 v127, v127, v127
	v_mul_f32_e32 v167, v167, v167
	v_fmac_f32_e32 v125, v124, v124
	v_fmac_f32_e32 v165, v164, v164
	v_add_f32_e32 v112, v113, v115
	v_add_f32_e32 v113, v161, v163
	v_fmac_f32_e32 v127, v126, v126
	v_fmac_f32_e32 v167, v166, v166
	v_add_f32_e32 v112, v125, v112
	v_add_f32_e32 v113, v165, v113
	v_cndmask_b32_e32 v159, v150, v159, vcc
	v_add_f32_e32 v112, v127, v112
	v_add_f32_e32 v113, v167, v113
	v_lshlrev_b32_e32 v159, 2, v159
	v_add_f32_e32 v113, v112, v113
	v_mov_b32_e32 v114, v113
	v_mov_b32_e32 v159, v113
	s_nop 1
	v_permlane16_swap_b32_e32 v114, v159
	v_xor_b32_e32 v112, 32, v150
	v_cmp_lt_i32_e32 vcc, v112, v178
	global_store_dwordx4 v[168:169], v[116:119], off
	global_store_dwordx4 v[168:169], v[120:123], off offset:256
	v_cndmask_b32_e32 v112, v150, v112, vcc
	v_lshlrev_b32_e32 v112, 2, v112
	s_waitcnt lgkmcnt(0)
	v_add_f32_e32 v113, v159, v114
	v_mov_b32_e32 v114, v113
	v_mov_b32_e32 v112, v113
	s_nop 1
	v_permlane32_swap_b32_e32 v114, v112
	s_and_saveexec_b64 s[36:37], s[6:7]
	s_cbranch_execz .LBB0_827
	s_waitcnt lgkmcnt(0)
	v_add_f32_e32 v113, v112, v114
	ds_write_b32 v151, v113
.LBB0_827:
	s_or_b64 exec, exec, s[36:37]
	s_waitcnt lgkmcnt(0)
	v_or_b32_e32 v114, 16, v142
	v_ashrrev_i32_e32 v115, 31, v114
	v_lshlrev_b64 v[114:115], 11, v[114:115]
	v_lshl_add_u64 v[114:115], s[48:49], 0, v[114:115]
	v_lshl_add_u64 v[122:123], v[140:141], 1, v[114:115]
	global_load_dwordx4 v[114:117], v[122:123], off
	global_load_dwordx4 v[118:121], v[122:123], off offset:256
	s_waitcnt vmcnt(1)
	v_lshlrev_b32_e32 v124, 16, v114
	v_and_b32_e32 v125, 0xffff0000, v114
	v_lshlrev_b32_e32 v114, 16, v115
	v_and_b32_e32 v115, 0xffff0000, v115
	s_waitcnt vmcnt(0)
; #define PG8_LAS __attribute__((address_space(3)))
;     __device__ __forceinline__ void operator()(const f32x4 (&acc)[2][2][4][2], const Unit& u, int wr, int wc, int fr, int fq, PG8_LAS unsigned char* lds, int wid) const {
;     ...
;                 float s = 0.f;
; #pragma unroll
;                 for (int bj = 0; bj < 2; ++bj) {
;                     const size_t off = (size_t)(row0 + ai * HALF + m * 16) * 1024 + col0 + bj * HALF;
;                     f32x4 b0, b1;
;                     if (FIRST) { b0 = *(const f32x4*)(base32 + off); b1 = *(const f32x4*)(base32 + off + 4); }
;                     else { const u32x4 r = *(const u32x4*)(xn + off);
;                         b0 = (f32x4){__uint_as_float(r.x << 16), __uint_as_float(r.x & 0xffff0000u), __uint_as_float(r.y << 16), __uint_as_float(r.y & 0xffff0000u)};
;                         b1 = (f32x4){__uint_as_float(r.z << 16), __uint_as_float(r.z & 0xffff0000u), __uint_as_float(r.w << 16), __uint_as_float(r.w & 0xffff0000u)}; }
;                     const f32x4 v0 = b0 + alpha * acc[ai][bj][m][0], v1 = b1 + alpha * acc[ai][bj][m][1];
;                     if (LAST) { *(f32x4*)(out32 + off) = v0; *(f32x4*)(out32 + off + 4) = v1; }
;                     else {
;                         u32x4 w; w.x = pk_bf16(v0[0], v0[1]); w.y = pk_bf16(v0[2], v0[3]); w.z = pk_bf16(v1[0], v1[1]); w.w = pk_bf16(v1[2], v1[3]);
;                         *(u32x4*)(xn + off) = w;
;                         const float r0 = __uint_as_float(w.x << 16), r1 = __uint_as_float(w.x & 0xffff0000u), r2 = __uint_as_float(w.y << 16), r3 = __uint_as_float(w.y & 0xffff0000u);
;                         const float r4 = __uint_as_float(w.z << 16), r5 = __uint_as_float(w.z & 0xffff0000u), r6 = __uint_as_float(w.w << 16), r7 = __uint_as_float(w.w & 0xffff0000u);
;                         s += (r0 * r0 + r1 * r1) + (r2 * r2 + r3 * r3) + (r4 * r4 + r5 * r5) + (r6 * r6 + r7 * r7);
;                     }
;                 }
;                 if (!LAST) { s += __shfl_xor(s, 16); s += __shfl_xor(s, 32);
;                     if (fq == 0) *(PG8_LAS float*)(lds + PRE_SLOT + 4096 + ((wr * 64 + fr + ai * HALF + m * 16) * 4 + wc) * 4) = s; }
	v_lshlrev_b32_e32 v160, 16, v118
	v_and_b32_e32 v161, 0xffff0000, v118
	v_lshlrev_b32_e32 v118, 16, v119
	v_and_b32_e32 v119, 0xffff0000, v119
	v_lshlrev_b32_e32 v126, 16, v116
	v_and_b32_e32 v127, 0xffff0000, v116
	v_lshlrev_b32_e32 v116, 16, v117
	v_and_b32_e32 v117, 0xffff0000, v117
	v_lshlrev_b32_e32 v162, 16, v120
	v_and_b32_e32 v163, 0xffff0000, v120
	v_lshlrev_b32_e32 v120, 16, v121
	v_and_b32_e32 v121, 0xffff0000, v121
	v_pk_add_f32 v[110:111], v[110:111], v[114:115]
	v_pk_add_f32 v[108:109], v[108:109], v[124:125]
	v_pk_add_f32 v[114:115], v[102:103], v[118:119]
	v_pk_add_f32 v[102:103], v[100:101], v[160:161]
	v_pk_add_f32 v[106:107], v[106:107], v[116:117]
	v_pk_add_f32 v[104:105], v[104:105], v[126:127]
	v_pk_add_f32 v[116:117], v[98:99], v[120:121]
	v_pk_add_f32 v[96:97], v[96:97], v[162:163]
	v_cvt_pk_bf16_f32 v98, v108, v109
	v_cvt_pk_bf16_f32 v99, v110, v111
	v_cvt_pk_bf16_f32 v102, v102, v103
	v_cvt_pk_bf16_f32 v103, v114, v115
	v_cvt_pk_bf16_f32 v100, v104, v105
	v_cvt_pk_bf16_f32 v101, v106, v107
	v_cvt_pk_bf16_f32 v104, v96, v97
	v_cvt_pk_bf16_f32 v105, v116, v117
	v_and_b32_e32 v97, 0xffff0000, v98
	v_and_b32_e32 v107, 0xffff0000, v99
	v_and_b32_e32 v114, 0xffff0000, v102
	v_and_b32_e32 v116, 0xffff0000, v103
	v_lshlrev_b32_e32 v96, 16, v98
	v_lshlrev_b32_e32 v106, 16, v99
	v_and_b32_e32 v109, 0xffff0000, v100
	v_lshlrev_b32_e32 v113, 16, v102
	v_lshlrev_b32_e32 v115, 16, v103
	v_and_b32_e32 v118, 0xffff0000, v104
	v_mul_f32_e32 v97, v97, v97
	v_mul_f32_e32 v107, v107, v107
	v_mul_f32_e32 v114, v114, v114
	v_mul_f32_e32 v116, v116, v116
	v_lshlrev_b32_e32 v108, 16, v100
	v_and_b32_e32 v111, 0xffff0000, v101
	v_lshlrev_b32_e32 v117, 16, v104
	v_and_b32_e32 v120, 0xffff0000, v105
	v_mul_f32_e32 v109, v109, v109
	v_mul_f32_e32 v118, v118, v118
	v_fmac_f32_e32 v97, v96, v96
	v_fmac_f32_e32 v107, v106, v106
	v_fmac_f32_e32 v114, v113, v113
	v_fmac_f32_e32 v116, v115, v115
	v_lshlrev_b32_e32 v110, 16, v101
	v_lshlrev_b32_e32 v119, 16, v105
	v_mul_f32_e32 v111, v111, v111
	v_mul_f32_e32 v120, v120, v120
	v_fmac_f32_e32 v109, v108, v108
	v_fmac_f32_e32 v118, v117, v117
	v_add_f32_e32 v96, v97, v107
	v_add_f32_e32 v97, v114, v116
	v_fmac_f32_e32 v111, v110, v110
	v_fmac_f32_e32 v120, v119, v119
	v_add_f32_e32 v96, v109, v96
	v_add_f32_e32 v97, v118, v97
	v_add_f32_e32 v96, v111, v96
	v_add_f32_e32 v97, v120, v97
	v_add_f32_e32 v96, v96, v97
	v_mov_b32_e32 v97, v96
	v_mov_b32_e32 v159, v96
	s_nop 1
	v_permlane16_swap_b32_e32 v97, v159
	global_store_dwordx4 v[122:123], v[98:101], off
	global_store_dwordx4 v[122:123], v[102:105], off offset:256
	s_waitcnt lgkmcnt(0)
	v_add_f32_e32 v96, v159, v97
	v_mov_b32_e32 v97, v96
	v_mov_b32_e32 v112, v96
	s_nop 1
	v_permlane32_swap_b32_e32 v97, v112
	s_and_saveexec_b64 s[36:37], s[6:7]
	s_cbranch_execz .LBB0_829
	s_waitcnt lgkmcnt(0)
	v_add_f32_e32 v96, v112, v97
	ds_write_b32 v152, v96
.LBB0_829:
	s_or_b64 exec, exec, s[36:37]
	v_or_b32_e32 v96, 32, v142
	s_waitcnt lgkmcnt(0)
	v_ashrrev_i32_e32 v97, 31, v96
	v_lshlrev_b64 v[96:97], 11, v[96:97]
	v_lshl_add_u64 v[96:97], s[48:49], 0, v[96:97]
	v_lshl_add_u64 v[104:105], v[140:141], 1, v[96:97]
	global_load_dwordx4 v[96:99], v[104:105], off
	global_load_dwordx4 v[100:103], v[104:105], off offset:256
	s_waitcnt vmcnt(1)
	v_lshlrev_b32_e32 v106, 16, v96
	v_and_b32_e32 v107, 0xffff0000, v96
	v_lshlrev_b32_e32 v96, 16, v97
	v_and_b32_e32 v97, 0xffff0000, v97
	s_waitcnt vmcnt(0)
	v_lshlrev_b32_e32 v110, 16, v100
	v_and_b32_e32 v111, 0xffff0000, v100
	v_lshlrev_b32_e32 v100, 16, v101
	v_and_b32_e32 v101, 0xffff0000, v101
	v_lshlrev_b32_e32 v108, 16, v98
	v_and_b32_e32 v109, 0xffff0000, v98
	v_lshlrev_b32_e32 v98, 16, v99
	v_and_b32_e32 v99, 0xffff0000, v99
	v_lshlrev_b32_e32 v114, 16, v102
	v_and_b32_e32 v115, 0xffff0000, v102
	v_lshlrev_b32_e32 v102, 16, v103
	v_and_b32_e32 v103, 0xffff0000, v103
	v_pk_add_f32 v[94:95], v[94:95], v[96:97]
	v_pk_add_f32 v[92:93], v[92:93], v[106:107]
	v_pk_add_f32 v[96:97], v[86:87], v[100:101]
	v_pk_add_f32 v[86:87], v[84:85], v[110:111]
	v_pk_add_f32 v[90:91], v[90:91], v[98:99]
	v_pk_add_f32 v[88:89], v[88:89], v[108:109]
	v_pk_add_f32 v[98:99], v[82:83], v[102:103]
	v_pk_add_f32 v[80:81], v[80:81], v[114:115]
	v_cvt_pk_bf16_f32 v82, v92, v93
	v_cvt_pk_bf16_f32 v83, v94, v95
	v_cvt_pk_bf16_f32 v86, v86, v87
	v_cvt_pk_bf16_f32 v87, v96, v97
	v_cvt_pk_bf16_f32 v84, v88, v89
	v_cvt_pk_bf16_f32 v85, v90, v91
	v_cvt_pk_bf16_f32 v88, v80, v81
	v_cvt_pk_bf16_f32 v89, v98, v99
	v_and_b32_e32 v81, 0xffff0000, v82
	v_and_b32_e32 v91, 0xffff0000, v83
	v_and_b32_e32 v97, 0xffff0000, v86
	v_and_b32_e32 v99, 0xffff0000, v87
	v_lshlrev_b32_e32 v80, 16, v82
	v_lshlrev_b32_e32 v90, 16, v83
	v_and_b32_e32 v93, 0xffff0000, v84
	v_lshlrev_b32_e32 v96, 16, v86
	v_lshlrev_b32_e32 v98, 16, v87
	v_and_b32_e32 v101, 0xffff0000, v88
	v_mul_f32_e32 v81, v81, v81
	v_mul_f32_e32 v91, v91, v91
	v_mul_f32_e32 v97, v97, v97
	v_mul_f32_e32 v99, v99, v99
	v_lshlrev_b32_e32 v92, 16, v84
	v_and_b32_e32 v95, 0xffff0000, v85
	v_lshlrev_b32_e32 v100, 16, v88
	v_and_b32_e32 v103, 0xffff0000, v89
	v_mul_f32_e32 v93, v93, v93
	v_mul_f32_e32 v101, v101, v101
	v_fmac_f32_e32 v81, v80, v80
	v_fmac_f32_e32 v91, v90, v90
	v_fmac_f32_e32 v97, v96, v96
	v_fmac_f32_e32 v99, v98, v98
	v_lshlrev_b32_e32 v94, 16, v85
	v_lshlrev_b32_e32 v102, 16, v89
	v_mul_f32_e32 v95, v95, v95
	v_mul_f32_e32 v103, v103, v103
	v_fmac_f32_e32 v93, v92, v92
	v_fmac_f32_e32 v101, v100, v100
	v_add_f32_e32 v80, v81, v91
	v_add_f32_e32 v81, v97, v99
	v_fmac_f32_e32 v95, v94, v94
	v_fmac_f32_e32 v103, v102, v102
	v_add_f32_e32 v80, v93, v80
	v_add_f32_e32 v81, v101, v81
	v_add_f32_e32 v80, v95, v80
	v_add_f32_e32 v81, v103, v81
	v_add_f32_e32 v80, v80, v81
	v_mov_b32_e32 v81, v80
	v_mov_b32_e32 v159, v80
	s_nop 1
	v_permlane16_swap_b32_e32 v81, v159
	global_store_dwordx4 v[104:105], v[82:85], off
	global_store_dwordx4 v[104:105], v[86:89], off offset:256
	s_waitcnt lgkmcnt(0)
	v_add_f32_e32 v80, v159, v81
	v_mov_b32_e32 v81, v80
	v_mov_b32_e32 v112, v80
	s_nop 1
	v_permlane32_swap_b32_e32 v81, v112
	s_and_saveexec_b64 s[36:37], s[6:7]
	s_cbranch_execz .LBB0_831
	s_waitcnt lgkmcnt(0)
	v_add_f32_e32 v80, v112, v81
	ds_write_b32 v153, v80
; #define PG8_LAS __attribute__((address_space(3)))
;     __device__ __forceinline__ void operator()(const f32x4 (&acc)[2][2][4][2], const Unit& u, int wr, int wc, int fr, int fq, PG8_LAS unsigned char* lds, int wid) const {
;     ...
;                 float s = 0.f;
; #pragma unroll
;                 for (int bj = 0; bj < 2; ++bj) {
;                     const size_t off = (size_t)(row0 + ai * HALF + m * 16) * 1024 + col0 + bj * HALF;
;                     f32x4 b0, b1;
;                     if (FIRST) { b0 = *(const f32x4*)(base32 + off); b1 = *(const f32x4*)(base32 + off + 4); }
;                     else { const u32x4 r = *(const u32x4*)(xn + off);
;                         b0 = (f32x4){__uint_as_float(r.x << 16), __uint_as_float(r.x & 0xffff0000u), __uint_as_float(r.y << 16), __uint_as_float(r.y & 0xffff0000u)};
;                         b1 = (f32x4){__uint_as_float(r.z << 16), __uint_as_float(r.z & 0xffff0000u), __uint_as_float(r.w << 16), __uint_as_float(r.w & 0xffff0000u)}; }
;                     const f32x4 v0 = b0 + alpha * acc[ai][bj][m][0], v1 = b1 + alpha * acc[ai][bj][m][1];
;                     if (LAST) { *(f32x4*)(out32 + off) = v0; *(f32x4*)(out32 + off + 4) = v1; }
;                     else {
;                         u32x4 w; w.x = pk_bf16(v0[0], v0[1]); w.y = pk_bf16(v0[2], v0[3]); w.z = pk_bf16(v1[0], v1[1]); w.w = pk_bf16(v1[2], v1[3]);
;                         *(u32x4*)(xn + off) = w;
;                         const float r0 = __uint_as_float(w.x << 16), r1 = __uint_as_float(w.x & 0xffff0000u), r2 = __uint_as_float(w.y << 16), r3 = __uint_as_float(w.y & 0xffff0000u);
;                         const float r4 = __uint_as_float(w.z << 16), r5 = __uint_as_float(w.z & 0xffff0000u), r6 = __uint_as_float(w.w << 16), r7 = __uint_as_float(w.w & 0xffff0000u);
;                         s += (r0 * r0 + r1 * r1) + (r2 * r2 + r3 * r3) + (r4 * r4 + r5 * r5) + (r6 * r6 + r7 * r7);
;                     }
;                 }
;                 if (!LAST) { s += __shfl_xor(s, 16); s += __shfl_xor(s, 32);
;                     if (fq == 0) *(PG8_LAS float*)(lds + PRE_SLOT + 4096 + ((wr * 64 + fr + ai * HALF + m * 16) * 4 + wc) * 4) = s; }
.LBB0_831:
	s_or_b64 exec, exec, s[36:37]
	v_or_b32_e32 v80, 48, v142
	s_waitcnt lgkmcnt(0)
	v_ashrrev_i32_e32 v81, 31, v80
	v_lshlrev_b64 v[80:81], 11, v[80:81]
	v_lshl_add_u64 v[80:81], s[48:49], 0, v[80:81]
	v_lshl_add_u64 v[88:89], v[140:141], 1, v[80:81]
	global_load_dwordx4 v[80:83], v[88:89], off
	global_load_dwordx4 v[84:87], v[88:89], off offset:256
	s_waitcnt vmcnt(1)
	v_lshlrev_b32_e32 v90, 16, v80
	v_and_b32_e32 v91, 0xffff0000, v80
	v_lshlrev_b32_e32 v80, 16, v81
	v_and_b32_e32 v81, 0xffff0000, v81
	s_waitcnt vmcnt(0)
	v_lshlrev_b32_e32 v94, 16, v84
	v_and_b32_e32 v95, 0xffff0000, v84
	v_lshlrev_b32_e32 v84, 16, v85
	v_and_b32_e32 v85, 0xffff0000, v85
	v_lshlrev_b32_e32 v92, 16, v82
	v_and_b32_e32 v93, 0xffff0000, v82
	v_lshlrev_b32_e32 v82, 16, v83
	v_and_b32_e32 v83, 0xffff0000, v83
	v_lshlrev_b32_e32 v96, 16, v86
	v_and_b32_e32 v97, 0xffff0000, v86
	v_lshlrev_b32_e32 v86, 16, v87
	v_and_b32_e32 v87, 0xffff0000, v87
	v_pk_add_f32 v[78:79], v[78:79], v[80:81]
	v_pk_add_f32 v[76:77], v[76:77], v[90:91]
	v_pk_add_f32 v[80:81], v[70:71], v[84:85]
	v_pk_add_f32 v[70:71], v[68:69], v[94:95]
	v_pk_add_f32 v[74:75], v[74:75], v[82:83]
	v_pk_add_f32 v[72:73], v[72:73], v[92:93]
	v_pk_add_f32 v[82:83], v[66:67], v[86:87]
	v_pk_add_f32 v[64:65], v[64:65], v[96:97]
	v_cvt_pk_bf16_f32 v66, v76, v77
	v_cvt_pk_bf16_f32 v67, v78, v79
	v_cvt_pk_bf16_f32 v70, v70, v71
	v_cvt_pk_bf16_f32 v71, v80, v81
	v_cvt_pk_bf16_f32 v68, v72, v73
	v_cvt_pk_bf16_f32 v69, v74, v75
	v_cvt_pk_bf16_f32 v72, v64, v65
	v_cvt_pk_bf16_f32 v73, v82, v83
	v_and_b32_e32 v65, 0xffff0000, v66
	v_and_b32_e32 v75, 0xffff0000, v67
	v_and_b32_e32 v81, 0xffff0000, v70
	v_and_b32_e32 v83, 0xffff0000, v71
	v_lshlrev_b32_e32 v64, 16, v66
	v_lshlrev_b32_e32 v74, 16, v67
	v_and_b32_e32 v77, 0xffff0000, v68
	v_lshlrev_b32_e32 v80, 16, v70
	v_lshlrev_b32_e32 v82, 16, v71
	v_and_b32_e32 v85, 0xffff0000, v72
	v_mul_f32_e32 v65, v65, v65
	v_mul_f32_e32 v75, v75, v75
	v_mul_f32_e32 v81, v81, v81
	v_mul_f32_e32 v83, v83, v83
	v_lshlrev_b32_e32 v76, 16, v68
	v_and_b32_e32 v79, 0xffff0000, v69
	v_lshlrev_b32_e32 v84, 16, v72
	v_and_b32_e32 v87, 0xffff0000, v73
	v_mul_f32_e32 v77, v77, v77
	v_mul_f32_e32 v85, v85, v85
	v_fmac_f32_e32 v65, v64, v64
	v_fmac_f32_e32 v75, v74, v74
	v_fmac_f32_e32 v81, v80, v80
	v_fmac_f32_e32 v83, v82, v82
	v_lshlrev_b32_e32 v78, 16, v69
	v_lshlrev_b32_e32 v86, 16, v73
	v_mul_f32_e32 v79, v79, v79
	v_mul_f32_e32 v87, v87, v87
	v_fmac_f32_e32 v77, v76, v76
	v_fmac_f32_e32 v85, v84, v84
	v_add_f32_e32 v64, v65, v75
	v_add_f32_e32 v65, v81, v83
	v_fmac_f32_e32 v79, v78, v78
	v_fmac_f32_e32 v87, v86, v86
	v_add_f32_e32 v64, v77, v64
	v_add_f32_e32 v65, v85, v65
	v_add_f32_e32 v64, v79, v64
	v_add_f32_e32 v65, v87, v65
	v_add_f32_e32 v64, v64, v65
	v_mov_b32_e32 v65, v64
	v_mov_b32_e32 v159, v64
	s_nop 1
	v_permlane16_swap_b32_e32 v65, v159
	global_store_dwordx4 v[88:89], v[66:69], off
	global_store_dwordx4 v[88:89], v[70:73], off offset:256
	s_waitcnt lgkmcnt(0)
	v_add_f32_e32 v64, v159, v65
	v_mov_b32_e32 v65, v64
	v_mov_b32_e32 v112, v64
	s_nop 1
	v_permlane32_swap_b32_e32 v65, v112
	s_and_saveexec_b64 s[36:37], s[6:7]
	s_cbranch_execz .LBB0_833
	s_waitcnt lgkmcnt(0)
	v_add_f32_e32 v64, v112, v65
	ds_write_b32 v154, v64
.LBB0_833:
	s_or_b64 exec, exec, s[36:37]
	s_waitcnt lgkmcnt(0)
	v_lshlrev_b64 v[64:65], 11, v[142:143]
	v_lshl_add_u64 v[64:65], s[48:49], 0, v[64:65]
	v_lshl_add_u64 v[64:65], v[140:141], 1, v[64:65]
	v_add_co_u32_e32 v74, vcc, 0x40000, v64
	v_lshl_add_u64 v[76:77], v[64:65], 0, s[10:11]
	s_nop 0
	v_addc_co_u32_e32 v75, vcc, 0, v65, vcc
	global_load_dwordx4 v[66:69], v[74:75], off
	global_load_dwordx4 v[70:73], v[76:77], off offset:256
	s_waitcnt vmcnt(1)
	v_lshlrev_b32_e32 v78, 16, v66
	v_and_b32_e32 v79, 0xffff0000, v66
	v_lshlrev_b32_e32 v66, 16, v67
	v_and_b32_e32 v67, 0xffff0000, v67
	s_waitcnt vmcnt(0)
	v_lshlrev_b32_e32 v82, 16, v70
	v_and_b32_e32 v83, 0xffff0000, v70
	v_lshlrev_b32_e32 v70, 16, v71
	v_and_b32_e32 v71, 0xffff0000, v71
	v_lshlrev_b32_e32 v80, 16, v68
	v_and_b32_e32 v81, 0xffff0000, v68
	v_lshlrev_b32_e32 v68, 16, v69
	v_and_b32_e32 v69, 0xffff0000, v69
	v_lshlrev_b32_e32 v84, 16, v72
	v_and_b32_e32 v85, 0xffff0000, v72
	v_lshlrev_b32_e32 v72, 16, v73
	v_and_b32_e32 v73, 0xffff0000, v73
	v_pk_add_f32 v[62:63], v[62:63], v[66:67]
	v_pk_add_f32 v[60:61], v[60:61], v[78:79]
	v_pk_add_f32 v[66:67], v[54:55], v[70:71]
	v_pk_add_f32 v[54:55], v[52:53], v[82:83]
	v_pk_add_f32 v[58:59], v[58:59], v[68:69]
	v_pk_add_f32 v[56:57], v[56:57], v[80:81]
	v_pk_add_f32 v[68:69], v[50:51], v[72:73]
	v_pk_add_f32 v[48:49], v[48:49], v[84:85]
	v_cvt_pk_bf16_f32 v50, v60, v61
	v_cvt_pk_bf16_f32 v51, v62, v63
	v_cvt_pk_bf16_f32 v54, v54, v55
	v_cvt_pk_bf16_f32 v55, v66, v67
	v_cvt_pk_bf16_f32 v52, v56, v57
	v_cvt_pk_bf16_f32 v53, v58, v59
	v_cvt_pk_bf16_f32 v56, v48, v49
	v_cvt_pk_bf16_f32 v57, v68, v69
	v_and_b32_e32 v49, 0xffff0000, v50
	v_and_b32_e32 v59, 0xffff0000, v51
	v_and_b32_e32 v67, 0xffff0000, v54
	v_and_b32_e32 v69, 0xffff0000, v55
	v_lshlrev_b32_e32 v48, 16, v50
	v_lshlrev_b32_e32 v58, 16, v51
	v_and_b32_e32 v61, 0xffff0000, v52
	v_lshlrev_b32_e32 v66, 16, v54
	v_lshlrev_b32_e32 v68, 16, v55
	v_and_b32_e32 v71, 0xffff0000, v56
	v_mul_f32_e32 v49, v49, v49
	v_mul_f32_e32 v59, v59, v59
	v_mul_f32_e32 v67, v67, v67
	v_mul_f32_e32 v69, v69, v69
	v_lshlrev_b32_e32 v60, 16, v52
	v_and_b32_e32 v63, 0xffff0000, v53
	v_lshlrev_b32_e32 v70, 16, v56
	v_and_b32_e32 v73, 0xffff0000, v57
	v_mul_f32_e32 v61, v61, v61
	v_mul_f32_e32 v71, v71, v71
	v_fmac_f32_e32 v49, v48, v48
	v_fmac_f32_e32 v59, v58, v58
	v_fmac_f32_e32 v67, v66, v66
	v_fmac_f32_e32 v69, v68, v68
	v_lshlrev_b32_e32 v62, 16, v53
	v_lshlrev_b32_e32 v72, 16, v57
	v_mul_f32_e32 v63, v63, v63
	v_mul_f32_e32 v73, v73, v73
	v_fmac_f32_e32 v61, v60, v60
	v_fmac_f32_e32 v71, v70, v70
	v_add_f32_e32 v48, v49, v59
	v_add_f32_e32 v49, v67, v69
	v_fmac_f32_e32 v63, v62, v62
	v_fmac_f32_e32 v73, v72, v72
	v_add_f32_e32 v48, v61, v48
	v_add_f32_e32 v49, v71, v49
	v_add_f32_e32 v48, v63, v48
	v_add_f32_e32 v49, v73, v49
	v_add_f32_e32 v48, v48, v49
	v_mov_b32_e32 v49, v48
	v_mov_b32_e32 v159, v48
	s_nop 1
	v_permlane16_swap_b32_e32 v49, v159
	global_store_dwordx4 v[74:75], v[50:53], off
	global_store_dwordx4 v[76:77], v[54:57], off offset:256
	s_waitcnt lgkmcnt(0)
	v_add_f32_e32 v48, v159, v49
	v_mov_b32_e32 v49, v48
	v_mov_b32_e32 v112, v48
	s_nop 1
	v_permlane32_swap_b32_e32 v49, v112
	s_and_saveexec_b64 s[36:37], s[6:7]
	s_cbranch_execz .LBB0_835
	s_waitcnt lgkmcnt(0)
	v_add_f32_e32 v48, v112, v49
	ds_write_b32 v155, v48
; #define PG8_LAS __attribute__((address_space(3)))
;     __device__ __forceinline__ void operator()(const f32x4 (&acc)[2][2][4][2], const Unit& u, int wr, int wc, int fr, int fq, PG8_LAS unsigned char* lds, int wid) const {
;     ...
;                 float s = 0.f;
; #pragma unroll
;                 for (int bj = 0; bj < 2; ++bj) {
;                     const size_t off = (size_t)(row0 + ai * HALF + m * 16) * 1024 + col0 + bj * HALF;
;                     f32x4 b0, b1;
;                     if (FIRST) { b0 = *(const f32x4*)(base32 + off); b1 = *(const f32x4*)(base32 + off + 4); }
;                     else { const u32x4 r = *(const u32x4*)(xn + off);
;                         b0 = (f32x4){__uint_as_float(r.x << 16), __uint_as_float(r.x & 0xffff0000u), __uint_as_float(r.y << 16), __uint_as_float(r.y & 0xffff0000u)};
;                         b1 = (f32x4){__uint_as_float(r.z << 16), __uint_as_float(r.z & 0xffff0000u), __uint_as_float(r.w << 16), __uint_as_float(r.w & 0xffff0000u)}; }
;                     const f32x4 v0 = b0 + alpha * acc[ai][bj][m][0], v1 = b1 + alpha * acc[ai][bj][m][1];
;                     if (LAST) { *(f32x4*)(out32 + off) = v0; *(f32x4*)(out32 + off + 4) = v1; }
;                     else {
;                         u32x4 w; w.x = pk_bf16(v0[0], v0[1]); w.y = pk_bf16(v0[2], v0[3]); w.z = pk_bf16(v1[0], v1[1]); w.w = pk_bf16(v1[2], v1[3]);
;                         *(u32x4*)(xn + off) = w;
;                         const float r0 = __uint_as_float(w.x << 16), r1 = __uint_as_float(w.x & 0xffff0000u), r2 = __uint_as_float(w.y << 16), r3 = __uint_as_float(w.y & 0xffff0000u);
;                         const float r4 = __uint_as_float(w.z << 16), r5 = __uint_as_float(w.z & 0xffff0000u), r6 = __uint_as_float(w.w << 16), r7 = __uint_as_float(w.w & 0xffff0000u);
;                         s += (r0 * r0 + r1 * r1) + (r2 * r2 + r3 * r3) + (r4 * r4 + r5 * r5) + (r6 * r6 + r7 * r7);
;                     }
;                 }
;                 if (!LAST) { s += __shfl_xor(s, 16); s += __shfl_xor(s, 32);
;                     if (fq == 0) *(PG8_LAS float*)(lds + PRE_SLOT + 4096 + ((wr * 64 + fr + ai * HALF + m * 16) * 4 + wc) * 4) = s; }
.LBB0_835:
	s_or_b64 exec, exec, s[36:37]
	v_add_co_u32_e32 v56, vcc, 0x48000, v64
	v_lshl_add_u64 v[58:59], v[64:65], 0, s[20:21]
	s_nop 0
	v_addc_co_u32_e32 v57, vcc, 0, v65, vcc
	s_waitcnt lgkmcnt(0)
	global_load_dwordx4 v[48:51], v[56:57], off
	global_load_dwordx4 v[52:55], v[58:59], off offset:256
	s_waitcnt vmcnt(1)
	v_lshlrev_b32_e32 v60, 16, v48
	v_and_b32_e32 v61, 0xffff0000, v48
	v_lshlrev_b32_e32 v48, 16, v49
	v_and_b32_e32 v49, 0xffff0000, v49
	s_waitcnt vmcnt(0)
	v_lshlrev_b32_e32 v64, 16, v52
	v_and_b32_e32 v65, 0xffff0000, v52
	v_lshlrev_b32_e32 v52, 16, v53
	v_and_b32_e32 v53, 0xffff0000, v53
	v_lshlrev_b32_e32 v62, 16, v50
	v_and_b32_e32 v63, 0xffff0000, v50
	v_lshlrev_b32_e32 v50, 16, v51
	v_and_b32_e32 v51, 0xffff0000, v51
	v_lshlrev_b32_e32 v66, 16, v54
	v_and_b32_e32 v67, 0xffff0000, v54
	v_lshlrev_b32_e32 v54, 16, v55
	v_and_b32_e32 v55, 0xffff0000, v55
	v_pk_add_f32 v[46:47], v[46:47], v[48:49]
	v_pk_add_f32 v[44:45], v[44:45], v[60:61]
	v_pk_add_f32 v[48:49], v[38:39], v[52:53]
	v_pk_add_f32 v[38:39], v[36:37], v[64:65]
	v_pk_add_f32 v[42:43], v[42:43], v[50:51]
	v_pk_add_f32 v[40:41], v[40:41], v[62:63]
	v_pk_add_f32 v[50:51], v[34:35], v[54:55]
	v_pk_add_f32 v[32:33], v[32:33], v[66:67]
	v_cvt_pk_bf16_f32 v34, v44, v45
	v_cvt_pk_bf16_f32 v35, v46, v47
	v_cvt_pk_bf16_f32 v38, v38, v39
	v_cvt_pk_bf16_f32 v39, v48, v49
	v_cvt_pk_bf16_f32 v36, v40, v41
	v_cvt_pk_bf16_f32 v37, v42, v43
	v_cvt_pk_bf16_f32 v40, v32, v33
	v_cvt_pk_bf16_f32 v41, v50, v51
	v_and_b32_e32 v33, 0xffff0000, v34
	v_and_b32_e32 v43, 0xffff0000, v35
	v_and_b32_e32 v49, 0xffff0000, v38
	v_and_b32_e32 v51, 0xffff0000, v39
	v_lshlrev_b32_e32 v32, 16, v34
	v_lshlrev_b32_e32 v42, 16, v35
	v_and_b32_e32 v45, 0xffff0000, v36
	v_lshlrev_b32_e32 v48, 16, v38
	v_lshlrev_b32_e32 v50, 16, v39
	v_and_b32_e32 v53, 0xffff0000, v40
	v_mul_f32_e32 v33, v33, v33
	v_mul_f32_e32 v43, v43, v43
	v_mul_f32_e32 v49, v49, v49
	v_mul_f32_e32 v51, v51, v51
	v_lshlrev_b32_e32 v44, 16, v36
	v_and_b32_e32 v47, 0xffff0000, v37
	v_lshlrev_b32_e32 v52, 16, v40
	v_and_b32_e32 v55, 0xffff0000, v41
	v_mul_f32_e32 v45, v45, v45
	v_mul_f32_e32 v53, v53, v53
	v_fmac_f32_e32 v33, v32, v32
	v_fmac_f32_e32 v43, v42, v42
	v_fmac_f32_e32 v49, v48, v48
	v_fmac_f32_e32 v51, v50, v50
	v_lshlrev_b32_e32 v46, 16, v37
	v_lshlrev_b32_e32 v54, 16, v41
	v_mul_f32_e32 v47, v47, v47
	v_mul_f32_e32 v55, v55, v55
	v_fmac_f32_e32 v45, v44, v44
	v_fmac_f32_e32 v53, v52, v52
	v_add_f32_e32 v32, v33, v43
	v_add_f32_e32 v33, v49, v51
	v_fmac_f32_e32 v47, v46, v46
	v_fmac_f32_e32 v55, v54, v54
	v_add_f32_e32 v32, v45, v32
	v_add_f32_e32 v33, v53, v33
	v_add_f32_e32 v32, v47, v32
	v_add_f32_e32 v33, v55, v33
	v_add_f32_e32 v32, v32, v33
	v_mov_b32_e32 v33, v32
	v_mov_b32_e32 v159, v32
	s_nop 1
	v_permlane16_swap_b32_e32 v33, v159
	global_store_dwordx4 v[56:57], v[34:37], off
	global_store_dwordx4 v[58:59], v[38:41], off offset:256
	s_waitcnt lgkmcnt(0)
	v_add_f32_e32 v32, v159, v33
	v_mov_b32_e32 v33, v32
	v_mov_b32_e32 v112, v32
	s_nop 1
	v_permlane32_swap_b32_e32 v33, v112
	s_and_saveexec_b64 s[36:37], s[6:7]
	s_cbranch_execz .LBB0_837
	s_waitcnt lgkmcnt(0)
	v_add_f32_e32 v32, v112, v33
	ds_write_b32 v156, v32
; #define PG8_LAS __attribute__((address_space(3)))
;     __device__ __forceinline__ void operator()(const f32x4 (&acc)[2][2][4][2], const Unit& u, int wr, int wc, int fr, int fq, PG8_LAS unsigned char* lds, int wid) const {
;     ...
;                 float s = 0.f;
; #pragma unroll
;                 for (int bj = 0; bj < 2; ++bj) {
;                     const size_t off = (size_t)(row0 + ai * HALF + m * 16) * 1024 + col0 + bj * HALF;
;                     f32x4 b0, b1;
;                     if (FIRST) { b0 = *(const f32x4*)(base32 + off); b1 = *(const f32x4*)(base32 + off + 4); }
;                     else { const u32x4 r = *(const u32x4*)(xn + off);
;                         b0 = (f32x4){__uint_as_float(r.x << 16), __uint_as_float(r.x & 0xffff0000u), __uint_as_float(r.y << 16), __uint_as_float(r.y & 0xffff0000u)};
;                         b1 = (f32x4){__uint_as_float(r.z << 16), __uint_as_float(r.z & 0xffff0000u), __uint_as_float(r.w << 16), __uint_as_float(r.w & 0xffff0000u)}; }
;                     const f32x4 v0 = b0 + alpha * acc[ai][bj][m][0], v1 = b1 + alpha * acc[ai][bj][m][1];
;                     if (LAST) { *(f32x4*)(out32 + off) = v0; *(f32x4*)(out32 + off + 4) = v1; }
;                     else {
;                         u32x4 w; w.x = pk_bf16(v0[0], v0[1]); w.y = pk_bf16(v0[2], v0[3]); w.z = pk_bf16(v1[0], v1[1]); w.w = pk_bf16(v1[2], v1[3]);
;                         *(u32x4*)(xn + off) = w;
;                         const float r0 = __uint_as_float(w.x << 16), r1 = __uint_as_float(w.x & 0xffff0000u), r2 = __uint_as_float(w.y << 16), r3 = __uint_as_float(w.y & 0xffff0000u);
;                         const float r4 = __uint_as_float(w.z << 16), r5 = __uint_as_float(w.z & 0xffff0000u), r6 = __uint_as_float(w.w << 16), r7 = __uint_as_float(w.w & 0xffff0000u);
;                         s += (r0 * r0 + r1 * r1) + (r2 * r2 + r3 * r3) + (r4 * r4 + r5 * r5) + (r6 * r6 + r7 * r7);
;                     }
;                 }
;                 if (!LAST) { s += __shfl_xor(s, 16); s += __shfl_xor(s, 32);
;                     if (fq == 0) *(PG8_LAS float*)(lds + PRE_SLOT + 4096 + ((wr * 64 + fr + ai * HALF + m * 16) * 4 + wc) * 4) = s; }
.LBB0_837:
	s_or_b64 exec, exec, s[36:37]
	s_waitcnt lgkmcnt(0)
	v_lshlrev_b64 v[32:33], 11, v[142:143]
	v_lshl_add_u64 v[32:33], s[48:49], 0, v[32:33]
	v_lshl_add_u64 v[32:33], v[140:141], 1, v[32:33]
	v_add_co_u32_e32 v42, vcc, 0x50000, v32
	v_lshl_add_u64 v[44:45], v[32:33], 0, s[22:23]
	s_nop 0
	v_addc_co_u32_e32 v43, vcc, 0, v33, vcc
	global_load_dwordx4 v[34:37], v[42:43], off
	global_load_dwordx4 v[38:41], v[44:45], off offset:256
	s_waitcnt vmcnt(1)
	v_lshlrev_b32_e32 v46, 16, v34
	v_and_b32_e32 v47, 0xffff0000, v34
	v_lshlrev_b32_e32 v34, 16, v35
	v_and_b32_e32 v35, 0xffff0000, v35
	s_waitcnt vmcnt(0)
	v_lshlrev_b32_e32 v50, 16, v38
	v_and_b32_e32 v51, 0xffff0000, v38
	v_lshlrev_b32_e32 v38, 16, v39
	v_and_b32_e32 v39, 0xffff0000, v39
	v_lshlrev_b32_e32 v48, 16, v36
	v_and_b32_e32 v49, 0xffff0000, v36
	v_lshlrev_b32_e32 v36, 16, v37
	v_and_b32_e32 v37, 0xffff0000, v37
	v_lshlrev_b32_e32 v52, 16, v40
	v_and_b32_e32 v53, 0xffff0000, v40
	v_lshlrev_b32_e32 v40, 16, v41
	v_and_b32_e32 v41, 0xffff0000, v41
	v_pk_add_f32 v[30:31], v[30:31], v[34:35]
	v_pk_add_f32 v[28:29], v[28:29], v[46:47]
	v_pk_add_f32 v[34:35], v[22:23], v[38:39]
	v_pk_add_f32 v[22:23], v[20:21], v[50:51]
	v_pk_add_f32 v[26:27], v[26:27], v[36:37]
	v_pk_add_f32 v[24:25], v[24:25], v[48:49]
	v_pk_add_f32 v[36:37], v[18:19], v[40:41]
	v_pk_add_f32 v[16:17], v[16:17], v[52:53]
	v_cvt_pk_bf16_f32 v18, v28, v29
	v_cvt_pk_bf16_f32 v19, v30, v31
	v_cvt_pk_bf16_f32 v22, v22, v23
	v_cvt_pk_bf16_f32 v23, v34, v35
	v_cvt_pk_bf16_f32 v20, v24, v25
	v_cvt_pk_bf16_f32 v21, v26, v27
	v_cvt_pk_bf16_f32 v24, v16, v17
	v_cvt_pk_bf16_f32 v25, v36, v37
	v_and_b32_e32 v17, 0xffff0000, v18
	v_and_b32_e32 v27, 0xffff0000, v19
	v_and_b32_e32 v35, 0xffff0000, v22
	v_and_b32_e32 v37, 0xffff0000, v23
	v_lshlrev_b32_e32 v16, 16, v18
	v_lshlrev_b32_e32 v26, 16, v19
	v_and_b32_e32 v29, 0xffff0000, v20
	v_lshlrev_b32_e32 v34, 16, v22
	v_lshlrev_b32_e32 v36, 16, v23
	v_and_b32_e32 v39, 0xffff0000, v24
	v_mul_f32_e32 v17, v17, v17
	v_mul_f32_e32 v27, v27, v27
	v_mul_f32_e32 v35, v35, v35
	v_mul_f32_e32 v37, v37, v37
	v_lshlrev_b32_e32 v28, 16, v20
	v_and_b32_e32 v31, 0xffff0000, v21
	v_lshlrev_b32_e32 v38, 16, v24
	v_and_b32_e32 v41, 0xffff0000, v25
	v_mul_f32_e32 v29, v29, v29
	v_mul_f32_e32 v39, v39, v39
	v_fmac_f32_e32 v17, v16, v16
	v_fmac_f32_e32 v27, v26, v26
	v_fmac_f32_e32 v35, v34, v34
	v_fmac_f32_e32 v37, v36, v36
	v_lshlrev_b32_e32 v30, 16, v21
	v_lshlrev_b32_e32 v40, 16, v25
	v_mul_f32_e32 v31, v31, v31
	v_mul_f32_e32 v41, v41, v41
	v_fmac_f32_e32 v29, v28, v28
	v_fmac_f32_e32 v39, v38, v38
	v_add_f32_e32 v16, v17, v27
	v_add_f32_e32 v17, v35, v37
	v_fmac_f32_e32 v31, v30, v30
	v_fmac_f32_e32 v41, v40, v40
	v_add_f32_e32 v16, v29, v16
	v_add_f32_e32 v17, v39, v17
	v_add_f32_e32 v16, v31, v16
	v_add_f32_e32 v17, v41, v17
	v_add_f32_e32 v16, v16, v17
	v_mov_b32_e32 v17, v16
	v_mov_b32_e32 v159, v16
	s_nop 1
	v_permlane16_swap_b32_e32 v17, v159
	global_store_dwordx4 v[42:43], v[18:21], off
	global_store_dwordx4 v[44:45], v[22:25], off offset:256
	s_waitcnt lgkmcnt(0)
	v_add_f32_e32 v16, v159, v17
	v_mov_b32_e32 v17, v16
	v_mov_b32_e32 v112, v16
	s_nop 1
	v_permlane32_swap_b32_e32 v17, v112
	s_and_saveexec_b64 s[36:37], s[6:7]
	s_cbranch_execz .LBB0_839
	s_waitcnt lgkmcnt(0)
	v_add_f32_e32 v16, v112, v17
	ds_write_b32 v157, v16
.LBB0_839:
	s_or_b64 exec, exec, s[36:37]
	v_add_co_u32_e32 v24, vcc, 0x58000, v32
	v_lshl_add_u64 v[26:27], v[32:33], 0, s[24:25]
	s_nop 0
	v_addc_co_u32_e32 v25, vcc, 0, v33, vcc
	s_waitcnt lgkmcnt(0)
	global_load_dwordx4 v[16:19], v[24:25], off
	global_load_dwordx4 v[20:23], v[26:27], off offset:256
	s_waitcnt vmcnt(1)
	v_lshlrev_b32_e32 v28, 16, v16
	v_and_b32_e32 v29, 0xffff0000, v16
	v_lshlrev_b32_e32 v16, 16, v17
	v_and_b32_e32 v17, 0xffff0000, v17
	s_waitcnt vmcnt(0)
	v_lshlrev_b32_e32 v32, 16, v20
	v_and_b32_e32 v33, 0xffff0000, v20
	v_lshlrev_b32_e32 v20, 16, v21
	v_and_b32_e32 v21, 0xffff0000, v21
	v_lshlrev_b32_e32 v30, 16, v18
	v_and_b32_e32 v31, 0xffff0000, v18
	v_lshlrev_b32_e32 v18, 16, v19
	v_and_b32_e32 v19, 0xffff0000, v19
	v_lshlrev_b32_e32 v34, 16, v22
	v_and_b32_e32 v35, 0xffff0000, v22
	v_lshlrev_b32_e32 v22, 16, v23
	v_and_b32_e32 v23, 0xffff0000, v23
	v_pk_add_f32 v[14:15], v[14:15], v[16:17]
	v_pk_add_f32 v[12:13], v[12:13], v[28:29]
	v_pk_add_f32 v[16:17], v[6:7], v[20:21]
	v_pk_add_f32 v[6:7], v[4:5], v[32:33]
	v_pk_add_f32 v[10:11], v[10:11], v[18:19]
	v_pk_add_f32 v[8:9], v[8:9], v[30:31]
	v_pk_add_f32 v[18:19], v[2:3], v[22:23]
	v_pk_add_f32 v[0:1], v[0:1], v[34:35]
	v_cvt_pk_bf16_f32 v2, v12, v13
	v_cvt_pk_bf16_f32 v3, v14, v15
	v_cvt_pk_bf16_f32 v6, v6, v7
	v_cvt_pk_bf16_f32 v7, v16, v17
	v_cvt_pk_bf16_f32 v4, v8, v9
	v_cvt_pk_bf16_f32 v5, v10, v11
	v_cvt_pk_bf16_f32 v8, v0, v1
	v_cvt_pk_bf16_f32 v9, v18, v19
	v_and_b32_e32 v1, 0xffff0000, v2
	v_and_b32_e32 v11, 0xffff0000, v3
	v_and_b32_e32 v17, 0xffff0000, v6
	v_and_b32_e32 v19, 0xffff0000, v7
	v_lshlrev_b32_e32 v0, 16, v2
	v_lshlrev_b32_e32 v10, 16, v3
	v_and_b32_e32 v13, 0xffff0000, v4
	v_lshlrev_b32_e32 v16, 16, v6
	v_lshlrev_b32_e32 v18, 16, v7
	v_and_b32_e32 v21, 0xffff0000, v8
	v_mul_f32_e32 v1, v1, v1
	v_mul_f32_e32 v11, v11, v11
	v_mul_f32_e32 v17, v17, v17
	v_mul_f32_e32 v19, v19, v19
	v_lshlrev_b32_e32 v12, 16, v4
	v_and_b32_e32 v15, 0xffff0000, v5
	v_lshlrev_b32_e32 v20, 16, v8
	v_and_b32_e32 v23, 0xffff0000, v9
	v_mul_f32_e32 v13, v13, v13
	v_mul_f32_e32 v21, v21, v21
	v_fmac_f32_e32 v1, v0, v0
	v_fmac_f32_e32 v11, v10, v10
	v_fmac_f32_e32 v17, v16, v16
	v_fmac_f32_e32 v19, v18, v18
	v_lshlrev_b32_e32 v14, 16, v5
	v_lshlrev_b32_e32 v22, 16, v9
	v_mul_f32_e32 v15, v15, v15
	v_mul_f32_e32 v23, v23, v23
	v_fmac_f32_e32 v13, v12, v12
	v_fmac_f32_e32 v21, v20, v20
	v_add_f32_e32 v0, v1, v11
	v_add_f32_e32 v1, v17, v19
	v_fmac_f32_e32 v15, v14, v14
	v_fmac_f32_e32 v23, v22, v22
	v_add_f32_e32 v0, v13, v0
	v_add_f32_e32 v1, v21, v1
	v_add_f32_e32 v0, v15, v0
	v_add_f32_e32 v1, v23, v1
	v_add_f32_e32 v0, v0, v1
	v_mov_b32_e32 v1, v0
	v_mov_b32_e32 v159, v0
	s_nop 1
	v_permlane16_swap_b32_e32 v1, v159
	global_store_dwordx4 v[24:25], v[2:5], off
	global_store_dwordx4 v[26:27], v[6:9], off offset:256
	s_waitcnt lgkmcnt(0)
	v_add_f32_e32 v0, v159, v1
	v_mov_b32_e32 v1, v0
	v_mov_b32_e32 v112, v0
	s_nop 1
	v_permlane32_swap_b32_e32 v1, v112
	s_and_saveexec_b64 s[36:37], s[6:7]
	s_cbranch_execz .LBB0_841
	s_waitcnt lgkmcnt(0)
	v_add_f32_e32 v0, v112, v1
	ds_write_b32 v158, v0

;     __device__ __forceinline__ void operator()(const f32x4 (&acc)[2][2][4][2], const Unit& u, int wr, int wc, int fr, int fq, PG8_LAS unsigned char* lds, int wid) const {
;         const int row0 = u.pm * BM + wr * 64 + fr, col0 = u.pn * BM + wc * 32 + 8 * fq;
;         constexpr float alpha = HALF_ALPHA ? 0.5f : 1.0f;
; #pragma unroll
;         for (int ai = 0; ai < 2; ++ai)
; #pragma unroll
;             for (int m = 0; m < 4; ++m) {
;                 float s = 0.f;
; #pragma unroll
;                 for (int bj = 0; bj < 2; ++bj) {
;                     const size_t off = (size_t)(row0 + ai * HALF + m * 16) * 1024 + col0 + bj * HALF;
;                     f32x4 b0, b1;
;                     if (FIRST) { b0 = *(const f32x4*)(base32 + off); b1 = *(const f32x4*)(base32 + off + 4); }
;                     else { const u32x4 r = *(const u32x4*)(xn + off);
;                         b0 = (f32x4){__uint_as_float(r.x << 16), __uint_as_float(r.x & 0xffff0000u), __uint_as_float(r.y << 16), __uint_as_float(r.y & 0xffff0000u)};
;                         b1 = (f32x4){__uint_as_float(r.z << 16), __uint_as_float(r.z & 0xffff0000u), __uint_as_float(r.w << 16), __uint_as_float(r.w & 0xffff0000u)}; }
;                     const f32x4 v0 = b0 + alpha * acc[ai][bj][m][0], v1 = b1 + alpha * acc[ai][bj][m][1];
;                     if (LAST) { *(f32x4*)(out32 + off) = v0; *(f32x4*)(out32 + off + 4) = v1; }
;                     else {
;                         u32x4 w; w.x = pk_bf16(v0[0], v0[1]); w.y = pk_bf16(v0[2], v0[3]); w.z = pk_bf16(v1[0], v1[1]); w.w = pk_bf16(v1[2], v1[3]);
;                         *(u32x4*)(xn + off) = w;
;                         const float r0 = __uint_as_float(w.x << 16), r1 = __uint_as_float(w.x & 0xffff0000u), r2 = __uint_as_float(w.y << 16), r3 = __uint_as_float(w.y & 0xffff0000u);
;                         const float r4 = __uint_as_float(w.z << 16), r5 = __uint_as_float(w.z & 0xffff0000u), r6 = __uint_as_float(w.w << 16), r7 = __uint_as_float(w.w & 0xffff0000u);
;                         s += (r0 * r0 + r1 * r1) + (r2 * r2 + r3 * r3) + (r4 * r4 + r5 * r5) + (r6 * r6 + r7 * r7);
;                     }
;                 }
;                 if (!LAST) { s += __shfl_xor(s, 16); s += __shfl_xor(s, 32);
;                     if (fq == 0) *(PG8_LAS float*)(lds + PRE_SLOT + 4096 + ((wr * 64 + fr + ai * HALF + m * 16) * 4 + wc) * 4) = s; }
.LBB0_1191:
	s_lshl_b32 s38, s97, 8
	v_add_u32_e32 v142, s38, v144
	v_ashrrev_i32_e32 v143, 31, v142
	v_lshl_or_b32 v140, s96, 8, v146
	v_lshlrev_b64 v[160:161], 11, v[142:143]
	v_ashrrev_i32_e32 v141, 31, v140
	v_lshl_add_u64 v[160:161], s[48:49], 0, v[160:161]
	v_lshl_add_u64 v[168:169], v[140:141], 1, v[160:161]
	global_load_dwordx4 v[160:163], v[168:169], off
	global_load_dwordx4 v[164:167], v[168:169], off offset:256
	v_and_b32_e32 v170, 64, v150
	v_add_u32_e32 v178, 64, v170
	v_xor_b32_e32 v159, 16, v150
	v_cmp_lt_i32_e32 vcc, v159, v178
	s_waitcnt vmcnt(0)
	v_lshlrev_b32_e32 v170, 16, v160
	v_and_b32_e32 v171, 0xffff0000, v160
	v_lshlrev_b32_e32 v160, 16, v161
	v_and_b32_e32 v161, 0xffff0000, v161
	v_lshlrev_b32_e32 v172, 16, v162
	v_and_b32_e32 v173, 0xffff0000, v162
	v_lshlrev_b32_e32 v162, 16, v163
	v_and_b32_e32 v163, 0xffff0000, v163
	v_lshlrev_b32_e32 v174, 16, v164
	v_and_b32_e32 v175, 0xffff0000, v164
	v_lshlrev_b32_e32 v164, 16, v165
	v_and_b32_e32 v165, 0xffff0000, v165
	v_lshlrev_b32_e32 v176, 16, v166
	v_and_b32_e32 v177, 0xffff0000, v166
	v_lshlrev_b32_e32 v166, 16, v167
	v_and_b32_e32 v167, 0xffff0000, v167
	v_pk_fma_f32 v[126:127], v[126:127], 0.5, v[160:161] op_sel_hi:[1,0,1]
	v_pk_fma_f32 v[124:125], v[124:125], 0.5, v[170:171] op_sel_hi:[1,0,1]
	v_pk_fma_f32 v[122:123], v[122:123], 0.5, v[162:163] op_sel_hi:[1,0,1]
	v_pk_fma_f32 v[120:121], v[120:121], 0.5, v[172:173] op_sel_hi:[1,0,1]
	v_pk_fma_f32 v[160:161], v[118:119], 0.5, v[164:165] op_sel_hi:[1,0,1]
	v_pk_fma_f32 v[162:163], v[116:117], 0.5, v[174:175] op_sel_hi:[1,0,1]
	v_pk_fma_f32 v[114:115], v[114:115], 0.5, v[166:167] op_sel_hi:[1,0,1]
	v_pk_fma_f32 v[112:113], v[112:113], 0.5, v[176:177] op_sel_hi:[1,0,1]
	v_cvt_pk_bf16_f32 v116, v124, v125
	v_cvt_pk_bf16_f32 v117, v126, v127
	v_cvt_pk_bf16_f32 v118, v120, v121
	v_cvt_pk_bf16_f32 v120, v162, v163
	v_cvt_pk_bf16_f32 v121, v160, v161
	v_cvt_pk_bf16_f32 v119, v122, v123
	v_cvt_pk_bf16_f32 v122, v112, v113
	v_cvt_pk_bf16_f32 v123, v114, v115
	v_and_b32_e32 v113, 0xffff0000, v116
	v_and_b32_e32 v115, 0xffff0000, v117
	v_and_b32_e32 v161, 0xffff0000, v120
	v_and_b32_e32 v163, 0xffff0000, v121
	v_lshlrev_b32_e32 v112, 16, v116
	v_lshlrev_b32_e32 v114, 16, v117
	v_and_b32_e32 v125, 0xffff0000, v118
	v_lshlrev_b32_e32 v160, 16, v120
	v_lshlrev_b32_e32 v162, 16, v121
	v_and_b32_e32 v165, 0xffff0000, v122
	v_mul_f32_e32 v113, v113, v113
	v_mul_f32_e32 v115, v115, v115
	v_mul_f32_e32 v161, v161, v161
	v_mul_f32_e32 v163, v163, v163
	v_lshlrev_b32_e32 v124, 16, v118
	v_and_b32_e32 v127, 0xffff0000, v119
	v_lshlrev_b32_e32 v164, 16, v122
	v_and_b32_e32 v167, 0xffff0000, v123
	v_mul_f32_e32 v125, v125, v125
	v_mul_f32_e32 v165, v165, v165
	v_fmac_f32_e32 v113, v112, v112
	v_fmac_f32_e32 v115, v114, v114
	v_fmac_f32_e32 v161, v160, v160
	v_fmac_f32_e32 v163, v162, v162
	v_lshlrev_b32_e32 v126, 16, v119
	v_lshlrev_b32_e32 v166, 16, v123
	v_mul_f32_e32 v127, v127, v127
	v_mul_f32_e32 v167, v167, v167
	v_fmac_f32_e32 v125, v124, v124
	v_fmac_f32_e32 v165, v164, v164
	v_add_f32_e32 v112, v113, v115
	v_add_f32_e32 v113, v161, v163
	v_fmac_f32_e32 v127, v126, v126
	v_fmac_f32_e32 v167, v166, v166
	v_add_f32_e32 v112, v125, v112
	v_add_f32_e32 v113, v165, v113
	v_cndmask_b32_e32 v159, v150, v159, vcc
	v_add_f32_e32 v112, v127, v112
	v_add_f32_e32 v113, v167, v113
	v_lshlrev_b32_e32 v159, 2, v159
	v_add_f32_e32 v113, v112, v113
	v_mov_b32_e32 v114, v113
	v_mov_b32_e32 v159, v113
	s_nop 1
	v_permlane16_swap_b32_e32 v114, v159
	v_xor_b32_e32 v112, 32, v150
	v_cmp_lt_i32_e32 vcc, v112, v178
	global_store_dwordx4 v[168:169], v[116:119], off
	global_store_dwordx4 v[168:169], v[120:123], off offset:256
	v_cndmask_b32_e32 v112, v150, v112, vcc
	v_lshlrev_b32_e32 v112, 2, v112
	s_waitcnt lgkmcnt(0)
	v_add_f32_e32 v113, v159, v114
	v_mov_b32_e32 v114, v113
	v_mov_b32_e32 v112, v113
	s_nop 1
	v_permlane32_swap_b32_e32 v114, v112
	s_and_saveexec_b64 s[40:41], s[8:9]
	s_cbranch_execz .LBB0_1193
	s_waitcnt lgkmcnt(0)
	v_add_f32_e32 v113, v112, v114
	ds_write_b32 v151, v113
.LBB0_1193:
	s_or_b64 exec, exec, s[40:41]
	s_waitcnt lgkmcnt(0)
	v_or_b32_e32 v114, 16, v142
	v_ashrrev_i32_e32 v115, 31, v114
	v_lshlrev_b64 v[114:115], 11, v[114:115]
	v_lshl_add_u64 v[114:115], s[48:49], 0, v[114:115]
	v_lshl_add_u64 v[122:123], v[140:141], 1, v[114:115]
	global_load_dwordx4 v[114:117], v[122:123], off
	global_load_dwordx4 v[118:121], v[122:123], off offset:256
	s_waitcnt vmcnt(1)
	v_lshlrev_b32_e32 v124, 16, v114
	v_and_b32_e32 v125, 0xffff0000, v114
	v_lshlrev_b32_e32 v114, 16, v115
	v_and_b32_e32 v115, 0xffff0000, v115
	s_waitcnt vmcnt(0)
; #define PG8_LAS __attribute__((address_space(3)))
;     __device__ __forceinline__ void operator()(const f32x4 (&acc)[2][2][4][2], const Unit& u, int wr, int wc, int fr, int fq, PG8_LAS unsigned char* lds, int wid) const {
;     ...
;                 float s = 0.f;
; #pragma unroll
;                 for (int bj = 0; bj < 2; ++bj) {
;                     const size_t off = (size_t)(row0 + ai * HALF + m * 16) * 1024 + col0 + bj * HALF;
;                     f32x4 b0, b1;
;                     if (FIRST) { b0 = *(const f32x4*)(base32 + off); b1 = *(const f32x4*)(base32 + off + 4); }
;                     else { const u32x4 r = *(const u32x4*)(xn + off);
;                         b0 = (f32x4){__uint_as_float(r.x << 16), __uint_as_float(r.x & 0xffff0000u), __uint_as_float(r.y << 16), __uint_as_float(r.y & 0xffff0000u)};
;                         b1 = (f32x4){__uint_as_float(r.z << 16), __uint_as_float(r.z & 0xffff0000u), __uint_as_float(r.w << 16), __uint_as_float(r.w & 0xffff0000u)}; }
;                     const f32x4 v0 = b0 + alpha * acc[ai][bj][m][0], v1 = b1 + alpha * acc[ai][bj][m][1];
;                     if (LAST) { *(f32x4*)(out32 + off) = v0; *(f32x4*)(out32 + off + 4) = v1; }
;                     else {
;                         u32x4 w; w.x = pk_bf16(v0[0], v0[1]); w.y = pk_bf16(v0[2], v0[3]); w.z = pk_bf16(v1[0], v1[1]); w.w = pk_bf16(v1[2], v1[3]);
;                         *(u32x4*)(xn + off) = w;
;                         const float r0 = __uint_as_float(w.x << 16), r1 = __uint_as_float(w.x & 0xffff0000u), r2 = __uint_as_float(w.y << 16), r3 = __uint_as_float(w.y & 0xffff0000u);
;                         const float r4 = __uint_as_float(w.z << 16), r5 = __uint_as_float(w.z & 0xffff0000u), r6 = __uint_as_float(w.w << 16), r7 = __uint_as_float(w.w & 0xffff0000u);
;                         s += (r0 * r0 + r1 * r1) + (r2 * r2 + r3 * r3) + (r4 * r4 + r5 * r5) + (r6 * r6 + r7 * r7);
;                     }
;                 }
;                 if (!LAST) { s += __shfl_xor(s, 16); s += __shfl_xor(s, 32);
;                     if (fq == 0) *(PG8_LAS float*)(lds + PRE_SLOT + 4096 + ((wr * 64 + fr + ai * HALF + m * 16) * 4 + wc) * 4) = s; }
	v_lshlrev_b32_e32 v160, 16, v118
	v_and_b32_e32 v161, 0xffff0000, v118
	v_lshlrev_b32_e32 v118, 16, v119
	v_and_b32_e32 v119, 0xffff0000, v119
	v_lshlrev_b32_e32 v126, 16, v116
	v_and_b32_e32 v127, 0xffff0000, v116
	v_lshlrev_b32_e32 v116, 16, v117
	v_and_b32_e32 v117, 0xffff0000, v117
	v_lshlrev_b32_e32 v162, 16, v120
	v_and_b32_e32 v163, 0xffff0000, v120
	v_lshlrev_b32_e32 v120, 16, v121
	v_and_b32_e32 v121, 0xffff0000, v121
	v_pk_fma_f32 v[110:111], v[110:111], 0.5, v[114:115] op_sel_hi:[1,0,1]
	v_pk_fma_f32 v[108:109], v[108:109], 0.5, v[124:125] op_sel_hi:[1,0,1]
	v_pk_fma_f32 v[114:115], v[102:103], 0.5, v[118:119] op_sel_hi:[1,0,1]
	v_pk_fma_f32 v[102:103], v[100:101], 0.5, v[160:161] op_sel_hi:[1,0,1]
	v_pk_fma_f32 v[106:107], v[106:107], 0.5, v[116:117] op_sel_hi:[1,0,1]
	v_pk_fma_f32 v[104:105], v[104:105], 0.5, v[126:127] op_sel_hi:[1,0,1]
	v_pk_fma_f32 v[116:117], v[98:99], 0.5, v[120:121] op_sel_hi:[1,0,1]
	v_pk_fma_f32 v[96:97], v[96:97], 0.5, v[162:163] op_sel_hi:[1,0,1]
	v_cvt_pk_bf16_f32 v98, v108, v109
	v_cvt_pk_bf16_f32 v99, v110, v111
	v_cvt_pk_bf16_f32 v102, v102, v103
	v_cvt_pk_bf16_f32 v103, v114, v115
	v_cvt_pk_bf16_f32 v100, v104, v105
	v_cvt_pk_bf16_f32 v101, v106, v107
	v_cvt_pk_bf16_f32 v104, v96, v97
	v_cvt_pk_bf16_f32 v105, v116, v117
	v_and_b32_e32 v97, 0xffff0000, v98
	v_and_b32_e32 v107, 0xffff0000, v99
	v_and_b32_e32 v114, 0xffff0000, v102
	v_and_b32_e32 v116, 0xffff0000, v103
	v_lshlrev_b32_e32 v96, 16, v98
	v_lshlrev_b32_e32 v106, 16, v99
	v_and_b32_e32 v109, 0xffff0000, v100
	v_lshlrev_b32_e32 v113, 16, v102
	v_lshlrev_b32_e32 v115, 16, v103
	v_and_b32_e32 v118, 0xffff0000, v104
	v_mul_f32_e32 v97, v97, v97
	v_mul_f32_e32 v107, v107, v107
	v_mul_f32_e32 v114, v114, v114
	v_mul_f32_e32 v116, v116, v116
	v_lshlrev_b32_e32 v108, 16, v100
	v_and_b32_e32 v111, 0xffff0000, v101
	v_lshlrev_b32_e32 v117, 16, v104
	v_and_b32_e32 v120, 0xffff0000, v105
	v_mul_f32_e32 v109, v109, v109
	v_mul_f32_e32 v118, v118, v118
	v_fmac_f32_e32 v97, v96, v96
	v_fmac_f32_e32 v107, v106, v106
	v_fmac_f32_e32 v114, v113, v113
	v_fmac_f32_e32 v116, v115, v115
	v_lshlrev_b32_e32 v110, 16, v101
	v_lshlrev_b32_e32 v119, 16, v105
	v_mul_f32_e32 v111, v111, v111
	v_mul_f32_e32 v120, v120, v120
	v_fmac_f32_e32 v109, v108, v108
	v_fmac_f32_e32 v118, v117, v117
	v_add_f32_e32 v96, v97, v107
	v_add_f32_e32 v97, v114, v116
	v_fmac_f32_e32 v111, v110, v110
	v_fmac_f32_e32 v120, v119, v119
	v_add_f32_e32 v96, v109, v96
	v_add_f32_e32 v97, v118, v97
	v_add_f32_e32 v96, v111, v96
	v_add_f32_e32 v97, v120, v97
	v_add_f32_e32 v96, v96, v97
	v_mov_b32_e32 v97, v96
	v_mov_b32_e32 v159, v96
	s_nop 1
	v_permlane16_swap_b32_e32 v97, v159
	global_store_dwordx4 v[122:123], v[98:101], off
	global_store_dwordx4 v[122:123], v[102:105], off offset:256
	s_waitcnt lgkmcnt(0)
	v_add_f32_e32 v96, v159, v97
	v_mov_b32_e32 v97, v96
	v_mov_b32_e32 v112, v96
	s_nop 1
	v_permlane32_swap_b32_e32 v97, v112
	s_and_saveexec_b64 s[40:41], s[8:9]
	s_cbranch_execz .LBB0_1195
	s_waitcnt lgkmcnt(0)
	v_add_f32_e32 v96, v112, v97
	ds_write_b32 v152, v96
.LBB0_1195:
	s_or_b64 exec, exec, s[40:41]
	v_or_b32_e32 v96, 32, v142
	s_waitcnt lgkmcnt(0)
	v_ashrrev_i32_e32 v97, 31, v96
	v_lshlrev_b64 v[96:97], 11, v[96:97]
	v_lshl_add_u64 v[96:97], s[48:49], 0, v[96:97]
	v_lshl_add_u64 v[104:105], v[140:141], 1, v[96:97]
	global_load_dwordx4 v[96:99], v[104:105], off
	global_load_dwordx4 v[100:103], v[104:105], off offset:256
	s_waitcnt vmcnt(1)
	v_lshlrev_b32_e32 v106, 16, v96
	v_and_b32_e32 v107, 0xffff0000, v96
	v_lshlrev_b32_e32 v96, 16, v97
	v_and_b32_e32 v97, 0xffff0000, v97
	s_waitcnt vmcnt(0)
	v_lshlrev_b32_e32 v110, 16, v100
	v_and_b32_e32 v111, 0xffff0000, v100
	v_lshlrev_b32_e32 v100, 16, v101
	v_and_b32_e32 v101, 0xffff0000, v101
	v_lshlrev_b32_e32 v108, 16, v98
	v_and_b32_e32 v109, 0xffff0000, v98
	v_lshlrev_b32_e32 v98, 16, v99
	v_and_b32_e32 v99, 0xffff0000, v99
	v_lshlrev_b32_e32 v114, 16, v102
	v_and_b32_e32 v115, 0xffff0000, v102
	v_lshlrev_b32_e32 v102, 16, v103
	v_and_b32_e32 v103, 0xffff0000, v103
	v_pk_fma_f32 v[94:95], v[94:95], 0.5, v[96:97] op_sel_hi:[1,0,1]
	v_pk_fma_f32 v[92:93], v[92:93], 0.5, v[106:107] op_sel_hi:[1,0,1]
	v_pk_fma_f32 v[96:97], v[86:87], 0.5, v[100:101] op_sel_hi:[1,0,1]
	v_pk_fma_f32 v[86:87], v[84:85], 0.5, v[110:111] op_sel_hi:[1,0,1]
	v_pk_fma_f32 v[90:91], v[90:91], 0.5, v[98:99] op_sel_hi:[1,0,1]
	v_pk_fma_f32 v[88:89], v[88:89], 0.5, v[108:109] op_sel_hi:[1,0,1]
	v_pk_fma_f32 v[98:99], v[82:83], 0.5, v[102:103] op_sel_hi:[1,0,1]
	v_pk_fma_f32 v[80:81], v[80:81], 0.5, v[114:115] op_sel_hi:[1,0,1]
	v_cvt_pk_bf16_f32 v82, v92, v93
	v_cvt_pk_bf16_f32 v83, v94, v95
	v_cvt_pk_bf16_f32 v86, v86, v87
	v_cvt_pk_bf16_f32 v87, v96, v97
	v_cvt_pk_bf16_f32 v84, v88, v89
	v_cvt_pk_bf16_f32 v85, v90, v91
	v_cvt_pk_bf16_f32 v88, v80, v81
	v_cvt_pk_bf16_f32 v89, v98, v99
	v_and_b32_e32 v81, 0xffff0000, v82
	v_and_b32_e32 v91, 0xffff0000, v83
	v_and_b32_e32 v97, 0xffff0000, v86
	v_and_b32_e32 v99, 0xffff0000, v87
	v_lshlrev_b32_e32 v80, 16, v82
	v_lshlrev_b32_e32 v90, 16, v83
	v_and_b32_e32 v93, 0xffff0000, v84
	v_lshlrev_b32_e32 v96, 16, v86
	v_lshlrev_b32_e32 v98, 16, v87
	v_and_b32_e32 v101, 0xffff0000, v88
	v_mul_f32_e32 v81, v81, v81
	v_mul_f32_e32 v91, v91, v91
	v_mul_f32_e32 v97, v97, v97
	v_mul_f32_e32 v99, v99, v99
	v_lshlrev_b32_e32 v92, 16, v84
	v_and_b32_e32 v95, 0xffff0000, v85
	v_lshlrev_b32_e32 v100, 16, v88
	v_and_b32_e32 v103, 0xffff0000, v89
	v_mul_f32_e32 v93, v93, v93
	v_mul_f32_e32 v101, v101, v101
	v_fmac_f32_e32 v81, v80, v80
	v_fmac_f32_e32 v91, v90, v90
	v_fmac_f32_e32 v97, v96, v96
	v_fmac_f32_e32 v99, v98, v98
	v_lshlrev_b32_e32 v94, 16, v85
	v_lshlrev_b32_e32 v102, 16, v89
	v_mul_f32_e32 v95, v95, v95
	v_mul_f32_e32 v103, v103, v103
	v_fmac_f32_e32 v93, v92, v92
	v_fmac_f32_e32 v101, v100, v100
	v_add_f32_e32 v80, v81, v91
	v_add_f32_e32 v81, v97, v99
	v_fmac_f32_e32 v95, v94, v94
	v_fmac_f32_e32 v103, v102, v102
	v_add_f32_e32 v80, v93, v80
	v_add_f32_e32 v81, v101, v81
	v_add_f32_e32 v80, v95, v80
	v_add_f32_e32 v81, v103, v81
	v_add_f32_e32 v80, v80, v81
	v_mov_b32_e32 v81, v80
	v_mov_b32_e32 v159, v80
	s_nop 1
	v_permlane16_swap_b32_e32 v81, v159
	global_store_dwordx4 v[104:105], v[82:85], off
	global_store_dwordx4 v[104:105], v[86:89], off offset:256
	s_waitcnt lgkmcnt(0)
	v_add_f32_e32 v80, v159, v81
	v_mov_b32_e32 v81, v80
	v_mov_b32_e32 v112, v80
	s_nop 1
	v_permlane32_swap_b32_e32 v81, v112
	s_and_saveexec_b64 s[40:41], s[8:9]
	s_cbranch_execz .LBB0_1197
	s_waitcnt lgkmcnt(0)
	v_add_f32_e32 v80, v112, v81
	ds_write_b32 v153, v80
; #define PG8_LAS __attribute__((address_space(3)))
;     __device__ __forceinline__ void operator()(const f32x4 (&acc)[2][2][4][2], const Unit& u, int wr, int wc, int fr, int fq, PG8_LAS unsigned char* lds, int wid) const {
;     ...
;                 float s = 0.f;
; #pragma unroll
;                 for (int bj = 0; bj < 2; ++bj) {
;                     const size_t off = (size_t)(row0 + ai * HALF + m * 16) * 1024 + col0 + bj * HALF;
;                     f32x4 b0, b1;
;                     if (FIRST) { b0 = *(const f32x4*)(base32 + off); b1 = *(const f32x4*)(base32 + off + 4); }
;                     else { const u32x4 r = *(const u32x4*)(xn + off);
;                         b0 = (f32x4){__uint_as_float(r.x << 16), __uint_as_float(r.x & 0xffff0000u), __uint_as_float(r.y << 16), __uint_as_float(r.y & 0xffff0000u)};
;                         b1 = (f32x4){__uint_as_float(r.z << 16), __uint_as_float(r.z & 0xffff0000u), __uint_as_float(r.w << 16), __uint_as_float(r.w & 0xffff0000u)}; }
;                     const f32x4 v0 = b0 + alpha * acc[ai][bj][m][0], v1 = b1 + alpha * acc[ai][bj][m][1];
;                     if (LAST) { *(f32x4*)(out32 + off) = v0; *(f32x4*)(out32 + off + 4) = v1; }
;                     else {
;                         u32x4 w; w.x = pk_bf16(v0[0], v0[1]); w.y = pk_bf16(v0[2], v0[3]); w.z = pk_bf16(v1[0], v1[1]); w.w = pk_bf16(v1[2], v1[3]);
;                         *(u32x4*)(xn + off) = w;
;                         const float r0 = __uint_as_float(w.x << 16), r1 = __uint_as_float(w.x & 0xffff0000u), r2 = __uint_as_float(w.y << 16), r3 = __uint_as_float(w.y & 0xffff0000u);
;                         const float r4 = __uint_as_float(w.z << 16), r5 = __uint_as_float(w.z & 0xffff0000u), r6 = __uint_as_float(w.w << 16), r7 = __uint_as_float(w.w & 0xffff0000u);
;                         s += (r0 * r0 + r1 * r1) + (r2 * r2 + r3 * r3) + (r4 * r4 + r5 * r5) + (r6 * r6 + r7 * r7);
;                     }
;                 }
;                 if (!LAST) { s += __shfl_xor(s, 16); s += __shfl_xor(s, 32);
;                     if (fq == 0) *(PG8_LAS float*)(lds + PRE_SLOT + 4096 + ((wr * 64 + fr + ai * HALF + m * 16) * 4 + wc) * 4) = s; }
.LBB0_1197:
	s_or_b64 exec, exec, s[40:41]
	v_or_b32_e32 v80, 48, v142
	s_waitcnt lgkmcnt(0)
	v_ashrrev_i32_e32 v81, 31, v80
	v_lshlrev_b64 v[80:81], 11, v[80:81]
	v_lshl_add_u64 v[80:81], s[48:49], 0, v[80:81]
	v_lshl_add_u64 v[88:89], v[140:141], 1, v[80:81]
	global_load_dwordx4 v[80:83], v[88:89], off
	global_load_dwordx4 v[84:87], v[88:89], off offset:256
	s_waitcnt vmcnt(1)
	v_lshlrev_b32_e32 v90, 16, v80
	v_and_b32_e32 v91, 0xffff0000, v80
	v_lshlrev_b32_e32 v80, 16, v81
	v_and_b32_e32 v81, 0xffff0000, v81
	s_waitcnt vmcnt(0)
	v_lshlrev_b32_e32 v94, 16, v84
	v_and_b32_e32 v95, 0xffff0000, v84
	v_lshlrev_b32_e32 v84, 16, v85
	v_and_b32_e32 v85, 0xffff0000, v85
	v_lshlrev_b32_e32 v92, 16, v82
	v_and_b32_e32 v93, 0xffff0000, v82
	v_lshlrev_b32_e32 v82, 16, v83
	v_and_b32_e32 v83, 0xffff0000, v83
	v_lshlrev_b32_e32 v96, 16, v86
	v_and_b32_e32 v97, 0xffff0000, v86
	v_lshlrev_b32_e32 v86, 16, v87
	v_and_b32_e32 v87, 0xffff0000, v87
	v_pk_fma_f32 v[78:79], v[78:79], 0.5, v[80:81] op_sel_hi:[1,0,1]
	v_pk_fma_f32 v[76:77], v[76:77], 0.5, v[90:91] op_sel_hi:[1,0,1]
	v_pk_fma_f32 v[80:81], v[70:71], 0.5, v[84:85] op_sel_hi:[1,0,1]
	v_pk_fma_f32 v[70:71], v[68:69], 0.5, v[94:95] op_sel_hi:[1,0,1]
	v_pk_fma_f32 v[74:75], v[74:75], 0.5, v[82:83] op_sel_hi:[1,0,1]
	v_pk_fma_f32 v[72:73], v[72:73], 0.5, v[92:93] op_sel_hi:[1,0,1]
	v_pk_fma_f32 v[82:83], v[66:67], 0.5, v[86:87] op_sel_hi:[1,0,1]
	v_pk_fma_f32 v[64:65], v[64:65], 0.5, v[96:97] op_sel_hi:[1,0,1]
	v_cvt_pk_bf16_f32 v66, v76, v77
	v_cvt_pk_bf16_f32 v67, v78, v79
	v_cvt_pk_bf16_f32 v70, v70, v71
	v_cvt_pk_bf16_f32 v71, v80, v81
	v_cvt_pk_bf16_f32 v68, v72, v73
	v_cvt_pk_bf16_f32 v69, v74, v75
	v_cvt_pk_bf16_f32 v72, v64, v65
	v_cvt_pk_bf16_f32 v73, v82, v83
	v_and_b32_e32 v65, 0xffff0000, v66
	v_and_b32_e32 v75, 0xffff0000, v67
	v_and_b32_e32 v81, 0xffff0000, v70
	v_and_b32_e32 v83, 0xffff0000, v71
	v_lshlrev_b32_e32 v64, 16, v66
	v_lshlrev_b32_e32 v74, 16, v67
	v_and_b32_e32 v77, 0xffff0000, v68
	v_lshlrev_b32_e32 v80, 16, v70
	v_lshlrev_b32_e32 v82, 16, v71
	v_and_b32_e32 v85, 0xffff0000, v72
	v_mul_f32_e32 v65, v65, v65
	v_mul_f32_e32 v75, v75, v75
	v_mul_f32_e32 v81, v81, v81
	v_mul_f32_e32 v83, v83, v83
	v_lshlrev_b32_e32 v76, 16, v68
	v_and_b32_e32 v79, 0xffff0000, v69
	v_lshlrev_b32_e32 v84, 16, v72
	v_and_b32_e32 v87, 0xffff0000, v73
	v_mul_f32_e32 v77, v77, v77
	v_mul_f32_e32 v85, v85, v85
	v_fmac_f32_e32 v65, v64, v64
	v_fmac_f32_e32 v75, v74, v74
	v_fmac_f32_e32 v81, v80, v80
	v_fmac_f32_e32 v83, v82, v82
	v_lshlrev_b32_e32 v78, 16, v69
	v_lshlrev_b32_e32 v86, 16, v73
	v_mul_f32_e32 v79, v79, v79
	v_mul_f32_e32 v87, v87, v87
	v_fmac_f32_e32 v77, v76, v76
	v_fmac_f32_e32 v85, v84, v84
	v_add_f32_e32 v64, v65, v75
	v_add_f32_e32 v65, v81, v83
	v_fmac_f32_e32 v79, v78, v78
	v_fmac_f32_e32 v87, v86, v86
	v_add_f32_e32 v64, v77, v64
	v_add_f32_e32 v65, v85, v65
	v_add_f32_e32 v64, v79, v64
	v_add_f32_e32 v65, v87, v65
	v_add_f32_e32 v64, v64, v65
	v_mov_b32_e32 v65, v64
	v_mov_b32_e32 v159, v64
	s_nop 1
	v_permlane16_swap_b32_e32 v65, v159
	global_store_dwordx4 v[88:89], v[66:69], off
	global_store_dwordx4 v[88:89], v[70:73], off offset:256
	s_waitcnt lgkmcnt(0)
	v_add_f32_e32 v64, v159, v65
	v_mov_b32_e32 v65, v64
	v_mov_b32_e32 v112, v64
	s_nop 1
	v_permlane32_swap_b32_e32 v65, v112
	s_and_saveexec_b64 s[40:41], s[8:9]
	s_cbranch_execz .LBB0_1199
	s_waitcnt lgkmcnt(0)
	v_add_f32_e32 v64, v112, v65
	ds_write_b32 v154, v64
.LBB0_1199:
	s_or_b64 exec, exec, s[40:41]
	s_waitcnt lgkmcnt(0)
	v_lshlrev_b64 v[64:65], 11, v[142:143]
	v_lshl_add_u64 v[64:65], s[48:49], 0, v[64:65]
	v_lshl_add_u64 v[64:65], v[140:141], 1, v[64:65]
	v_add_co_u32_e32 v74, vcc, 0x40000, v64
	v_lshl_add_u64 v[76:77], v[64:65], 0, s[26:27]
	s_nop 0
	v_addc_co_u32_e32 v75, vcc, 0, v65, vcc
	global_load_dwordx4 v[66:69], v[74:75], off
	global_load_dwordx4 v[70:73], v[76:77], off offset:256
	s_waitcnt vmcnt(1)
	v_lshlrev_b32_e32 v78, 16, v66
	v_and_b32_e32 v79, 0xffff0000, v66
	v_lshlrev_b32_e32 v66, 16, v67
	v_and_b32_e32 v67, 0xffff0000, v67
	s_waitcnt vmcnt(0)
	v_lshlrev_b32_e32 v82, 16, v70
	v_and_b32_e32 v83, 0xffff0000, v70
	v_lshlrev_b32_e32 v70, 16, v71
	v_and_b32_e32 v71, 0xffff0000, v71
	v_lshlrev_b32_e32 v80, 16, v68
	v_and_b32_e32 v81, 0xffff0000, v68
	v_lshlrev_b32_e32 v68, 16, v69
	v_and_b32_e32 v69, 0xffff0000, v69
	v_lshlrev_b32_e32 v84, 16, v72
	v_and_b32_e32 v85, 0xffff0000, v72
	v_lshlrev_b32_e32 v72, 16, v73
	v_and_b32_e32 v73, 0xffff0000, v73
	v_pk_fma_f32 v[62:63], v[62:63], 0.5, v[66:67] op_sel_hi:[1,0,1]
	v_pk_fma_f32 v[60:61], v[60:61], 0.5, v[78:79] op_sel_hi:[1,0,1]
	v_pk_fma_f32 v[66:67], v[54:55], 0.5, v[70:71] op_sel_hi:[1,0,1]
	v_pk_fma_f32 v[54:55], v[52:53], 0.5, v[82:83] op_sel_hi:[1,0,1]
	v_pk_fma_f32 v[58:59], v[58:59], 0.5, v[68:69] op_sel_hi:[1,0,1]
	v_pk_fma_f32 v[56:57], v[56:57], 0.5, v[80:81] op_sel_hi:[1,0,1]
	v_pk_fma_f32 v[68:69], v[50:51], 0.5, v[72:73] op_sel_hi:[1,0,1]
	v_pk_fma_f32 v[48:49], v[48:49], 0.5, v[84:85] op_sel_hi:[1,0,1]
	v_cvt_pk_bf16_f32 v50, v60, v61
	v_cvt_pk_bf16_f32 v51, v62, v63
	v_cvt_pk_bf16_f32 v54, v54, v55
	v_cvt_pk_bf16_f32 v55, v66, v67
	v_cvt_pk_bf16_f32 v52, v56, v57
	v_cvt_pk_bf16_f32 v53, v58, v59
	v_cvt_pk_bf16_f32 v56, v48, v49
	v_cvt_pk_bf16_f32 v57, v68, v69
	v_and_b32_e32 v49, 0xffff0000, v50
	v_and_b32_e32 v59, 0xffff0000, v51
	v_and_b32_e32 v67, 0xffff0000, v54
	v_and_b32_e32 v69, 0xffff0000, v55
	v_lshlrev_b32_e32 v48, 16, v50
	v_lshlrev_b32_e32 v58, 16, v51
	v_and_b32_e32 v61, 0xffff0000, v52
	v_lshlrev_b32_e32 v66, 16, v54
	v_lshlrev_b32_e32 v68, 16, v55
	v_and_b32_e32 v71, 0xffff0000, v56
	v_mul_f32_e32 v49, v49, v49
	v_mul_f32_e32 v59, v59, v59
	v_mul_f32_e32 v67, v67, v67
	v_mul_f32_e32 v69, v69, v69
	v_lshlrev_b32_e32 v60, 16, v52
	v_and_b32_e32 v63, 0xffff0000, v53
	v_lshlrev_b32_e32 v70, 16, v56
	v_and_b32_e32 v73, 0xffff0000, v57
	v_mul_f32_e32 v61, v61, v61
	v_mul_f32_e32 v71, v71, v71
	v_fmac_f32_e32 v49, v48, v48
	v_fmac_f32_e32 v59, v58, v58
	v_fmac_f32_e32 v67, v66, v66
	v_fmac_f32_e32 v69, v68, v68
	v_lshlrev_b32_e32 v62, 16, v53
	v_lshlrev_b32_e32 v72, 16, v57
	v_mul_f32_e32 v63, v63, v63
	v_mul_f32_e32 v73, v73, v73
	v_fmac_f32_e32 v61, v60, v60
	v_fmac_f32_e32 v71, v70, v70
	v_add_f32_e32 v48, v49, v59
	v_add_f32_e32 v49, v67, v69
	v_fmac_f32_e32 v63, v62, v62
	v_fmac_f32_e32 v73, v72, v72
	v_add_f32_e32 v48, v61, v48
	v_add_f32_e32 v49, v71, v49
	v_add_f32_e32 v48, v63, v48
	v_add_f32_e32 v49, v73, v49
	v_add_f32_e32 v48, v48, v49
	v_mov_b32_e32 v49, v48
	v_mov_b32_e32 v159, v48
	s_nop 1
	v_permlane16_swap_b32_e32 v49, v159
	global_store_dwordx4 v[74:75], v[50:53], off
	global_store_dwordx4 v[76:77], v[54:57], off offset:256
	s_waitcnt lgkmcnt(0)
	v_add_f32_e32 v48, v159, v49
	v_mov_b32_e32 v49, v48
	v_mov_b32_e32 v112, v48
	s_nop 1
	v_permlane32_swap_b32_e32 v49, v112
	s_and_saveexec_b64 s[40:41], s[8:9]
	s_cbranch_execz .LBB0_1201
	s_waitcnt lgkmcnt(0)
	v_add_f32_e32 v48, v112, v49
	ds_write_b32 v155, v48
; #define PG8_LAS __attribute__((address_space(3)))
;     __device__ __forceinline__ void operator()(const f32x4 (&acc)[2][2][4][2], const Unit& u, int wr, int wc, int fr, int fq, PG8_LAS unsigned char* lds, int wid) const {
;     ...
;                 float s = 0.f;
; #pragma unroll
;                 for (int bj = 0; bj < 2; ++bj) {
;                     const size_t off = (size_t)(row0 + ai * HALF + m * 16) * 1024 + col0 + bj * HALF;
;                     f32x4 b0, b1;
;                     if (FIRST) { b0 = *(const f32x4*)(base32 + off); b1 = *(const f32x4*)(base32 + off + 4); }
;                     else { const u32x4 r = *(const u32x4*)(xn + off);
;                         b0 = (f32x4){__uint_as_float(r.x << 16), __uint_as_float(r.x & 0xffff0000u), __uint_as_float(r.y << 16), __uint_as_float(r.y & 0xffff0000u)};
;                         b1 = (f32x4){__uint_as_float(r.z << 16), __uint_as_float(r.z & 0xffff0000u), __uint_as_float(r.w << 16), __uint_as_float(r.w & 0xffff0000u)}; }
;                     const f32x4 v0 = b0 + alpha * acc[ai][bj][m][0], v1 = b1 + alpha * acc[ai][bj][m][1];
;                     if (LAST) { *(f32x4*)(out32 + off) = v0; *(f32x4*)(out32 + off + 4) = v1; }
;                     else {
;                         u32x4 w; w.x = pk_bf16(v0[0], v0[1]); w.y = pk_bf16(v0[2], v0[3]); w.z = pk_bf16(v1[0], v1[1]); w.w = pk_bf16(v1[2], v1[3]);
;                         *(u32x4*)(xn + off) = w;
;                         const float r0 = __uint_as_float(w.x << 16), r1 = __uint_as_float(w.x & 0xffff0000u), r2 = __uint_as_float(w.y << 16), r3 = __uint_as_float(w.y & 0xffff0000u);
;                         const float r4 = __uint_as_float(w.z << 16), r5 = __uint_as_float(w.z & 0xffff0000u), r6 = __uint_as_float(w.w << 16), r7 = __uint_as_float(w.w & 0xffff0000u);
;                         s += (r0 * r0 + r1 * r1) + (r2 * r2 + r3 * r3) + (r4 * r4 + r5 * r5) + (r6 * r6 + r7 * r7);
;                     }
;                 }
;                 if (!LAST) { s += __shfl_xor(s, 16); s += __shfl_xor(s, 32);
;                     if (fq == 0) *(PG8_LAS float*)(lds + PRE_SLOT + 4096 + ((wr * 64 + fr + ai * HALF + m * 16) * 4 + wc) * 4) = s; }
.LBB0_1201:
	s_or_b64 exec, exec, s[40:41]
	v_add_co_u32_e32 v56, vcc, 0x48000, v64
	v_lshl_add_u64 v[58:59], v[64:65], 0, s[28:29]
	s_nop 0
	v_addc_co_u32_e32 v57, vcc, 0, v65, vcc
	s_waitcnt lgkmcnt(0)
	global_load_dwordx4 v[48:51], v[56:57], off
	global_load_dwordx4 v[52:55], v[58:59], off offset:256
	s_waitcnt vmcnt(1)
	v_lshlrev_b32_e32 v60, 16, v48
	v_and_b32_e32 v61, 0xffff0000, v48
	v_lshlrev_b32_e32 v48, 16, v49
	v_and_b32_e32 v49, 0xffff0000, v49
	s_waitcnt vmcnt(0)
	v_lshlrev_b32_e32 v64, 16, v52
	v_and_b32_e32 v65, 0xffff0000, v52
	v_lshlrev_b32_e32 v52, 16, v53
	v_and_b32_e32 v53, 0xffff0000, v53
	v_lshlrev_b32_e32 v62, 16, v50
	v_and_b32_e32 v63, 0xffff0000, v50
	v_lshlrev_b32_e32 v50, 16, v51
	v_and_b32_e32 v51, 0xffff0000, v51
	v_lshlrev_b32_e32 v66, 16, v54
	v_and_b32_e32 v67, 0xffff0000, v54
	v_lshlrev_b32_e32 v54, 16, v55
	v_and_b32_e32 v55, 0xffff0000, v55
	v_pk_fma_f32 v[46:47], v[46:47], 0.5, v[48:49] op_sel_hi:[1,0,1]
	v_pk_fma_f32 v[44:45], v[44:45], 0.5, v[60:61] op_sel_hi:[1,0,1]
	v_pk_fma_f32 v[48:49], v[38:39], 0.5, v[52:53] op_sel_hi:[1,0,1]
	v_pk_fma_f32 v[38:39], v[36:37], 0.5, v[64:65] op_sel_hi:[1,0,1]
	v_pk_fma_f32 v[42:43], v[42:43], 0.5, v[50:51] op_sel_hi:[1,0,1]
	v_pk_fma_f32 v[40:41], v[40:41], 0.5, v[62:63] op_sel_hi:[1,0,1]
	v_pk_fma_f32 v[50:51], v[34:35], 0.5, v[54:55] op_sel_hi:[1,0,1]
	v_pk_fma_f32 v[32:33], v[32:33], 0.5, v[66:67] op_sel_hi:[1,0,1]
	v_cvt_pk_bf16_f32 v34, v44, v45
	v_cvt_pk_bf16_f32 v35, v46, v47
	v_cvt_pk_bf16_f32 v38, v38, v39
	v_cvt_pk_bf16_f32 v39, v48, v49
	v_cvt_pk_bf16_f32 v36, v40, v41
	v_cvt_pk_bf16_f32 v37, v42, v43
	v_cvt_pk_bf16_f32 v40, v32, v33
	v_cvt_pk_bf16_f32 v41, v50, v51
	v_and_b32_e32 v33, 0xffff0000, v34
	v_and_b32_e32 v43, 0xffff0000, v35
	v_and_b32_e32 v49, 0xffff0000, v38
	v_and_b32_e32 v51, 0xffff0000, v39
	v_lshlrev_b32_e32 v32, 16, v34
	v_lshlrev_b32_e32 v42, 16, v35
	v_and_b32_e32 v45, 0xffff0000, v36
	v_lshlrev_b32_e32 v48, 16, v38
	v_lshlrev_b32_e32 v50, 16, v39
	v_and_b32_e32 v53, 0xffff0000, v40
	v_mul_f32_e32 v33, v33, v33
	v_mul_f32_e32 v43, v43, v43
	v_mul_f32_e32 v49, v49, v49
	v_mul_f32_e32 v51, v51, v51
	v_lshlrev_b32_e32 v44, 16, v36
	v_and_b32_e32 v47, 0xffff0000, v37
	v_lshlrev_b32_e32 v52, 16, v40
	v_and_b32_e32 v55, 0xffff0000, v41
	v_mul_f32_e32 v45, v45, v45
	v_mul_f32_e32 v53, v53, v53
	v_fmac_f32_e32 v33, v32, v32
	v_fmac_f32_e32 v43, v42, v42
	v_fmac_f32_e32 v49, v48, v48
	v_fmac_f32_e32 v51, v50, v50
	v_lshlrev_b32_e32 v46, 16, v37
	v_lshlrev_b32_e32 v54, 16, v41
	v_mul_f32_e32 v47, v47, v47
	v_mul_f32_e32 v55, v55, v55
	v_fmac_f32_e32 v45, v44, v44
	v_fmac_f32_e32 v53, v52, v52
	v_add_f32_e32 v32, v33, v43
	v_add_f32_e32 v33, v49, v51
	v_fmac_f32_e32 v47, v46, v46
	v_fmac_f32_e32 v55, v54, v54
	v_add_f32_e32 v32, v45, v32
	v_add_f32_e32 v33, v53, v33
	v_add_f32_e32 v32, v47, v32
	v_add_f32_e32 v33, v55, v33
	v_add_f32_e32 v32, v32, v33
	v_mov_b32_e32 v33, v32
	v_mov_b32_e32 v159, v32
	s_nop 1
	v_permlane16_swap_b32_e32 v33, v159
	global_store_dwordx4 v[56:57], v[34:37], off
	global_store_dwordx4 v[58:59], v[38:41], off offset:256
	s_waitcnt lgkmcnt(0)
	v_add_f32_e32 v32, v159, v33
	v_mov_b32_e32 v33, v32
	v_mov_b32_e32 v112, v32
	s_nop 1
	v_permlane32_swap_b32_e32 v33, v112
	s_and_saveexec_b64 s[40:41], s[8:9]
	s_cbranch_execz .LBB0_1203
	s_waitcnt lgkmcnt(0)
	v_add_f32_e32 v32, v112, v33
	ds_write_b32 v156, v32
; #define PG8_LAS __attribute__((address_space(3)))
;     __device__ __forceinline__ void operator()(const f32x4 (&acc)[2][2][4][2], const Unit& u, int wr, int wc, int fr, int fq, PG8_LAS unsigned char* lds, int wid) const {
;     ...
;                 float s = 0.f;
; #pragma unroll
;                 for (int bj = 0; bj < 2; ++bj) {
;                     const size_t off = (size_t)(row0 + ai * HALF + m * 16) * 1024 + col0 + bj * HALF;
;                     f32x4 b0, b1;
;                     if (FIRST) { b0 = *(const f32x4*)(base32 + off); b1 = *(const f32x4*)(base32 + off + 4); }
;                     else { const u32x4 r = *(const u32x4*)(xn + off);
;                         b0 = (f32x4){__uint_as_float(r.x << 16), __uint_as_float(r.x & 0xffff0000u), __uint_as_float(r.y << 16), __uint_as_float(r.y & 0xffff0000u)};
;                         b1 = (f32x4){__uint_as_float(r.z << 16), __uint_as_float(r.z & 0xffff0000u), __uint_as_float(r.w << 16), __uint_as_float(r.w & 0xffff0000u)}; }
;                     const f32x4 v0 = b0 + alpha * acc[ai][bj][m][0], v1 = b1 + alpha * acc[ai][bj][m][1];
;                     if (LAST) { *(f32x4*)(out32 + off) = v0; *(f32x4*)(out32 + off + 4) = v1; }
;                     else {
;                         u32x4 w; w.x = pk_bf16(v0[0], v0[1]); w.y = pk_bf16(v0[2], v0[3]); w.z = pk_bf16(v1[0], v1[1]); w.w = pk_bf16(v1[2], v1[3]);
;                         *(u32x4*)(xn + off) = w;
;                         const float r0 = __uint_as_float(w.x << 16), r1 = __uint_as_float(w.x & 0xffff0000u), r2 = __uint_as_float(w.y << 16), r3 = __uint_as_float(w.y & 0xffff0000u);
;                         const float r4 = __uint_as_float(w.z << 16), r5 = __uint_as_float(w.z & 0xffff0000u), r6 = __uint_as_float(w.w << 16), r7 = __uint_as_float(w.w & 0xffff0000u);
;                         s += (r0 * r0 + r1 * r1) + (r2 * r2 + r3 * r3) + (r4 * r4 + r5 * r5) + (r6 * r6 + r7 * r7);
;                     }
;                 }
;                 if (!LAST) { s += __shfl_xor(s, 16); s += __shfl_xor(s, 32);
;                     if (fq == 0) *(PG8_LAS float*)(lds + PRE_SLOT + 4096 + ((wr * 64 + fr + ai * HALF + m * 16) * 4 + wc) * 4) = s; }
.LBB0_1203:
	s_or_b64 exec, exec, s[40:41]
	s_waitcnt lgkmcnt(0)
	v_lshlrev_b64 v[32:33], 11, v[142:143]
	v_lshl_add_u64 v[32:33], s[48:49], 0, v[32:33]
	v_lshl_add_u64 v[32:33], v[140:141], 1, v[32:33]
	v_add_co_u32_e32 v42, vcc, 0x50000, v32
	v_lshl_add_u64 v[44:45], v[32:33], 0, s[30:31]
	s_nop 0
	v_addc_co_u32_e32 v43, vcc, 0, v33, vcc
	global_load_dwordx4 v[34:37], v[42:43], off
	global_load_dwordx4 v[38:41], v[44:45], off offset:256
	s_waitcnt vmcnt(1)
	v_lshlrev_b32_e32 v46, 16, v34
	v_and_b32_e32 v47, 0xffff0000, v34
	v_lshlrev_b32_e32 v34, 16, v35
	v_and_b32_e32 v35, 0xffff0000, v35
	s_waitcnt vmcnt(0)
	v_lshlrev_b32_e32 v50, 16, v38
	v_and_b32_e32 v51, 0xffff0000, v38
	v_lshlrev_b32_e32 v38, 16, v39
	v_and_b32_e32 v39, 0xffff0000, v39
	v_lshlrev_b32_e32 v48, 16, v36
	v_and_b32_e32 v49, 0xffff0000, v36
	v_lshlrev_b32_e32 v36, 16, v37
	v_and_b32_e32 v37, 0xffff0000, v37
	v_lshlrev_b32_e32 v52, 16, v40
	v_and_b32_e32 v53, 0xffff0000, v40
	v_lshlrev_b32_e32 v40, 16, v41
	v_and_b32_e32 v41, 0xffff0000, v41
	v_pk_fma_f32 v[30:31], v[30:31], 0.5, v[34:35] op_sel_hi:[1,0,1]
	v_pk_fma_f32 v[28:29], v[28:29], 0.5, v[46:47] op_sel_hi:[1,0,1]
	v_pk_fma_f32 v[34:35], v[22:23], 0.5, v[38:39] op_sel_hi:[1,0,1]
	v_pk_fma_f32 v[22:23], v[20:21], 0.5, v[50:51] op_sel_hi:[1,0,1]
	v_pk_fma_f32 v[26:27], v[26:27], 0.5, v[36:37] op_sel_hi:[1,0,1]
	v_pk_fma_f32 v[24:25], v[24:25], 0.5, v[48:49] op_sel_hi:[1,0,1]
	v_pk_fma_f32 v[36:37], v[18:19], 0.5, v[40:41] op_sel_hi:[1,0,1]
	v_pk_fma_f32 v[16:17], v[16:17], 0.5, v[52:53] op_sel_hi:[1,0,1]
	v_cvt_pk_bf16_f32 v18, v28, v29
	v_cvt_pk_bf16_f32 v19, v30, v31
	v_cvt_pk_bf16_f32 v22, v22, v23
	v_cvt_pk_bf16_f32 v23, v34, v35
	v_cvt_pk_bf16_f32 v20, v24, v25
	v_cvt_pk_bf16_f32 v21, v26, v27
	v_cvt_pk_bf16_f32 v24, v16, v17
	v_cvt_pk_bf16_f32 v25, v36, v37
	v_and_b32_e32 v17, 0xffff0000, v18
	v_and_b32_e32 v27, 0xffff0000, v19
	v_and_b32_e32 v35, 0xffff0000, v22
	v_and_b32_e32 v37, 0xffff0000, v23
	v_lshlrev_b32_e32 v16, 16, v18
	v_lshlrev_b32_e32 v26, 16, v19
	v_and_b32_e32 v29, 0xffff0000, v20
	v_lshlrev_b32_e32 v34, 16, v22
	v_lshlrev_b32_e32 v36, 16, v23
	v_and_b32_e32 v39, 0xffff0000, v24
	v_mul_f32_e32 v17, v17, v17
	v_mul_f32_e32 v27, v27, v27
	v_mul_f32_e32 v35, v35, v35
	v_mul_f32_e32 v37, v37, v37
	v_lshlrev_b32_e32 v28, 16, v20
	v_and_b32_e32 v31, 0xffff0000, v21
	v_lshlrev_b32_e32 v38, 16, v24
	v_and_b32_e32 v41, 0xffff0000, v25
	v_mul_f32_e32 v29, v29, v29
	v_mul_f32_e32 v39, v39, v39
	v_fmac_f32_e32 v17, v16, v16
	v_fmac_f32_e32 v27, v26, v26
	v_fmac_f32_e32 v35, v34, v34
	v_fmac_f32_e32 v37, v36, v36
	v_lshlrev_b32_e32 v30, 16, v21
	v_lshlrev_b32_e32 v40, 16, v25
	v_mul_f32_e32 v31, v31, v31
	v_mul_f32_e32 v41, v41, v41
	v_fmac_f32_e32 v29, v28, v28
	v_fmac_f32_e32 v39, v38, v38
	v_add_f32_e32 v16, v17, v27
	v_add_f32_e32 v17, v35, v37
	v_fmac_f32_e32 v31, v30, v30
	v_fmac_f32_e32 v41, v40, v40
	v_add_f32_e32 v16, v29, v16
	v_add_f32_e32 v17, v39, v17
	v_add_f32_e32 v16, v31, v16
	v_add_f32_e32 v17, v41, v17
	v_add_f32_e32 v16, v16, v17
	v_mov_b32_e32 v17, v16
	v_mov_b32_e32 v159, v16
	s_nop 1
	v_permlane16_swap_b32_e32 v17, v159
	global_store_dwordx4 v[42:43], v[18:21], off
	global_store_dwordx4 v[44:45], v[22:25], off offset:256
	s_waitcnt lgkmcnt(0)
	v_add_f32_e32 v16, v159, v17
	v_mov_b32_e32 v17, v16
	v_mov_b32_e32 v112, v16
	s_nop 1
	v_permlane32_swap_b32_e32 v17, v112
	s_and_saveexec_b64 s[40:41], s[8:9]
	s_cbranch_execz .LBB0_1205
	s_waitcnt lgkmcnt(0)
	v_add_f32_e32 v16, v112, v17
	ds_write_b32 v157, v16
.LBB0_1205:
	s_or_b64 exec, exec, s[40:41]
	v_add_co_u32_e32 v24, vcc, 0x58000, v32
	v_lshl_add_u64 v[26:27], v[32:33], 0, s[34:35]
	s_nop 0
	v_addc_co_u32_e32 v25, vcc, 0, v33, vcc
	s_waitcnt lgkmcnt(0)
	global_load_dwordx4 v[16:19], v[24:25], off
	global_load_dwordx4 v[20:23], v[26:27], off offset:256
	s_waitcnt vmcnt(1)
	v_lshlrev_b32_e32 v28, 16, v16
	v_and_b32_e32 v29, 0xffff0000, v16
	v_lshlrev_b32_e32 v16, 16, v17
	v_and_b32_e32 v17, 0xffff0000, v17
	s_waitcnt vmcnt(0)
	v_lshlrev_b32_e32 v32, 16, v20
	v_and_b32_e32 v33, 0xffff0000, v20
	v_lshlrev_b32_e32 v20, 16, v21
	v_and_b32_e32 v21, 0xffff0000, v21
	v_lshlrev_b32_e32 v30, 16, v18
	v_and_b32_e32 v31, 0xffff0000, v18
	v_lshlrev_b32_e32 v18, 16, v19
	v_and_b32_e32 v19, 0xffff0000, v19
	v_lshlrev_b32_e32 v34, 16, v22
	v_and_b32_e32 v35, 0xffff0000, v22
	v_lshlrev_b32_e32 v22, 16, v23
	v_and_b32_e32 v23, 0xffff0000, v23
	v_pk_fma_f32 v[14:15], v[14:15], 0.5, v[16:17] op_sel_hi:[1,0,1]
	v_pk_fma_f32 v[12:13], v[12:13], 0.5, v[28:29] op_sel_hi:[1,0,1]
	v_pk_fma_f32 v[16:17], v[6:7], 0.5, v[20:21] op_sel_hi:[1,0,1]
	v_pk_fma_f32 v[6:7], v[4:5], 0.5, v[32:33] op_sel_hi:[1,0,1]
	v_pk_fma_f32 v[10:11], v[10:11], 0.5, v[18:19] op_sel_hi:[1,0,1]
	v_pk_fma_f32 v[8:9], v[8:9], 0.5, v[30:31] op_sel_hi:[1,0,1]
	v_pk_fma_f32 v[18:19], v[2:3], 0.5, v[22:23] op_sel_hi:[1,0,1]
	v_pk_fma_f32 v[0:1], v[0:1], 0.5, v[34:35] op_sel_hi:[1,0,1]
	v_cvt_pk_bf16_f32 v2, v12, v13
	v_cvt_pk_bf16_f32 v3, v14, v15
	v_cvt_pk_bf16_f32 v6, v6, v7
	v_cvt_pk_bf16_f32 v7, v16, v17
	v_cvt_pk_bf16_f32 v4, v8, v9
	v_cvt_pk_bf16_f32 v5, v10, v11
	v_cvt_pk_bf16_f32 v8, v0, v1
	v_cvt_pk_bf16_f32 v9, v18, v19
	v_and_b32_e32 v1, 0xffff0000, v2
	v_and_b32_e32 v11, 0xffff0000, v3
	v_and_b32_e32 v17, 0xffff0000, v6
	v_and_b32_e32 v19, 0xffff0000, v7
	v_lshlrev_b32_e32 v0, 16, v2
	v_lshlrev_b32_e32 v10, 16, v3
	v_and_b32_e32 v13, 0xffff0000, v4
	v_lshlrev_b32_e32 v16, 16, v6
	v_lshlrev_b32_e32 v18, 16, v7
	v_and_b32_e32 v21, 0xffff0000, v8
	v_mul_f32_e32 v1, v1, v1
	v_mul_f32_e32 v11, v11, v11
	v_mul_f32_e32 v17, v17, v17
	v_mul_f32_e32 v19, v19, v19
	v_lshlrev_b32_e32 v12, 16, v4
	v_and_b32_e32 v15, 0xffff0000, v5
	v_lshlrev_b32_e32 v20, 16, v8
	v_and_b32_e32 v23, 0xffff0000, v9
	v_mul_f32_e32 v13, v13, v13
	v_mul_f32_e32 v21, v21, v21
	v_fmac_f32_e32 v1, v0, v0
	v_fmac_f32_e32 v11, v10, v10
	v_fmac_f32_e32 v17, v16, v16
	v_fmac_f32_e32 v19, v18, v18
	v_lshlrev_b32_e32 v14, 16, v5
	v_lshlrev_b32_e32 v22, 16, v9
	v_mul_f32_e32 v15, v15, v15
	v_mul_f32_e32 v23, v23, v23
	v_fmac_f32_e32 v13, v12, v12
	v_fmac_f32_e32 v21, v20, v20
	v_add_f32_e32 v0, v1, v11
	v_add_f32_e32 v1, v17, v19
	v_fmac_f32_e32 v15, v14, v14
	v_fmac_f32_e32 v23, v22, v22
	v_add_f32_e32 v0, v13, v0
	v_add_f32_e32 v1, v21, v1
	v_add_f32_e32 v0, v15, v0
	v_add_f32_e32 v1, v23, v1
	v_add_f32_e32 v0, v0, v1
	v_mov_b32_e32 v1, v0
	v_mov_b32_e32 v159, v0
	s_nop 1
	v_permlane16_swap_b32_e32 v1, v159
	global_store_dwordx4 v[24:25], v[2:5], off
	global_store_dwordx4 v[26:27], v[6:9], off offset:256
	s_waitcnt lgkmcnt(0)
	v_add_f32_e32 v0, v159, v1
	v_mov_b32_e32 v1, v0
	v_mov_b32_e32 v112, v0
	s_nop 1
	v_permlane32_swap_b32_e32 v1, v112
	s_and_saveexec_b64 s[40:41], s[8:9]
	s_cbranch_execz .LBB0_1207
	s_waitcnt lgkmcnt(0)
	v_add_f32_e32 v0, v112, v1
	ds_write_b32 v158, v0

;     __device__ __forceinline__ void operator()(const f32x4 (&acc)[2][2][4][2], const Unit& u, int wr, int wc, int fr, int fq, PG8_LAS unsigned char* lds, int wid) const {
;         const int row0 = u.pm * BM + wr * 64 + fr, col0 = u.pn * BM + wc * 32 + 8 * fq;
;         constexpr float alpha = HALF_ALPHA ? 0.5f : 1.0f;
; #pragma unroll
;         for (int ai = 0; ai < 2; ++ai)
; #pragma unroll
;             for (int m = 0; m < 4; ++m) {
;                 float s = 0.f;
; #pragma unroll
;                 for (int bj = 0; bj < 2; ++bj) {
;                     const size_t off = (size_t)(row0 + ai * HALF + m * 16) * 1024 + col0 + bj * HALF;
;                     f32x4 b0, b1;
;                     if (FIRST) { b0 = *(const f32x4*)(base32 + off); b1 = *(const f32x4*)(base32 + off + 4); }
;                     else { const u32x4 r = *(const u32x4*)(xn + off);
;                         b0 = (f32x4){__uint_as_float(r.x << 16), __uint_as_float(r.x & 0xffff0000u), __uint_as_float(r.y << 16), __uint_as_float(r.y & 0xffff0000u)};
;                         b1 = (f32x4){__uint_as_float(r.z << 16), __uint_as_float(r.z & 0xffff0000u), __uint_as_float(r.w << 16), __uint_as_float(r.w & 0xffff0000u)}; }
;                     const f32x4 v0 = b0 + alpha * acc[ai][bj][m][0], v1 = b1 + alpha * acc[ai][bj][m][1];
;                     if (LAST) { *(f32x4*)(out32 + off) = v0; *(f32x4*)(out32 + off + 4) = v1; }
;                     else {
;                         u32x4 w; w.x = pk_bf16(v0[0], v0[1]); w.y = pk_bf16(v0[2], v0[3]); w.z = pk_bf16(v1[0], v1[1]); w.w = pk_bf16(v1[2], v1[3]);
;                         *(u32x4*)(xn + off) = w;
;                         const float r0 = __uint_as_float(w.x << 16), r1 = __uint_as_float(w.x & 0xffff0000u), r2 = __uint_as_float(w.y << 16), r3 = __uint_as_float(w.y & 0xffff0000u);
;                         const float r4 = __uint_as_float(w.z << 16), r5 = __uint_as_float(w.z & 0xffff0000u), r6 = __uint_as_float(w.w << 16), r7 = __uint_as_float(w.w & 0xffff0000u);
;                         s += (r0 * r0 + r1 * r1) + (r2 * r2 + r3 * r3) + (r4 * r4 + r5 * r5) + (r6 * r6 + r7 * r7);
;                     }
;                 }
;                 if (!LAST) { s += __shfl_xor(s, 16); s += __shfl_xor(s, 32);
;                     if (fq == 0) *(PG8_LAS float*)(lds + PRE_SLOT + 4096 + ((wr * 64 + fr + ai * HALF + m * 16) * 4 + wc) * 4) = s; }
.LBB0_1669:
	s_lshl_b32 s30, s76, 8
	v_add_u32_e32 v142, s30, v144
	v_ashrrev_i32_e32 v143, 31, v142
	v_lshl_or_b32 v140, s75, 8, v146
	v_lshlrev_b64 v[160:161], 11, v[142:143]
	v_ashrrev_i32_e32 v141, 31, v140
	v_lshl_add_u64 v[160:161], s[48:49], 0, v[160:161]
	v_lshl_add_u64 v[168:169], v[140:141], 1, v[160:161]
	global_load_dwordx4 v[160:163], v[168:169], off
	global_load_dwordx4 v[164:167], v[168:169], off offset:256
	v_and_b32_e32 v170, 64, v150
	v_add_u32_e32 v178, 64, v170
	v_xor_b32_e32 v159, 16, v150
	v_cmp_lt_i32_e32 vcc, v159, v178
	s_waitcnt vmcnt(0)
	v_lshlrev_b32_e32 v170, 16, v160
	v_and_b32_e32 v171, 0xffff0000, v160
	v_lshlrev_b32_e32 v160, 16, v161
	v_and_b32_e32 v161, 0xffff0000, v161
	v_lshlrev_b32_e32 v172, 16, v162
	v_and_b32_e32 v173, 0xffff0000, v162
	v_lshlrev_b32_e32 v162, 16, v163
	v_and_b32_e32 v163, 0xffff0000, v163
	v_lshlrev_b32_e32 v174, 16, v164
	v_and_b32_e32 v175, 0xffff0000, v164
	v_lshlrev_b32_e32 v164, 16, v165
	v_and_b32_e32 v165, 0xffff0000, v165
	v_lshlrev_b32_e32 v176, 16, v166
	v_and_b32_e32 v177, 0xffff0000, v166
	v_lshlrev_b32_e32 v166, 16, v167
	v_and_b32_e32 v167, 0xffff0000, v167
	v_pk_fma_f32 v[126:127], v[126:127], 0.5, v[160:161] op_sel_hi:[1,0,1]
	v_pk_fma_f32 v[124:125], v[124:125], 0.5, v[170:171] op_sel_hi:[1,0,1]
	v_pk_fma_f32 v[122:123], v[122:123], 0.5, v[162:163] op_sel_hi:[1,0,1]
	v_pk_fma_f32 v[120:121], v[120:121], 0.5, v[172:173] op_sel_hi:[1,0,1]
	v_pk_fma_f32 v[160:161], v[118:119], 0.5, v[164:165] op_sel_hi:[1,0,1]
	v_pk_fma_f32 v[162:163], v[116:117], 0.5, v[174:175] op_sel_hi:[1,0,1]
	v_pk_fma_f32 v[114:115], v[114:115], 0.5, v[166:167] op_sel_hi:[1,0,1]
	v_pk_fma_f32 v[112:113], v[112:113], 0.5, v[176:177] op_sel_hi:[1,0,1]
	v_cvt_pk_bf16_f32 v116, v124, v125
	v_cvt_pk_bf16_f32 v117, v126, v127
	v_cvt_pk_bf16_f32 v118, v120, v121
	v_cvt_pk_bf16_f32 v120, v162, v163
	v_cvt_pk_bf16_f32 v121, v160, v161
	v_cvt_pk_bf16_f32 v119, v122, v123
	v_cvt_pk_bf16_f32 v122, v112, v113
	v_cvt_pk_bf16_f32 v123, v114, v115
	v_and_b32_e32 v113, 0xffff0000, v116
	v_and_b32_e32 v115, 0xffff0000, v117
	v_and_b32_e32 v161, 0xffff0000, v120
	v_and_b32_e32 v163, 0xffff0000, v121
	v_lshlrev_b32_e32 v112, 16, v116
	v_lshlrev_b32_e32 v114, 16, v117
	v_and_b32_e32 v125, 0xffff0000, v118
	v_lshlrev_b32_e32 v160, 16, v120
	v_lshlrev_b32_e32 v162, 16, v121
	v_and_b32_e32 v165, 0xffff0000, v122
	v_mul_f32_e32 v113, v113, v113
	v_mul_f32_e32 v115, v115, v115
	v_mul_f32_e32 v161, v161, v161
	v_mul_f32_e32 v163, v163, v163
	v_lshlrev_b32_e32 v124, 16, v118
	v_and_b32_e32 v127, 0xffff0000, v119
	v_lshlrev_b32_e32 v164, 16, v122
	v_and_b32_e32 v167, 0xffff0000, v123
	v_mul_f32_e32 v125, v125, v125
	v_mul_f32_e32 v165, v165, v165
	v_fmac_f32_e32 v113, v112, v112
	v_fmac_f32_e32 v115, v114, v114
	v_fmac_f32_e32 v161, v160, v160
	v_fmac_f32_e32 v163, v162, v162
	v_lshlrev_b32_e32 v126, 16, v119
	v_lshlrev_b32_e32 v166, 16, v123
	v_mul_f32_e32 v127, v127, v127
	v_mul_f32_e32 v167, v167, v167
	v_fmac_f32_e32 v125, v124, v124
	v_fmac_f32_e32 v165, v164, v164
	v_add_f32_e32 v112, v113, v115
	v_add_f32_e32 v113, v161, v163
	v_fmac_f32_e32 v127, v126, v126
	v_fmac_f32_e32 v167, v166, v166
	v_add_f32_e32 v112, v125, v112
	v_add_f32_e32 v113, v165, v113
	v_cndmask_b32_e32 v159, v150, v159, vcc
	v_add_f32_e32 v112, v127, v112
	v_add_f32_e32 v113, v167, v113
	v_lshlrev_b32_e32 v159, 2, v159
	v_add_f32_e32 v113, v112, v113
	v_mov_b32_e32 v114, v113
	v_mov_b32_e32 v159, v113
	s_nop 1
	v_permlane16_swap_b32_e32 v114, v159
	v_xor_b32_e32 v112, 32, v150
	v_cmp_lt_i32_e32 vcc, v112, v178
	global_store_dwordx4 v[168:169], v[116:119], off
	global_store_dwordx4 v[168:169], v[120:123], off offset:256
	v_cndmask_b32_e32 v112, v150, v112, vcc
	v_lshlrev_b32_e32 v112, 2, v112
	s_waitcnt lgkmcnt(0)
	v_add_f32_e32 v113, v159, v114
	v_mov_b32_e32 v114, v113
	v_mov_b32_e32 v112, v113
	s_nop 1
	v_permlane32_swap_b32_e32 v114, v112
	s_and_saveexec_b64 s[34:35], s[8:9]
	s_cbranch_execz .LBB0_1671
	s_waitcnt lgkmcnt(0)
	v_add_f32_e32 v113, v112, v114
	ds_write_b32 v151, v113
.LBB0_1671:
	s_or_b64 exec, exec, s[34:35]
	s_waitcnt lgkmcnt(0)
	v_or_b32_e32 v114, 16, v142
	v_ashrrev_i32_e32 v115, 31, v114
	v_lshlrev_b64 v[114:115], 11, v[114:115]
	v_lshl_add_u64 v[114:115], s[48:49], 0, v[114:115]
	v_lshl_add_u64 v[122:123], v[140:141], 1, v[114:115]
	global_load_dwordx4 v[114:117], v[122:123], off
	global_load_dwordx4 v[118:121], v[122:123], off offset:256
	s_waitcnt vmcnt(1)
	v_lshlrev_b32_e32 v124, 16, v114
	v_and_b32_e32 v125, 0xffff0000, v114
	v_lshlrev_b32_e32 v114, 16, v115
	v_and_b32_e32 v115, 0xffff0000, v115
	s_waitcnt vmcnt(0)
; #define PG8_LAS __attribute__((address_space(3)))
;     __device__ __forceinline__ void operator()(const f32x4 (&acc)[2][2][4][2], const Unit& u, int wr, int wc, int fr, int fq, PG8_LAS unsigned char* lds, int wid) const {
;     ...
;                 float s = 0.f;
; #pragma unroll
;                 for (int bj = 0; bj < 2; ++bj) {
;                     const size_t off = (size_t)(row0 + ai * HALF + m * 16) * 1024 + col0 + bj * HALF;
;                     f32x4 b0, b1;
;                     if (FIRST) { b0 = *(const f32x4*)(base32 + off); b1 = *(const f32x4*)(base32 + off + 4); }
;                     else { const u32x4 r = *(const u32x4*)(xn + off);
;                         b0 = (f32x4){__uint_as_float(r.x << 16), __uint_as_float(r.x & 0xffff0000u), __uint_as_float(r.y << 16), __uint_as_float(r.y & 0xffff0000u)};
;                         b1 = (f32x4){__uint_as_float(r.z << 16), __uint_as_float(r.z & 0xffff0000u), __uint_as_float(r.w << 16), __uint_as_float(r.w & 0xffff0000u)}; }
;                     const f32x4 v0 = b0 + alpha * acc[ai][bj][m][0], v1 = b1 + alpha * acc[ai][bj][m][1];
;                     if (LAST) { *(f32x4*)(out32 + off) = v0; *(f32x4*)(out32 + off + 4) = v1; }
;                     else {
;                         u32x4 w; w.x = pk_bf16(v0[0], v0[1]); w.y = pk_bf16(v0[2], v0[3]); w.z = pk_bf16(v1[0], v1[1]); w.w = pk_bf16(v1[2], v1[3]);
;                         *(u32x4*)(xn + off) = w;
;                         const float r0 = __uint_as_float(w.x << 16), r1 = __uint_as_float(w.x & 0xffff0000u), r2 = __uint_as_float(w.y << 16), r3 = __uint_as_float(w.y & 0xffff0000u);
;                         const float r4 = __uint_as_float(w.z << 16), r5 = __uint_as_float(w.z & 0xffff0000u), r6 = __uint_as_float(w.w << 16), r7 = __uint_as_float(w.w & 0xffff0000u);
;                         s += (r0 * r0 + r1 * r1) + (r2 * r2 + r3 * r3) + (r4 * r4 + r5 * r5) + (r6 * r6 + r7 * r7);
;                     }
;                 }
;                 if (!LAST) { s += __shfl_xor(s, 16); s += __shfl_xor(s, 32);
;                     if (fq == 0) *(PG8_LAS float*)(lds + PRE_SLOT + 4096 + ((wr * 64 + fr + ai * HALF + m * 16) * 4 + wc) * 4) = s; }
	v_lshlrev_b32_e32 v160, 16, v118
	v_and_b32_e32 v161, 0xffff0000, v118
	v_lshlrev_b32_e32 v118, 16, v119
	v_and_b32_e32 v119, 0xffff0000, v119
	v_lshlrev_b32_e32 v126, 16, v116
	v_and_b32_e32 v127, 0xffff0000, v116
	v_lshlrev_b32_e32 v116, 16, v117
	v_and_b32_e32 v117, 0xffff0000, v117
	v_lshlrev_b32_e32 v162, 16, v120
	v_and_b32_e32 v163, 0xffff0000, v120
	v_lshlrev_b32_e32 v120, 16, v121
	v_and_b32_e32 v121, 0xffff0000, v121
	v_pk_fma_f32 v[110:111], v[110:111], 0.5, v[114:115] op_sel_hi:[1,0,1]
	v_pk_fma_f32 v[108:109], v[108:109], 0.5, v[124:125] op_sel_hi:[1,0,1]
	v_pk_fma_f32 v[114:115], v[102:103], 0.5, v[118:119] op_sel_hi:[1,0,1]
	v_pk_fma_f32 v[102:103], v[100:101], 0.5, v[160:161] op_sel_hi:[1,0,1]
	v_pk_fma_f32 v[106:107], v[106:107], 0.5, v[116:117] op_sel_hi:[1,0,1]
	v_pk_fma_f32 v[104:105], v[104:105], 0.5, v[126:127] op_sel_hi:[1,0,1]
	v_pk_fma_f32 v[116:117], v[98:99], 0.5, v[120:121] op_sel_hi:[1,0,1]
	v_pk_fma_f32 v[96:97], v[96:97], 0.5, v[162:163] op_sel_hi:[1,0,1]
	v_cvt_pk_bf16_f32 v98, v108, v109
	v_cvt_pk_bf16_f32 v99, v110, v111
	v_cvt_pk_bf16_f32 v102, v102, v103
	v_cvt_pk_bf16_f32 v103, v114, v115
	v_cvt_pk_bf16_f32 v100, v104, v105
	v_cvt_pk_bf16_f32 v101, v106, v107
	v_cvt_pk_bf16_f32 v104, v96, v97
	v_cvt_pk_bf16_f32 v105, v116, v117
	v_and_b32_e32 v97, 0xffff0000, v98
	v_and_b32_e32 v107, 0xffff0000, v99
	v_and_b32_e32 v114, 0xffff0000, v102
	v_and_b32_e32 v116, 0xffff0000, v103
	v_lshlrev_b32_e32 v96, 16, v98
	v_lshlrev_b32_e32 v106, 16, v99
	v_and_b32_e32 v109, 0xffff0000, v100
	v_lshlrev_b32_e32 v113, 16, v102
	v_lshlrev_b32_e32 v115, 16, v103
	v_and_b32_e32 v118, 0xffff0000, v104
	v_mul_f32_e32 v97, v97, v97
	v_mul_f32_e32 v107, v107, v107
	v_mul_f32_e32 v114, v114, v114
	v_mul_f32_e32 v116, v116, v116
	v_lshlrev_b32_e32 v108, 16, v100
	v_and_b32_e32 v111, 0xffff0000, v101
	v_lshlrev_b32_e32 v117, 16, v104
	v_and_b32_e32 v120, 0xffff0000, v105
	v_mul_f32_e32 v109, v109, v109
	v_mul_f32_e32 v118, v118, v118
	v_fmac_f32_e32 v97, v96, v96
	v_fmac_f32_e32 v107, v106, v106
	v_fmac_f32_e32 v114, v113, v113
	v_fmac_f32_e32 v116, v115, v115
	v_lshlrev_b32_e32 v110, 16, v101
	v_lshlrev_b32_e32 v119, 16, v105
	v_mul_f32_e32 v111, v111, v111
	v_mul_f32_e32 v120, v120, v120
	v_fmac_f32_e32 v109, v108, v108
	v_fmac_f32_e32 v118, v117, v117
	v_add_f32_e32 v96, v97, v107
	v_add_f32_e32 v97, v114, v116
	v_fmac_f32_e32 v111, v110, v110
	v_fmac_f32_e32 v120, v119, v119
	v_add_f32_e32 v96, v109, v96
	v_add_f32_e32 v97, v118, v97
	v_add_f32_e32 v96, v111, v96
	v_add_f32_e32 v97, v120, v97
	v_add_f32_e32 v96, v96, v97
	v_mov_b32_e32 v97, v96
	v_mov_b32_e32 v159, v96
	s_nop 1
	v_permlane16_swap_b32_e32 v97, v159
	global_store_dwordx4 v[122:123], v[98:101], off
	global_store_dwordx4 v[122:123], v[102:105], off offset:256
	s_waitcnt lgkmcnt(0)
	v_add_f32_e32 v96, v159, v97
	v_mov_b32_e32 v97, v96
	v_mov_b32_e32 v112, v96
	s_nop 1
	v_permlane32_swap_b32_e32 v97, v112
	s_and_saveexec_b64 s[34:35], s[8:9]
	s_cbranch_execz .LBB0_1673
	s_waitcnt lgkmcnt(0)
	v_add_f32_e32 v96, v112, v97
	ds_write_b32 v152, v96
.LBB0_1673:
	s_or_b64 exec, exec, s[34:35]
	v_or_b32_e32 v96, 32, v142
	s_waitcnt lgkmcnt(0)
	v_ashrrev_i32_e32 v97, 31, v96
	v_lshlrev_b64 v[96:97], 11, v[96:97]
	v_lshl_add_u64 v[96:97], s[48:49], 0, v[96:97]
	v_lshl_add_u64 v[104:105], v[140:141], 1, v[96:97]
	global_load_dwordx4 v[96:99], v[104:105], off
	global_load_dwordx4 v[100:103], v[104:105], off offset:256
	s_waitcnt vmcnt(1)
	v_lshlrev_b32_e32 v106, 16, v96
	v_and_b32_e32 v107, 0xffff0000, v96
	v_lshlrev_b32_e32 v96, 16, v97
	v_and_b32_e32 v97, 0xffff0000, v97
	s_waitcnt vmcnt(0)
	v_lshlrev_b32_e32 v110, 16, v100
	v_and_b32_e32 v111, 0xffff0000, v100
	v_lshlrev_b32_e32 v100, 16, v101
	v_and_b32_e32 v101, 0xffff0000, v101
	v_lshlrev_b32_e32 v108, 16, v98
	v_and_b32_e32 v109, 0xffff0000, v98
	v_lshlrev_b32_e32 v98, 16, v99
	v_and_b32_e32 v99, 0xffff0000, v99
	v_lshlrev_b32_e32 v114, 16, v102
	v_and_b32_e32 v115, 0xffff0000, v102
	v_lshlrev_b32_e32 v102, 16, v103
	v_and_b32_e32 v103, 0xffff0000, v103
	v_pk_fma_f32 v[94:95], v[94:95], 0.5, v[96:97] op_sel_hi:[1,0,1]
	v_pk_fma_f32 v[92:93], v[92:93], 0.5, v[106:107] op_sel_hi:[1,0,1]
	v_pk_fma_f32 v[96:97], v[86:87], 0.5, v[100:101] op_sel_hi:[1,0,1]
	v_pk_fma_f32 v[86:87], v[84:85], 0.5, v[110:111] op_sel_hi:[1,0,1]
	v_pk_fma_f32 v[90:91], v[90:91], 0.5, v[98:99] op_sel_hi:[1,0,1]
	v_pk_fma_f32 v[88:89], v[88:89], 0.5, v[108:109] op_sel_hi:[1,0,1]
	v_pk_fma_f32 v[98:99], v[82:83], 0.5, v[102:103] op_sel_hi:[1,0,1]
	v_pk_fma_f32 v[80:81], v[80:81], 0.5, v[114:115] op_sel_hi:[1,0,1]
	v_cvt_pk_bf16_f32 v82, v92, v93
	v_cvt_pk_bf16_f32 v83, v94, v95
	v_cvt_pk_bf16_f32 v86, v86, v87
	v_cvt_pk_bf16_f32 v87, v96, v97
	v_cvt_pk_bf16_f32 v84, v88, v89
	v_cvt_pk_bf16_f32 v85, v90, v91
	v_cvt_pk_bf16_f32 v88, v80, v81
	v_cvt_pk_bf16_f32 v89, v98, v99
	v_and_b32_e32 v81, 0xffff0000, v82
	v_and_b32_e32 v91, 0xffff0000, v83
	v_and_b32_e32 v97, 0xffff0000, v86
	v_and_b32_e32 v99, 0xffff0000, v87
	v_lshlrev_b32_e32 v80, 16, v82
	v_lshlrev_b32_e32 v90, 16, v83
	v_and_b32_e32 v93, 0xffff0000, v84
	v_lshlrev_b32_e32 v96, 16, v86
	v_lshlrev_b32_e32 v98, 16, v87
	v_and_b32_e32 v101, 0xffff0000, v88
	v_mul_f32_e32 v81, v81, v81
	v_mul_f32_e32 v91, v91, v91
	v_mul_f32_e32 v97, v97, v97
	v_mul_f32_e32 v99, v99, v99
	v_lshlrev_b32_e32 v92, 16, v84
	v_and_b32_e32 v95, 0xffff0000, v85
	v_lshlrev_b32_e32 v100, 16, v88
	v_and_b32_e32 v103, 0xffff0000, v89
	v_mul_f32_e32 v93, v93, v93
	v_mul_f32_e32 v101, v101, v101
	v_fmac_f32_e32 v81, v80, v80
	v_fmac_f32_e32 v91, v90, v90
	v_fmac_f32_e32 v97, v96, v96
	v_fmac_f32_e32 v99, v98, v98
	v_lshlrev_b32_e32 v94, 16, v85
	v_lshlrev_b32_e32 v102, 16, v89
	v_mul_f32_e32 v95, v95, v95
	v_mul_f32_e32 v103, v103, v103
	v_fmac_f32_e32 v93, v92, v92
	v_fmac_f32_e32 v101, v100, v100
	v_add_f32_e32 v80, v81, v91
	v_add_f32_e32 v81, v97, v99
	v_fmac_f32_e32 v95, v94, v94
	v_fmac_f32_e32 v103, v102, v102
	v_add_f32_e32 v80, v93, v80
	v_add_f32_e32 v81, v101, v81
	v_add_f32_e32 v80, v95, v80
	v_add_f32_e32 v81, v103, v81
	v_add_f32_e32 v80, v80, v81
	v_mov_b32_e32 v81, v80
	v_mov_b32_e32 v159, v80
	s_nop 1
	v_permlane16_swap_b32_e32 v81, v159
	global_store_dwordx4 v[104:105], v[82:85], off
	global_store_dwordx4 v[104:105], v[86:89], off offset:256
	s_waitcnt lgkmcnt(0)
	v_add_f32_e32 v80, v159, v81
	v_mov_b32_e32 v81, v80
	v_mov_b32_e32 v112, v80
	s_nop 1
	v_permlane32_swap_b32_e32 v81, v112
	s_and_saveexec_b64 s[34:35], s[8:9]
	s_cbranch_execz .LBB0_1675
	s_waitcnt lgkmcnt(0)
	v_add_f32_e32 v80, v112, v81
	ds_write_b32 v153, v80
.LBB0_1675:
	s_or_b64 exec, exec, s[34:35]
	v_or_b32_e32 v80, 48, v142
	s_waitcnt lgkmcnt(0)
	v_ashrrev_i32_e32 v81, 31, v80
	v_lshlrev_b64 v[80:81], 11, v[80:81]
	v_lshl_add_u64 v[80:81], s[48:49], 0, v[80:81]
	v_lshl_add_u64 v[88:89], v[140:141], 1, v[80:81]
	global_load_dwordx4 v[80:83], v[88:89], off
	global_load_dwordx4 v[84:87], v[88:89], off offset:256
	s_waitcnt vmcnt(1)
	v_lshlrev_b32_e32 v90, 16, v80
	v_and_b32_e32 v91, 0xffff0000, v80
	v_lshlrev_b32_e32 v80, 16, v81
	v_and_b32_e32 v81, 0xffff0000, v81
	s_waitcnt vmcnt(0)
	v_lshlrev_b32_e32 v94, 16, v84
	v_and_b32_e32 v95, 0xffff0000, v84
	v_lshlrev_b32_e32 v84, 16, v85
	v_and_b32_e32 v85, 0xffff0000, v85
	v_lshlrev_b32_e32 v92, 16, v82
	v_and_b32_e32 v93, 0xffff0000, v82
	v_lshlrev_b32_e32 v82, 16, v83
	v_and_b32_e32 v83, 0xffff0000, v83
	v_lshlrev_b32_e32 v96, 16, v86
	v_and_b32_e32 v97, 0xffff0000, v86
	v_lshlrev_b32_e32 v86, 16, v87
	v_and_b32_e32 v87, 0xffff0000, v87
	v_pk_fma_f32 v[78:79], v[78:79], 0.5, v[80:81] op_sel_hi:[1,0,1]
	v_pk_fma_f32 v[76:77], v[76:77], 0.5, v[90:91] op_sel_hi:[1,0,1]
	v_pk_fma_f32 v[80:81], v[70:71], 0.5, v[84:85] op_sel_hi:[1,0,1]
	v_pk_fma_f32 v[70:71], v[68:69], 0.5, v[94:95] op_sel_hi:[1,0,1]
	v_pk_fma_f32 v[74:75], v[74:75], 0.5, v[82:83] op_sel_hi:[1,0,1]
	v_pk_fma_f32 v[72:73], v[72:73], 0.5, v[92:93] op_sel_hi:[1,0,1]
	v_pk_fma_f32 v[82:83], v[66:67], 0.5, v[86:87] op_sel_hi:[1,0,1]
	v_pk_fma_f32 v[64:65], v[64:65], 0.5, v[96:97] op_sel_hi:[1,0,1]
	v_cvt_pk_bf16_f32 v66, v76, v77
	v_cvt_pk_bf16_f32 v67, v78, v79
	v_cvt_pk_bf16_f32 v70, v70, v71
	v_cvt_pk_bf16_f32 v71, v80, v81
	v_cvt_pk_bf16_f32 v68, v72, v73
	v_cvt_pk_bf16_f32 v69, v74, v75
	v_cvt_pk_bf16_f32 v72, v64, v65
	v_cvt_pk_bf16_f32 v73, v82, v83
	v_and_b32_e32 v65, 0xffff0000, v66
	v_and_b32_e32 v75, 0xffff0000, v67
	v_and_b32_e32 v81, 0xffff0000, v70
	v_and_b32_e32 v83, 0xffff0000, v71
	v_lshlrev_b32_e32 v64, 16, v66
	v_lshlrev_b32_e32 v74, 16, v67
	v_and_b32_e32 v77, 0xffff0000, v68
	v_lshlrev_b32_e32 v80, 16, v70
	v_lshlrev_b32_e32 v82, 16, v71
	v_and_b32_e32 v85, 0xffff0000, v72
	v_mul_f32_e32 v65, v65, v65
	v_mul_f32_e32 v75, v75, v75
	v_mul_f32_e32 v81, v81, v81
	v_mul_f32_e32 v83, v83, v83
	v_lshlrev_b32_e32 v76, 16, v68
	v_and_b32_e32 v79, 0xffff0000, v69
	v_lshlrev_b32_e32 v84, 16, v72
	v_and_b32_e32 v87, 0xffff0000, v73
	v_mul_f32_e32 v77, v77, v77
	v_mul_f32_e32 v85, v85, v85
	v_fmac_f32_e32 v65, v64, v64
	v_fmac_f32_e32 v75, v74, v74
	v_fmac_f32_e32 v81, v80, v80
	v_fmac_f32_e32 v83, v82, v82
	v_lshlrev_b32_e32 v78, 16, v69
	v_lshlrev_b32_e32 v86, 16, v73
	v_mul_f32_e32 v79, v79, v79
	v_mul_f32_e32 v87, v87, v87
	v_fmac_f32_e32 v77, v76, v76
	v_fmac_f32_e32 v85, v84, v84
	v_add_f32_e32 v64, v65, v75
	v_add_f32_e32 v65, v81, v83
	v_fmac_f32_e32 v79, v78, v78
	v_fmac_f32_e32 v87, v86, v86
	v_add_f32_e32 v64, v77, v64
	v_add_f32_e32 v65, v85, v65
	v_add_f32_e32 v64, v79, v64
	v_add_f32_e32 v65, v87, v65
	v_add_f32_e32 v64, v64, v65
	v_mov_b32_e32 v65, v64
	v_mov_b32_e32 v159, v64
	s_nop 1
	v_permlane16_swap_b32_e32 v65, v159
	global_store_dwordx4 v[88:89], v[66:69], off
	global_store_dwordx4 v[88:89], v[70:73], off offset:256
	s_waitcnt lgkmcnt(0)
	v_add_f32_e32 v64, v159, v65
	v_mov_b32_e32 v65, v64
	v_mov_b32_e32 v112, v64
	s_nop 1
	v_permlane32_swap_b32_e32 v65, v112
	s_and_saveexec_b64 s[34:35], s[8:9]
	s_cbranch_execz .LBB0_1677
	s_waitcnt lgkmcnt(0)
	v_add_f32_e32 v64, v112, v65
	ds_write_b32 v154, v64
.LBB0_1677:
	s_or_b64 exec, exec, s[34:35]
	s_waitcnt lgkmcnt(0)
	v_lshlrev_b64 v[64:65], 11, v[142:143]
	v_lshl_add_u64 v[64:65], s[48:49], 0, v[64:65]
	v_lshl_add_u64 v[64:65], v[140:141], 1, v[64:65]
	v_add_co_u32_e32 v74, vcc, 0x40000, v64
	v_lshl_add_u64 v[76:77], v[64:65], 0, s[20:21]
	s_nop 0
	v_addc_co_u32_e32 v75, vcc, 0, v65, vcc
	global_load_dwordx4 v[66:69], v[74:75], off
	global_load_dwordx4 v[70:73], v[76:77], off offset:256
	s_waitcnt vmcnt(1)
	v_lshlrev_b32_e32 v78, 16, v66
	v_and_b32_e32 v79, 0xffff0000, v66
	v_lshlrev_b32_e32 v66, 16, v67
	v_and_b32_e32 v67, 0xffff0000, v67
	s_waitcnt vmcnt(0)
	v_lshlrev_b32_e32 v82, 16, v70
	v_and_b32_e32 v83, 0xffff0000, v70
	v_lshlrev_b32_e32 v70, 16, v71
	v_and_b32_e32 v71, 0xffff0000, v71
	v_lshlrev_b32_e32 v80, 16, v68
	v_and_b32_e32 v81, 0xffff0000, v68
	v_lshlrev_b32_e32 v68, 16, v69
	v_and_b32_e32 v69, 0xffff0000, v69
	v_lshlrev_b32_e32 v84, 16, v72
	v_and_b32_e32 v85, 0xffff0000, v72
	v_lshlrev_b32_e32 v72, 16, v73
	v_and_b32_e32 v73, 0xffff0000, v73
	v_pk_fma_f32 v[62:63], v[62:63], 0.5, v[66:67] op_sel_hi:[1,0,1]
	v_pk_fma_f32 v[60:61], v[60:61], 0.5, v[78:79] op_sel_hi:[1,0,1]
	v_pk_fma_f32 v[66:67], v[54:55], 0.5, v[70:71] op_sel_hi:[1,0,1]
	v_pk_fma_f32 v[54:55], v[52:53], 0.5, v[82:83] op_sel_hi:[1,0,1]
	v_pk_fma_f32 v[58:59], v[58:59], 0.5, v[68:69] op_sel_hi:[1,0,1]
	v_pk_fma_f32 v[56:57], v[56:57], 0.5, v[80:81] op_sel_hi:[1,0,1]
	v_pk_fma_f32 v[68:69], v[50:51], 0.5, v[72:73] op_sel_hi:[1,0,1]
	v_pk_fma_f32 v[48:49], v[48:49], 0.5, v[84:85] op_sel_hi:[1,0,1]
	v_cvt_pk_bf16_f32 v50, v60, v61
	v_cvt_pk_bf16_f32 v51, v62, v63
	v_cvt_pk_bf16_f32 v54, v54, v55
	v_cvt_pk_bf16_f32 v55, v66, v67
	v_cvt_pk_bf16_f32 v52, v56, v57
	v_cvt_pk_bf16_f32 v53, v58, v59
	v_cvt_pk_bf16_f32 v56, v48, v49
	v_cvt_pk_bf16_f32 v57, v68, v69
	v_and_b32_e32 v49, 0xffff0000, v50
	v_and_b32_e32 v59, 0xffff0000, v51
	v_and_b32_e32 v67, 0xffff0000, v54
	v_and_b32_e32 v69, 0xffff0000, v55
	v_lshlrev_b32_e32 v48, 16, v50
	v_lshlrev_b32_e32 v58, 16, v51
	v_and_b32_e32 v61, 0xffff0000, v52
	v_lshlrev_b32_e32 v66, 16, v54
	v_lshlrev_b32_e32 v68, 16, v55
	v_and_b32_e32 v71, 0xffff0000, v56
	v_mul_f32_e32 v49, v49, v49
	v_mul_f32_e32 v59, v59, v59
	v_mul_f32_e32 v67, v67, v67
	v_mul_f32_e32 v69, v69, v69
	v_lshlrev_b32_e32 v60, 16, v52
	v_and_b32_e32 v63, 0xffff0000, v53
	v_lshlrev_b32_e32 v70, 16, v56
	v_and_b32_e32 v73, 0xffff0000, v57
	v_mul_f32_e32 v61, v61, v61
	v_mul_f32_e32 v71, v71, v71
	v_fmac_f32_e32 v49, v48, v48
	v_fmac_f32_e32 v59, v58, v58
	v_fmac_f32_e32 v67, v66, v66
	v_fmac_f32_e32 v69, v68, v68
	v_lshlrev_b32_e32 v62, 16, v53
	v_lshlrev_b32_e32 v72, 16, v57
	v_mul_f32_e32 v63, v63, v63
	v_mul_f32_e32 v73, v73, v73
	v_fmac_f32_e32 v61, v60, v60
	v_fmac_f32_e32 v71, v70, v70
	v_add_f32_e32 v48, v49, v59
	v_add_f32_e32 v49, v67, v69
	v_fmac_f32_e32 v63, v62, v62
	v_fmac_f32_e32 v73, v72, v72
	v_add_f32_e32 v48, v61, v48
	v_add_f32_e32 v49, v71, v49
	v_add_f32_e32 v48, v63, v48
	v_add_f32_e32 v49, v73, v49
	v_add_f32_e32 v48, v48, v49
	v_mov_b32_e32 v49, v48
	v_mov_b32_e32 v159, v48
	s_nop 1
	v_permlane16_swap_b32_e32 v49, v159
	global_store_dwordx4 v[74:75], v[50:53], off
	global_store_dwordx4 v[76:77], v[54:57], off offset:256
	s_waitcnt lgkmcnt(0)
	v_add_f32_e32 v48, v159, v49
	v_mov_b32_e32 v49, v48
	v_mov_b32_e32 v112, v48
	s_nop 1
	v_permlane32_swap_b32_e32 v49, v112
	s_and_saveexec_b64 s[34:35], s[8:9]
	s_cbranch_execz .LBB0_1679
	s_waitcnt lgkmcnt(0)
	v_add_f32_e32 v48, v112, v49
	ds_write_b32 v155, v48
.LBB0_1679:
	s_or_b64 exec, exec, s[34:35]
	v_add_co_u32_e32 v56, vcc, 0x48000, v64
	v_lshl_add_u64 v[58:59], v[64:65], 0, s[22:23]
	s_nop 0
	v_addc_co_u32_e32 v57, vcc, 0, v65, vcc
	s_waitcnt lgkmcnt(0)
	global_load_dwordx4 v[48:51], v[56:57], off
	global_load_dwordx4 v[52:55], v[58:59], off offset:256
	s_waitcnt vmcnt(1)
	v_lshlrev_b32_e32 v60, 16, v48
	v_and_b32_e32 v61, 0xffff0000, v48
	v_lshlrev_b32_e32 v48, 16, v49
	v_and_b32_e32 v49, 0xffff0000, v49
	s_waitcnt vmcnt(0)
	v_lshlrev_b32_e32 v64, 16, v52
	v_and_b32_e32 v65, 0xffff0000, v52
	v_lshlrev_b32_e32 v52, 16, v53
	v_and_b32_e32 v53, 0xffff0000, v53
	v_lshlrev_b32_e32 v62, 16, v50
	v_and_b32_e32 v63, 0xffff0000, v50
	v_lshlrev_b32_e32 v50, 16, v51
	v_and_b32_e32 v51, 0xffff0000, v51
	v_lshlrev_b32_e32 v66, 16, v54
	v_and_b32_e32 v67, 0xffff0000, v54
	v_lshlrev_b32_e32 v54, 16, v55
	v_and_b32_e32 v55, 0xffff0000, v55
	v_pk_fma_f32 v[46:47], v[46:47], 0.5, v[48:49] op_sel_hi:[1,0,1]
	v_pk_fma_f32 v[44:45], v[44:45], 0.5, v[60:61] op_sel_hi:[1,0,1]
	v_pk_fma_f32 v[48:49], v[38:39], 0.5, v[52:53] op_sel_hi:[1,0,1]
	v_pk_fma_f32 v[38:39], v[36:37], 0.5, v[64:65] op_sel_hi:[1,0,1]
	v_pk_fma_f32 v[42:43], v[42:43], 0.5, v[50:51] op_sel_hi:[1,0,1]
	v_pk_fma_f32 v[40:41], v[40:41], 0.5, v[62:63] op_sel_hi:[1,0,1]
	v_pk_fma_f32 v[50:51], v[34:35], 0.5, v[54:55] op_sel_hi:[1,0,1]
	v_pk_fma_f32 v[32:33], v[32:33], 0.5, v[66:67] op_sel_hi:[1,0,1]
	v_cvt_pk_bf16_f32 v34, v44, v45
	v_cvt_pk_bf16_f32 v35, v46, v47
	v_cvt_pk_bf16_f32 v38, v38, v39
	v_cvt_pk_bf16_f32 v39, v48, v49
	v_cvt_pk_bf16_f32 v36, v40, v41
	v_cvt_pk_bf16_f32 v37, v42, v43
	v_cvt_pk_bf16_f32 v40, v32, v33
	v_cvt_pk_bf16_f32 v41, v50, v51
	v_and_b32_e32 v33, 0xffff0000, v34
	v_and_b32_e32 v43, 0xffff0000, v35
	v_and_b32_e32 v49, 0xffff0000, v38
	v_and_b32_e32 v51, 0xffff0000, v39
	v_lshlrev_b32_e32 v32, 16, v34
	v_lshlrev_b32_e32 v42, 16, v35
	v_and_b32_e32 v45, 0xffff0000, v36
	v_lshlrev_b32_e32 v48, 16, v38
	v_lshlrev_b32_e32 v50, 16, v39
	v_and_b32_e32 v53, 0xffff0000, v40
	v_mul_f32_e32 v33, v33, v33
	v_mul_f32_e32 v43, v43, v43
	v_mul_f32_e32 v49, v49, v49
	v_mul_f32_e32 v51, v51, v51
	v_lshlrev_b32_e32 v44, 16, v36
	v_and_b32_e32 v47, 0xffff0000, v37
	v_lshlrev_b32_e32 v52, 16, v40
	v_and_b32_e32 v55, 0xffff0000, v41
	v_mul_f32_e32 v45, v45, v45
	v_mul_f32_e32 v53, v53, v53
	v_fmac_f32_e32 v33, v32, v32
	v_fmac_f32_e32 v43, v42, v42
	v_fmac_f32_e32 v49, v48, v48
	v_fmac_f32_e32 v51, v50, v50
	v_lshlrev_b32_e32 v46, 16, v37
	v_lshlrev_b32_e32 v54, 16, v41
	v_mul_f32_e32 v47, v47, v47
	v_mul_f32_e32 v55, v55, v55
	v_fmac_f32_e32 v45, v44, v44
	v_fmac_f32_e32 v53, v52, v52
	v_add_f32_e32 v32, v33, v43
	v_add_f32_e32 v33, v49, v51
	v_fmac_f32_e32 v47, v46, v46
	v_fmac_f32_e32 v55, v54, v54
	v_add_f32_e32 v32, v45, v32
	v_add_f32_e32 v33, v53, v33
	v_add_f32_e32 v32, v47, v32
	v_add_f32_e32 v33, v55, v33
	v_add_f32_e32 v32, v32, v33
	v_mov_b32_e32 v33, v32
	v_mov_b32_e32 v159, v32
	s_nop 1
	v_permlane16_swap_b32_e32 v33, v159
	global_store_dwordx4 v[56:57], v[34:37], off
	global_store_dwordx4 v[58:59], v[38:41], off offset:256
	s_waitcnt lgkmcnt(0)
	v_add_f32_e32 v32, v159, v33
	v_mov_b32_e32 v33, v32
	v_mov_b32_e32 v112, v32
	s_nop 1
	v_permlane32_swap_b32_e32 v33, v112
	s_and_saveexec_b64 s[34:35], s[8:9]
	s_cbranch_execz .LBB0_1681
	s_waitcnt lgkmcnt(0)
	v_add_f32_e32 v32, v112, v33
	ds_write_b32 v156, v32
.LBB0_1681:
	s_or_b64 exec, exec, s[34:35]
	s_waitcnt lgkmcnt(0)
	v_lshlrev_b64 v[32:33], 11, v[142:143]
	v_lshl_add_u64 v[32:33], s[48:49], 0, v[32:33]
	v_lshl_add_u64 v[32:33], v[140:141], 1, v[32:33]
	v_add_co_u32_e32 v42, vcc, 0x50000, v32
	v_lshl_add_u64 v[44:45], v[32:33], 0, s[24:25]
	s_nop 0
	v_addc_co_u32_e32 v43, vcc, 0, v33, vcc
	global_load_dwordx4 v[34:37], v[42:43], off
	global_load_dwordx4 v[38:41], v[44:45], off offset:256
	s_waitcnt vmcnt(1)
	v_lshlrev_b32_e32 v46, 16, v34
	v_and_b32_e32 v47, 0xffff0000, v34
	v_lshlrev_b32_e32 v34, 16, v35
	v_and_b32_e32 v35, 0xffff0000, v35
	s_waitcnt vmcnt(0)
	v_lshlrev_b32_e32 v50, 16, v38
	v_and_b32_e32 v51, 0xffff0000, v38
	v_lshlrev_b32_e32 v38, 16, v39
	v_and_b32_e32 v39, 0xffff0000, v39
	v_lshlrev_b32_e32 v48, 16, v36
	v_and_b32_e32 v49, 0xffff0000, v36
	v_lshlrev_b32_e32 v36, 16, v37
	v_and_b32_e32 v37, 0xffff0000, v37
	v_lshlrev_b32_e32 v52, 16, v40
	v_and_b32_e32 v53, 0xffff0000, v40
	v_lshlrev_b32_e32 v40, 16, v41
	v_and_b32_e32 v41, 0xffff0000, v41
	v_pk_fma_f32 v[30:31], v[30:31], 0.5, v[34:35] op_sel_hi:[1,0,1]
	v_pk_fma_f32 v[28:29], v[28:29], 0.5, v[46:47] op_sel_hi:[1,0,1]
	v_pk_fma_f32 v[34:35], v[22:23], 0.5, v[38:39] op_sel_hi:[1,0,1]
	v_pk_fma_f32 v[22:23], v[20:21], 0.5, v[50:51] op_sel_hi:[1,0,1]
	v_pk_fma_f32 v[26:27], v[26:27], 0.5, v[36:37] op_sel_hi:[1,0,1]
	v_pk_fma_f32 v[24:25], v[24:25], 0.5, v[48:49] op_sel_hi:[1,0,1]
	v_pk_fma_f32 v[36:37], v[18:19], 0.5, v[40:41] op_sel_hi:[1,0,1]
	v_pk_fma_f32 v[16:17], v[16:17], 0.5, v[52:53] op_sel_hi:[1,0,1]
	v_cvt_pk_bf16_f32 v18, v28, v29
	v_cvt_pk_bf16_f32 v19, v30, v31
	v_cvt_pk_bf16_f32 v22, v22, v23
	v_cvt_pk_bf16_f32 v23, v34, v35
	v_cvt_pk_bf16_f32 v20, v24, v25
	v_cvt_pk_bf16_f32 v21, v26, v27
	v_cvt_pk_bf16_f32 v24, v16, v17
	v_cvt_pk_bf16_f32 v25, v36, v37
	v_and_b32_e32 v17, 0xffff0000, v18
	v_and_b32_e32 v27, 0xffff0000, v19
	v_and_b32_e32 v35, 0xffff0000, v22
	v_and_b32_e32 v37, 0xffff0000, v23
	v_lshlrev_b32_e32 v16, 16, v18
	v_lshlrev_b32_e32 v26, 16, v19
	v_and_b32_e32 v29, 0xffff0000, v20
	v_lshlrev_b32_e32 v34, 16, v22
	v_lshlrev_b32_e32 v36, 16, v23
	v_and_b32_e32 v39, 0xffff0000, v24
	v_mul_f32_e32 v17, v17, v17
	v_mul_f32_e32 v27, v27, v27
	v_mul_f32_e32 v35, v35, v35
	v_mul_f32_e32 v37, v37, v37
	v_lshlrev_b32_e32 v28, 16, v20
	v_and_b32_e32 v31, 0xffff0000, v21
	v_lshlrev_b32_e32 v38, 16, v24
	v_and_b32_e32 v41, 0xffff0000, v25
	v_mul_f32_e32 v29, v29, v29
	v_mul_f32_e32 v39, v39, v39
	v_fmac_f32_e32 v17, v16, v16
	v_fmac_f32_e32 v27, v26, v26
	v_fmac_f32_e32 v35, v34, v34
	v_fmac_f32_e32 v37, v36, v36
	v_lshlrev_b32_e32 v30, 16, v21
	v_lshlrev_b32_e32 v40, 16, v25
	v_mul_f32_e32 v31, v31, v31
	v_mul_f32_e32 v41, v41, v41
	v_fmac_f32_e32 v29, v28, v28
	v_fmac_f32_e32 v39, v38, v38
	v_add_f32_e32 v16, v17, v27
	v_add_f32_e32 v17, v35, v37
	v_fmac_f32_e32 v31, v30, v30
	v_fmac_f32_e32 v41, v40, v40
	v_add_f32_e32 v16, v29, v16
	v_add_f32_e32 v17, v39, v17
	v_add_f32_e32 v16, v31, v16
	v_add_f32_e32 v17, v41, v17
	v_add_f32_e32 v16, v16, v17
	v_mov_b32_e32 v17, v16
	v_mov_b32_e32 v159, v16
	s_nop 1
	v_permlane16_swap_b32_e32 v17, v159
	global_store_dwordx4 v[42:43], v[18:21], off
	global_store_dwordx4 v[44:45], v[22:25], off offset:256
	s_waitcnt lgkmcnt(0)
	v_add_f32_e32 v16, v159, v17
	v_mov_b32_e32 v17, v16
	v_mov_b32_e32 v112, v16
	s_nop 1
	v_permlane32_swap_b32_e32 v17, v112
	s_and_saveexec_b64 s[34:35], s[8:9]
	s_cbranch_execz .LBB0_1683
	s_waitcnt lgkmcnt(0)
	v_add_f32_e32 v16, v112, v17
	ds_write_b32 v157, v16
.LBB0_1683:
	s_or_b64 exec, exec, s[34:35]
	v_add_co_u32_e32 v24, vcc, 0x58000, v32
	v_lshl_add_u64 v[26:27], v[32:33], 0, s[26:27]
	s_nop 0
	v_addc_co_u32_e32 v25, vcc, 0, v33, vcc
	s_waitcnt lgkmcnt(0)
	global_load_dwordx4 v[16:19], v[24:25], off
	global_load_dwordx4 v[20:23], v[26:27], off offset:256
	s_waitcnt vmcnt(1)
	v_lshlrev_b32_e32 v28, 16, v16
	v_and_b32_e32 v29, 0xffff0000, v16
	v_lshlrev_b32_e32 v16, 16, v17
	v_and_b32_e32 v17, 0xffff0000, v17
	s_waitcnt vmcnt(0)
	v_lshlrev_b32_e32 v32, 16, v20
	v_and_b32_e32 v33, 0xffff0000, v20
	v_lshlrev_b32_e32 v20, 16, v21
	v_and_b32_e32 v21, 0xffff0000, v21
	v_lshlrev_b32_e32 v30, 16, v18
	v_and_b32_e32 v31, 0xffff0000, v18
	v_lshlrev_b32_e32 v18, 16, v19
	v_and_b32_e32 v19, 0xffff0000, v19
	v_lshlrev_b32_e32 v34, 16, v22
	v_and_b32_e32 v35, 0xffff0000, v22
	v_lshlrev_b32_e32 v22, 16, v23
	v_and_b32_e32 v23, 0xffff0000, v23
	v_pk_fma_f32 v[14:15], v[14:15], 0.5, v[16:17] op_sel_hi:[1,0,1]
	v_pk_fma_f32 v[12:13], v[12:13], 0.5, v[28:29] op_sel_hi:[1,0,1]
	v_pk_fma_f32 v[16:17], v[6:7], 0.5, v[20:21] op_sel_hi:[1,0,1]
	v_pk_fma_f32 v[6:7], v[4:5], 0.5, v[32:33] op_sel_hi:[1,0,1]
	v_pk_fma_f32 v[10:11], v[10:11], 0.5, v[18:19] op_sel_hi:[1,0,1]
	v_pk_fma_f32 v[8:9], v[8:9], 0.5, v[30:31] op_sel_hi:[1,0,1]
	v_pk_fma_f32 v[18:19], v[2:3], 0.5, v[22:23] op_sel_hi:[1,0,1]
	v_pk_fma_f32 v[0:1], v[0:1], 0.5, v[34:35] op_sel_hi:[1,0,1]
	v_cvt_pk_bf16_f32 v2, v12, v13
	v_cvt_pk_bf16_f32 v3, v14, v15
	v_cvt_pk_bf16_f32 v6, v6, v7
	v_cvt_pk_bf16_f32 v7, v16, v17
	v_cvt_pk_bf16_f32 v4, v8, v9
	v_cvt_pk_bf16_f32 v5, v10, v11
	v_cvt_pk_bf16_f32 v8, v0, v1
	v_cvt_pk_bf16_f32 v9, v18, v19
	v_and_b32_e32 v1, 0xffff0000, v2
	v_and_b32_e32 v11, 0xffff0000, v3
	v_and_b32_e32 v17, 0xffff0000, v6
	v_and_b32_e32 v19, 0xffff0000, v7
	v_lshlrev_b32_e32 v0, 16, v2
	v_lshlrev_b32_e32 v10, 16, v3
	v_and_b32_e32 v13, 0xffff0000, v4
	v_lshlrev_b32_e32 v16, 16, v6
	v_lshlrev_b32_e32 v18, 16, v7
	v_and_b32_e32 v21, 0xffff0000, v8
	v_mul_f32_e32 v1, v1, v1
	v_mul_f32_e32 v11, v11, v11
	v_mul_f32_e32 v17, v17, v17
	v_mul_f32_e32 v19, v19, v19
	v_lshlrev_b32_e32 v12, 16, v4
	v_and_b32_e32 v15, 0xffff0000, v5
	v_lshlrev_b32_e32 v20, 16, v8
	v_and_b32_e32 v23, 0xffff0000, v9
	v_mul_f32_e32 v13, v13, v13
	v_mul_f32_e32 v21, v21, v21
	v_fmac_f32_e32 v1, v0, v0
	v_fmac_f32_e32 v11, v10, v10
	v_fmac_f32_e32 v17, v16, v16
	v_fmac_f32_e32 v19, v18, v18
	v_lshlrev_b32_e32 v14, 16, v5
	v_lshlrev_b32_e32 v22, 16, v9
	v_mul_f32_e32 v15, v15, v15
	v_mul_f32_e32 v23, v23, v23
	v_fmac_f32_e32 v13, v12, v12
	v_fmac_f32_e32 v21, v20, v20
	v_add_f32_e32 v0, v1, v11
	v_add_f32_e32 v1, v17, v19
	v_fmac_f32_e32 v15, v14, v14
	v_fmac_f32_e32 v23, v22, v22
	v_add_f32_e32 v0, v13, v0
	v_add_f32_e32 v1, v21, v1
	v_add_f32_e32 v0, v15, v0
	v_add_f32_e32 v1, v23, v1
	v_add_f32_e32 v0, v0, v1
	v_mov_b32_e32 v1, v0
	v_mov_b32_e32 v159, v0
	s_nop 1
	v_permlane16_swap_b32_e32 v1, v159
	global_store_dwordx4 v[24:25], v[2:5], off
	global_store_dwordx4 v[26:27], v[6:9], off offset:256
	s_waitcnt lgkmcnt(0)
	v_add_f32_e32 v0, v159, v1
	v_mov_b32_e32 v1, v0
	v_mov_b32_e32 v112, v0
	s_nop 1
	v_permlane32_swap_b32_e32 v1, v112
	s_and_saveexec_b64 s[34:35], s[8:9]
	s_cbranch_execz .LBB0_1685
	s_waitcnt lgkmcnt(0)
	v_add_f32_e32 v0, v112, v1
	ds_write_b32 v158, v0

.LBB0_2305:
	s_lshl_b32 s36, s36, 8
	v_add_u32_e32 v142, s36, v144
	v_ashrrev_i32_e32 v143, 31, v142
	v_lshl_or_b32 v140, s38, 8, v146
	v_lshlrev_b64 v[160:161], 11, v[142:143]
	v_ashrrev_i32_e32 v141, 31, v140
	v_lshl_add_u64 v[160:161], s[48:49], 0, v[160:161]
	v_lshl_add_u64 v[168:169], v[140:141], 1, v[160:161]
	global_load_dwordx4 v[160:163], v[168:169], off
	global_load_dwordx4 v[164:167], v[168:169], off offset:256
	v_and_b32_e32 v170, 64, v150
	v_add_u32_e32 v178, 64, v170
	v_xor_b32_e32 v159, 16, v150
	v_cmp_lt_i32_e32 vcc, v159, v178
	s_waitcnt vmcnt(0)
	v_lshlrev_b32_e32 v170, 16, v160
	v_and_b32_e32 v171, 0xffff0000, v160
	v_lshlrev_b32_e32 v160, 16, v161
	v_and_b32_e32 v161, 0xffff0000, v161
	v_lshlrev_b32_e32 v172, 16, v162
	v_and_b32_e32 v173, 0xffff0000, v162
	v_lshlrev_b32_e32 v162, 16, v163
	v_and_b32_e32 v163, 0xffff0000, v163
	v_lshlrev_b32_e32 v174, 16, v164
	v_and_b32_e32 v175, 0xffff0000, v164
	v_lshlrev_b32_e32 v164, 16, v165
	v_and_b32_e32 v165, 0xffff0000, v165
	v_lshlrev_b32_e32 v176, 16, v166
	v_and_b32_e32 v177, 0xffff0000, v166
	v_lshlrev_b32_e32 v166, 16, v167
	v_and_b32_e32 v167, 0xffff0000, v167
	v_pk_add_f32 v[126:127], v[126:127], v[160:161]
	v_pk_add_f32 v[124:125], v[124:125], v[170:171]
	v_pk_add_f32 v[122:123], v[122:123], v[162:163]
	v_pk_add_f32 v[120:121], v[120:121], v[172:173]
	v_pk_add_f32 v[160:161], v[118:119], v[164:165]
	v_pk_add_f32 v[162:163], v[116:117], v[174:175]
	v_pk_add_f32 v[114:115], v[114:115], v[166:167]
	v_pk_add_f32 v[112:113], v[112:113], v[176:177]
	v_cvt_pk_bf16_f32 v116, v124, v125
	v_cvt_pk_bf16_f32 v117, v126, v127
	v_cvt_pk_bf16_f32 v118, v120, v121
	v_cvt_pk_bf16_f32 v120, v162, v163
	v_cvt_pk_bf16_f32 v121, v160, v161
	v_cvt_pk_bf16_f32 v119, v122, v123
	v_cvt_pk_bf16_f32 v122, v112, v113
	v_cvt_pk_bf16_f32 v123, v114, v115
	v_and_b32_e32 v113, 0xffff0000, v116
	v_and_b32_e32 v115, 0xffff0000, v117
	v_and_b32_e32 v161, 0xffff0000, v120
	v_and_b32_e32 v163, 0xffff0000, v121
	v_lshlrev_b32_e32 v112, 16, v116
	v_lshlrev_b32_e32 v114, 16, v117
	v_and_b32_e32 v125, 0xffff0000, v118
	v_lshlrev_b32_e32 v160, 16, v120
	v_lshlrev_b32_e32 v162, 16, v121
	v_and_b32_e32 v165, 0xffff0000, v122
	v_mul_f32_e32 v113, v113, v113
	v_mul_f32_e32 v115, v115, v115
	v_mul_f32_e32 v161, v161, v161
	v_mul_f32_e32 v163, v163, v163
	v_lshlrev_b32_e32 v124, 16, v118
	v_and_b32_e32 v127, 0xffff0000, v119
	v_lshlrev_b32_e32 v164, 16, v122
	v_and_b32_e32 v167, 0xffff0000, v123
	v_mul_f32_e32 v125, v125, v125
	v_mul_f32_e32 v165, v165, v165
	v_fmac_f32_e32 v113, v112, v112
	v_fmac_f32_e32 v115, v114, v114
	v_fmac_f32_e32 v161, v160, v160
	v_fmac_f32_e32 v163, v162, v162
	v_lshlrev_b32_e32 v126, 16, v119
	v_lshlrev_b32_e32 v166, 16, v123
	v_mul_f32_e32 v127, v127, v127
	v_mul_f32_e32 v167, v167, v167
	v_fmac_f32_e32 v125, v124, v124
	v_fmac_f32_e32 v165, v164, v164
	v_add_f32_e32 v112, v113, v115
	v_add_f32_e32 v113, v161, v163
	v_fmac_f32_e32 v127, v126, v126
	v_fmac_f32_e32 v167, v166, v166
	v_add_f32_e32 v112, v125, v112
	v_add_f32_e32 v113, v165, v113
	v_cndmask_b32_e32 v159, v150, v159, vcc
	v_add_f32_e32 v112, v127, v112
	v_add_f32_e32 v113, v167, v113
	v_lshlrev_b32_e32 v159, 2, v159
	v_add_f32_e32 v113, v112, v113
	v_mov_b32_e32 v114, v113
	v_mov_b32_e32 v159, v113
	s_nop 1
	v_permlane16_swap_b32_e32 v114, v159
	v_xor_b32_e32 v112, 32, v150
	v_cmp_lt_i32_e32 vcc, v112, v178
	global_store_dwordx4 v[168:169], v[116:119], off
	global_store_dwordx4 v[168:169], v[120:123], off offset:256
	v_cndmask_b32_e32 v112, v150, v112, vcc
	v_lshlrev_b32_e32 v112, 2, v112
	s_waitcnt lgkmcnt(0)
	v_add_f32_e32 v113, v159, v114
	v_mov_b32_e32 v114, v113
	v_mov_b32_e32 v112, v113
	s_nop 1
	v_permlane32_swap_b32_e32 v114, v112
	s_and_saveexec_b64 s[38:39], s[8:9]
	s_cbranch_execz .LBB0_2307
	s_waitcnt lgkmcnt(0)
	v_add_f32_e32 v113, v112, v114
	ds_write_b32 v151, v113
.LBB0_2307:
	s_or_b64 exec, exec, s[38:39]
	s_waitcnt lgkmcnt(0)
	v_or_b32_e32 v114, 16, v142
	v_ashrrev_i32_e32 v115, 31, v114
	v_lshlrev_b64 v[114:115], 11, v[114:115]
	v_lshl_add_u64 v[114:115], s[48:49], 0, v[114:115]
	v_lshl_add_u64 v[122:123], v[140:141], 1, v[114:115]
	global_load_dwordx4 v[114:117], v[122:123], off
	global_load_dwordx4 v[118:121], v[122:123], off offset:256
	s_waitcnt vmcnt(1)
	v_lshlrev_b32_e32 v124, 16, v114
	v_and_b32_e32 v125, 0xffff0000, v114
	v_lshlrev_b32_e32 v114, 16, v115
	v_and_b32_e32 v115, 0xffff0000, v115
	s_waitcnt vmcnt(0)
	v_lshlrev_b32_e32 v160, 16, v118
	v_and_b32_e32 v161, 0xffff0000, v118
	v_lshlrev_b32_e32 v118, 16, v119
	v_and_b32_e32 v119, 0xffff0000, v119
	v_lshlrev_b32_e32 v126, 16, v116
	v_and_b32_e32 v127, 0xffff0000, v116
	v_lshlrev_b32_e32 v116, 16, v117
	v_and_b32_e32 v117, 0xffff0000, v117
	v_lshlrev_b32_e32 v162, 16, v120
	v_and_b32_e32 v163, 0xffff0000, v120
	v_lshlrev_b32_e32 v120, 16, v121
	v_and_b32_e32 v121, 0xffff0000, v121
	v_pk_add_f32 v[110:111], v[110:111], v[114:115]
	v_pk_add_f32 v[108:109], v[108:109], v[124:125]
	v_pk_add_f32 v[114:115], v[102:103], v[118:119]
	v_pk_add_f32 v[102:103], v[100:101], v[160:161]
	v_pk_add_f32 v[106:107], v[106:107], v[116:117]
	v_pk_add_f32 v[104:105], v[104:105], v[126:127]
	v_pk_add_f32 v[116:117], v[98:99], v[120:121]
	v_pk_add_f32 v[96:97], v[96:97], v[162:163]
	v_cvt_pk_bf16_f32 v98, v108, v109
	v_cvt_pk_bf16_f32 v99, v110, v111
	v_cvt_pk_bf16_f32 v102, v102, v103
	v_cvt_pk_bf16_f32 v103, v114, v115
	v_cvt_pk_bf16_f32 v100, v104, v105
	v_cvt_pk_bf16_f32 v101, v106, v107
	v_cvt_pk_bf16_f32 v104, v96, v97
	v_cvt_pk_bf16_f32 v105, v116, v117
	v_and_b32_e32 v97, 0xffff0000, v98
	v_and_b32_e32 v107, 0xffff0000, v99
	v_and_b32_e32 v114, 0xffff0000, v102
	v_and_b32_e32 v116, 0xffff0000, v103
	v_lshlrev_b32_e32 v96, 16, v98
	v_lshlrev_b32_e32 v106, 16, v99
	v_and_b32_e32 v109, 0xffff0000, v100
	v_lshlrev_b32_e32 v113, 16, v102
	v_lshlrev_b32_e32 v115, 16, v103
	v_and_b32_e32 v118, 0xffff0000, v104
	v_mul_f32_e32 v97, v97, v97
	v_mul_f32_e32 v107, v107, v107
	v_mul_f32_e32 v114, v114, v114
	v_mul_f32_e32 v116, v116, v116
	v_lshlrev_b32_e32 v108, 16, v100
	v_and_b32_e32 v111, 0xffff0000, v101
	v_lshlrev_b32_e32 v117, 16, v104
	v_and_b32_e32 v120, 0xffff0000, v105
	v_mul_f32_e32 v109, v109, v109
	v_mul_f32_e32 v118, v118, v118
	v_fmac_f32_e32 v97, v96, v96
	v_fmac_f32_e32 v107, v106, v106
	v_fmac_f32_e32 v114, v113, v113
	v_fmac_f32_e32 v116, v115, v115
	v_lshlrev_b32_e32 v110, 16, v101
	v_lshlrev_b32_e32 v119, 16, v105
	v_mul_f32_e32 v111, v111, v111
	v_mul_f32_e32 v120, v120, v120
	v_fmac_f32_e32 v109, v108, v108
	v_fmac_f32_e32 v118, v117, v117
	v_add_f32_e32 v96, v97, v107
	v_add_f32_e32 v97, v114, v116
	v_fmac_f32_e32 v111, v110, v110
	v_fmac_f32_e32 v120, v119, v119
	v_add_f32_e32 v96, v109, v96
	v_add_f32_e32 v97, v118, v97
	v_add_f32_e32 v96, v111, v96
	v_add_f32_e32 v97, v120, v97
	v_add_f32_e32 v96, v96, v97
	v_mov_b32_e32 v97, v96
	v_mov_b32_e32 v159, v96
	s_nop 1
	v_permlane16_swap_b32_e32 v97, v159
	global_store_dwordx4 v[122:123], v[98:101], off
	global_store_dwordx4 v[122:123], v[102:105], off offset:256
	s_waitcnt lgkmcnt(0)
	v_add_f32_e32 v96, v159, v97
	v_mov_b32_e32 v97, v96
	v_mov_b32_e32 v112, v96
	s_nop 1
	v_permlane32_swap_b32_e32 v97, v112
	s_and_saveexec_b64 s[38:39], s[8:9]
	s_cbranch_execz .LBB0_2309
	s_waitcnt lgkmcnt(0)
	v_add_f32_e32 v96, v112, v97
	ds_write_b32 v152, v96
.LBB0_2309:
	s_or_b64 exec, exec, s[38:39]
	v_or_b32_e32 v96, 32, v142
	s_waitcnt lgkmcnt(0)
	v_ashrrev_i32_e32 v97, 31, v96
	v_lshlrev_b64 v[96:97], 11, v[96:97]
	v_lshl_add_u64 v[96:97], s[48:49], 0, v[96:97]
	v_lshl_add_u64 v[104:105], v[140:141], 1, v[96:97]
	global_load_dwordx4 v[96:99], v[104:105], off
	global_load_dwordx4 v[100:103], v[104:105], off offset:256
	s_waitcnt vmcnt(1)
	v_lshlrev_b32_e32 v106, 16, v96
	v_and_b32_e32 v107, 0xffff0000, v96
	v_lshlrev_b32_e32 v96, 16, v97
	v_and_b32_e32 v97, 0xffff0000, v97
	s_waitcnt vmcnt(0)
	v_lshlrev_b32_e32 v110, 16, v100
	v_and_b32_e32 v111, 0xffff0000, v100
	v_lshlrev_b32_e32 v100, 16, v101
	v_and_b32_e32 v101, 0xffff0000, v101
	v_lshlrev_b32_e32 v108, 16, v98
	v_and_b32_e32 v109, 0xffff0000, v98
	v_lshlrev_b32_e32 v98, 16, v99
	v_and_b32_e32 v99, 0xffff0000, v99
	v_lshlrev_b32_e32 v114, 16, v102
	v_and_b32_e32 v115, 0xffff0000, v102
	v_lshlrev_b32_e32 v102, 16, v103
	v_and_b32_e32 v103, 0xffff0000, v103
	v_pk_add_f32 v[94:95], v[94:95], v[96:97]
	v_pk_add_f32 v[92:93], v[92:93], v[106:107]
	v_pk_add_f32 v[96:97], v[86:87], v[100:101]
	v_pk_add_f32 v[86:87], v[84:85], v[110:111]
	v_pk_add_f32 v[90:91], v[90:91], v[98:99]
	v_pk_add_f32 v[88:89], v[88:89], v[108:109]
	v_pk_add_f32 v[98:99], v[82:83], v[102:103]
	v_pk_add_f32 v[80:81], v[80:81], v[114:115]
	v_cvt_pk_bf16_f32 v82, v92, v93
	v_cvt_pk_bf16_f32 v83, v94, v95
	v_cvt_pk_bf16_f32 v86, v86, v87
	v_cvt_pk_bf16_f32 v87, v96, v97
	v_cvt_pk_bf16_f32 v84, v88, v89
	v_cvt_pk_bf16_f32 v85, v90, v91
	v_cvt_pk_bf16_f32 v88, v80, v81
	v_cvt_pk_bf16_f32 v89, v98, v99
	v_and_b32_e32 v81, 0xffff0000, v82
	v_and_b32_e32 v91, 0xffff0000, v83
	v_and_b32_e32 v97, 0xffff0000, v86
	v_and_b32_e32 v99, 0xffff0000, v87
	v_lshlrev_b32_e32 v80, 16, v82
	v_lshlrev_b32_e32 v90, 16, v83
	v_and_b32_e32 v93, 0xffff0000, v84
	v_lshlrev_b32_e32 v96, 16, v86
	v_lshlrev_b32_e32 v98, 16, v87
	v_and_b32_e32 v101, 0xffff0000, v88
	v_mul_f32_e32 v81, v81, v81
	v_mul_f32_e32 v91, v91, v91
	v_mul_f32_e32 v97, v97, v97
	v_mul_f32_e32 v99, v99, v99
	v_lshlrev_b32_e32 v92, 16, v84
	v_and_b32_e32 v95, 0xffff0000, v85
	v_lshlrev_b32_e32 v100, 16, v88
	v_and_b32_e32 v103, 0xffff0000, v89
	v_mul_f32_e32 v93, v93, v93
	v_mul_f32_e32 v101, v101, v101
	v_fmac_f32_e32 v81, v80, v80
	v_fmac_f32_e32 v91, v90, v90
	v_fmac_f32_e32 v97, v96, v96
	v_fmac_f32_e32 v99, v98, v98
	v_lshlrev_b32_e32 v94, 16, v85
	v_lshlrev_b32_e32 v102, 16, v89
	v_mul_f32_e32 v95, v95, v95
	v_mul_f32_e32 v103, v103, v103
	v_fmac_f32_e32 v93, v92, v92
	v_fmac_f32_e32 v101, v100, v100
	v_add_f32_e32 v80, v81, v91
	v_add_f32_e32 v81, v97, v99
	v_fmac_f32_e32 v95, v94, v94
	v_fmac_f32_e32 v103, v102, v102
	v_add_f32_e32 v80, v93, v80
	v_add_f32_e32 v81, v101, v81
	v_add_f32_e32 v80, v95, v80
	v_add_f32_e32 v81, v103, v81
	v_add_f32_e32 v80, v80, v81
	v_mov_b32_e32 v81, v80
	v_mov_b32_e32 v159, v80
	s_nop 1
	v_permlane16_swap_b32_e32 v81, v159
	global_store_dwordx4 v[104:105], v[82:85], off
	global_store_dwordx4 v[104:105], v[86:89], off offset:256
	s_waitcnt lgkmcnt(0)
	v_add_f32_e32 v80, v159, v81
	v_mov_b32_e32 v81, v80
	v_mov_b32_e32 v112, v80
	s_nop 1
	v_permlane32_swap_b32_e32 v81, v112
	s_and_saveexec_b64 s[38:39], s[8:9]
	s_cbranch_execz .LBB0_2311
	s_waitcnt lgkmcnt(0)
	v_add_f32_e32 v80, v112, v81
	ds_write_b32 v153, v80
.LBB0_2311:
	s_or_b64 exec, exec, s[38:39]
	v_or_b32_e32 v80, 48, v142
	s_waitcnt lgkmcnt(0)
	v_ashrrev_i32_e32 v81, 31, v80
	v_lshlrev_b64 v[80:81], 11, v[80:81]
	v_lshl_add_u64 v[80:81], s[48:49], 0, v[80:81]
	v_lshl_add_u64 v[88:89], v[140:141], 1, v[80:81]
	global_load_dwordx4 v[80:83], v[88:89], off
	global_load_dwordx4 v[84:87], v[88:89], off offset:256
	s_waitcnt vmcnt(1)
	v_lshlrev_b32_e32 v90, 16, v80
	v_and_b32_e32 v91, 0xffff0000, v80
	v_lshlrev_b32_e32 v80, 16, v81
	v_and_b32_e32 v81, 0xffff0000, v81
	s_waitcnt vmcnt(0)
	v_lshlrev_b32_e32 v94, 16, v84
	v_and_b32_e32 v95, 0xffff0000, v84
	v_lshlrev_b32_e32 v84, 16, v85
	v_and_b32_e32 v85, 0xffff0000, v85
	v_lshlrev_b32_e32 v92, 16, v82
	v_and_b32_e32 v93, 0xffff0000, v82
	v_lshlrev_b32_e32 v82, 16, v83
	v_and_b32_e32 v83, 0xffff0000, v83
	v_lshlrev_b32_e32 v96, 16, v86
	v_and_b32_e32 v97, 0xffff0000, v86
	v_lshlrev_b32_e32 v86, 16, v87
	v_and_b32_e32 v87, 0xffff0000, v87
	v_pk_add_f32 v[78:79], v[78:79], v[80:81]
	v_pk_add_f32 v[76:77], v[76:77], v[90:91]
	v_pk_add_f32 v[80:81], v[70:71], v[84:85]
	v_pk_add_f32 v[70:71], v[68:69], v[94:95]
	v_pk_add_f32 v[74:75], v[74:75], v[82:83]
	v_pk_add_f32 v[72:73], v[72:73], v[92:93]
	v_pk_add_f32 v[82:83], v[66:67], v[86:87]
	v_pk_add_f32 v[64:65], v[64:65], v[96:97]
	v_cvt_pk_bf16_f32 v66, v76, v77
	v_cvt_pk_bf16_f32 v67, v78, v79
	v_cvt_pk_bf16_f32 v70, v70, v71
	v_cvt_pk_bf16_f32 v71, v80, v81
	v_cvt_pk_bf16_f32 v68, v72, v73
	v_cvt_pk_bf16_f32 v69, v74, v75
	v_cvt_pk_bf16_f32 v72, v64, v65
	v_cvt_pk_bf16_f32 v73, v82, v83
	v_and_b32_e32 v65, 0xffff0000, v66
	v_and_b32_e32 v75, 0xffff0000, v67
	v_and_b32_e32 v81, 0xffff0000, v70
	v_and_b32_e32 v83, 0xffff0000, v71
	v_lshlrev_b32_e32 v64, 16, v66
	v_lshlrev_b32_e32 v74, 16, v67
	v_and_b32_e32 v77, 0xffff0000, v68
	v_lshlrev_b32_e32 v80, 16, v70
	v_lshlrev_b32_e32 v82, 16, v71
	v_and_b32_e32 v85, 0xffff0000, v72
	v_mul_f32_e32 v65, v65, v65
	v_mul_f32_e32 v75, v75, v75
	v_mul_f32_e32 v81, v81, v81
	v_mul_f32_e32 v83, v83, v83
	v_lshlrev_b32_e32 v76, 16, v68
	v_and_b32_e32 v79, 0xffff0000, v69
	v_lshlrev_b32_e32 v84, 16, v72
	v_and_b32_e32 v87, 0xffff0000, v73
	v_mul_f32_e32 v77, v77, v77
	v_mul_f32_e32 v85, v85, v85
	v_fmac_f32_e32 v65, v64, v64
	v_fmac_f32_e32 v75, v74, v74
	v_fmac_f32_e32 v81, v80, v80
	v_fmac_f32_e32 v83, v82, v82
	v_lshlrev_b32_e32 v78, 16, v69
	v_lshlrev_b32_e32 v86, 16, v73
	v_mul_f32_e32 v79, v79, v79
	v_mul_f32_e32 v87, v87, v87
	v_fmac_f32_e32 v77, v76, v76
	v_fmac_f32_e32 v85, v84, v84
	v_add_f32_e32 v64, v65, v75
	v_add_f32_e32 v65, v81, v83
	v_fmac_f32_e32 v79, v78, v78
	v_fmac_f32_e32 v87, v86, v86
	v_add_f32_e32 v64, v77, v64
	v_add_f32_e32 v65, v85, v65
	v_add_f32_e32 v64, v79, v64
	v_add_f32_e32 v65, v87, v65
	v_add_f32_e32 v64, v64, v65
	v_mov_b32_e32 v65, v64
	v_mov_b32_e32 v159, v64
	s_nop 1
	v_permlane16_swap_b32_e32 v65, v159
	global_store_dwordx4 v[88:89], v[66:69], off
	global_store_dwordx4 v[88:89], v[70:73], off offset:256
	s_waitcnt lgkmcnt(0)
	v_add_f32_e32 v64, v159, v65
	v_mov_b32_e32 v65, v64
	v_mov_b32_e32 v112, v64
	s_nop 1
	v_permlane32_swap_b32_e32 v65, v112
	s_and_saveexec_b64 s[38:39], s[8:9]
	s_cbranch_execz .LBB0_2313
	s_waitcnt lgkmcnt(0)
	v_add_f32_e32 v64, v112, v65
	ds_write_b32 v154, v64
.LBB0_2313:
	s_or_b64 exec, exec, s[38:39]
	s_waitcnt lgkmcnt(0)
	v_lshlrev_b64 v[64:65], 11, v[142:143]
	v_lshl_add_u64 v[64:65], s[48:49], 0, v[64:65]
	v_lshl_add_u64 v[64:65], v[140:141], 1, v[64:65]
	v_add_co_u32_e32 v74, vcc, 0x40000, v64
	v_lshl_add_u64 v[76:77], v[64:65], 0, s[12:13]
	s_nop 0
	v_addc_co_u32_e32 v75, vcc, 0, v65, vcc
	global_load_dwordx4 v[66:69], v[74:75], off
	global_load_dwordx4 v[70:73], v[76:77], off offset:256
	s_waitcnt vmcnt(1)
	v_lshlrev_b32_e32 v78, 16, v66
	v_and_b32_e32 v79, 0xffff0000, v66
	v_lshlrev_b32_e32 v66, 16, v67
	v_and_b32_e32 v67, 0xffff0000, v67
	s_waitcnt vmcnt(0)
	v_lshlrev_b32_e32 v82, 16, v70
	v_and_b32_e32 v83, 0xffff0000, v70
	v_lshlrev_b32_e32 v70, 16, v71
	v_and_b32_e32 v71, 0xffff0000, v71
	v_lshlrev_b32_e32 v80, 16, v68
	v_and_b32_e32 v81, 0xffff0000, v68
	v_lshlrev_b32_e32 v68, 16, v69
	v_and_b32_e32 v69, 0xffff0000, v69
	v_lshlrev_b32_e32 v84, 16, v72
	v_and_b32_e32 v85, 0xffff0000, v72
	v_lshlrev_b32_e32 v72, 16, v73
	v_and_b32_e32 v73, 0xffff0000, v73
	v_pk_add_f32 v[62:63], v[62:63], v[66:67]
	v_pk_add_f32 v[60:61], v[60:61], v[78:79]
	v_pk_add_f32 v[66:67], v[54:55], v[70:71]
	v_pk_add_f32 v[54:55], v[52:53], v[82:83]
	v_pk_add_f32 v[58:59], v[58:59], v[68:69]
	v_pk_add_f32 v[56:57], v[56:57], v[80:81]
	v_pk_add_f32 v[68:69], v[50:51], v[72:73]
	v_pk_add_f32 v[48:49], v[48:49], v[84:85]
	v_cvt_pk_bf16_f32 v50, v60, v61
	v_cvt_pk_bf16_f32 v51, v62, v63
	v_cvt_pk_bf16_f32 v54, v54, v55
	v_cvt_pk_bf16_f32 v55, v66, v67
	v_cvt_pk_bf16_f32 v52, v56, v57
	v_cvt_pk_bf16_f32 v53, v58, v59
	v_cvt_pk_bf16_f32 v56, v48, v49
	v_cvt_pk_bf16_f32 v57, v68, v69
	v_and_b32_e32 v49, 0xffff0000, v50
	v_and_b32_e32 v59, 0xffff0000, v51
	v_and_b32_e32 v67, 0xffff0000, v54
	v_and_b32_e32 v69, 0xffff0000, v55
	v_lshlrev_b32_e32 v48, 16, v50
	v_lshlrev_b32_e32 v58, 16, v51
	v_and_b32_e32 v61, 0xffff0000, v52
	v_lshlrev_b32_e32 v66, 16, v54
	v_lshlrev_b32_e32 v68, 16, v55
	v_and_b32_e32 v71, 0xffff0000, v56
	v_mul_f32_e32 v49, v49, v49
	v_mul_f32_e32 v59, v59, v59
	v_mul_f32_e32 v67, v67, v67
	v_mul_f32_e32 v69, v69, v69
	v_lshlrev_b32_e32 v60, 16, v52
	v_and_b32_e32 v63, 0xffff0000, v53
	v_lshlrev_b32_e32 v70, 16, v56
	v_and_b32_e32 v73, 0xffff0000, v57
	v_mul_f32_e32 v61, v61, v61
	v_mul_f32_e32 v71, v71, v71
	v_fmac_f32_e32 v49, v48, v48
	v_fmac_f32_e32 v59, v58, v58
	v_fmac_f32_e32 v67, v66, v66
	v_fmac_f32_e32 v69, v68, v68
	v_lshlrev_b32_e32 v62, 16, v53
	v_lshlrev_b32_e32 v72, 16, v57
	v_mul_f32_e32 v63, v63, v63
	v_mul_f32_e32 v73, v73, v73
	v_fmac_f32_e32 v61, v60, v60
	v_fmac_f32_e32 v71, v70, v70
	v_add_f32_e32 v48, v49, v59
	v_add_f32_e32 v49, v67, v69
	v_fmac_f32_e32 v63, v62, v62
	v_fmac_f32_e32 v73, v72, v72
	v_add_f32_e32 v48, v61, v48
	v_add_f32_e32 v49, v71, v49
	v_add_f32_e32 v48, v63, v48
	v_add_f32_e32 v49, v73, v49
	v_add_f32_e32 v48, v48, v49
	v_mov_b32_e32 v49, v48
	v_mov_b32_e32 v159, v48
	s_nop 1
	v_permlane16_swap_b32_e32 v49, v159
	global_store_dwordx4 v[74:75], v[50:53], off
	global_store_dwordx4 v[76:77], v[54:57], off offset:256
	s_waitcnt lgkmcnt(0)
	v_add_f32_e32 v48, v159, v49
	v_mov_b32_e32 v49, v48
	v_mov_b32_e32 v112, v48
	s_nop 1
	v_permlane32_swap_b32_e32 v49, v112
	s_and_saveexec_b64 s[38:39], s[8:9]
	s_cbranch_execz .LBB0_2315
	s_waitcnt lgkmcnt(0)
	v_add_f32_e32 v48, v112, v49
	ds_write_b32 v155, v48
.LBB0_2315:
	s_or_b64 exec, exec, s[38:39]
	v_add_co_u32_e32 v56, vcc, 0x48000, v64
	v_lshl_add_u64 v[58:59], v[64:65], 0, s[20:21]
	s_nop 0
	v_addc_co_u32_e32 v57, vcc, 0, v65, vcc
	s_waitcnt lgkmcnt(0)
	global_load_dwordx4 v[48:51], v[56:57], off
	global_load_dwordx4 v[52:55], v[58:59], off offset:256
	s_waitcnt vmcnt(1)
	v_lshlrev_b32_e32 v60, 16, v48
	v_and_b32_e32 v61, 0xffff0000, v48
	v_lshlrev_b32_e32 v48, 16, v49
	v_and_b32_e32 v49, 0xffff0000, v49
	s_waitcnt vmcnt(0)
	v_lshlrev_b32_e32 v64, 16, v52
	v_and_b32_e32 v65, 0xffff0000, v52
	v_lshlrev_b32_e32 v52, 16, v53
	v_and_b32_e32 v53, 0xffff0000, v53
	v_lshlrev_b32_e32 v62, 16, v50
	v_and_b32_e32 v63, 0xffff0000, v50
	v_lshlrev_b32_e32 v50, 16, v51
	v_and_b32_e32 v51, 0xffff0000, v51
	v_lshlrev_b32_e32 v66, 16, v54
	v_and_b32_e32 v67, 0xffff0000, v54
	v_lshlrev_b32_e32 v54, 16, v55
	v_and_b32_e32 v55, 0xffff0000, v55
	v_pk_add_f32 v[46:47], v[46:47], v[48:49]
	v_pk_add_f32 v[44:45], v[44:45], v[60:61]
	v_pk_add_f32 v[48:49], v[38:39], v[52:53]
	v_pk_add_f32 v[38:39], v[36:37], v[64:65]
	v_pk_add_f32 v[42:43], v[42:43], v[50:51]
	v_pk_add_f32 v[40:41], v[40:41], v[62:63]
	v_pk_add_f32 v[50:51], v[34:35], v[54:55]
	v_pk_add_f32 v[32:33], v[32:33], v[66:67]
	v_cvt_pk_bf16_f32 v34, v44, v45
	v_cvt_pk_bf16_f32 v35, v46, v47
	v_cvt_pk_bf16_f32 v38, v38, v39
	v_cvt_pk_bf16_f32 v39, v48, v49
	v_cvt_pk_bf16_f32 v36, v40, v41
	v_cvt_pk_bf16_f32 v37, v42, v43
	v_cvt_pk_bf16_f32 v40, v32, v33
	v_cvt_pk_bf16_f32 v41, v50, v51
	v_and_b32_e32 v33, 0xffff0000, v34
	v_and_b32_e32 v43, 0xffff0000, v35
	v_and_b32_e32 v49, 0xffff0000, v38
	v_and_b32_e32 v51, 0xffff0000, v39
	v_lshlrev_b32_e32 v32, 16, v34
	v_lshlrev_b32_e32 v42, 16, v35
	v_and_b32_e32 v45, 0xffff0000, v36
	v_lshlrev_b32_e32 v48, 16, v38
	v_lshlrev_b32_e32 v50, 16, v39
	v_and_b32_e32 v53, 0xffff0000, v40
	v_mul_f32_e32 v33, v33, v33
	v_mul_f32_e32 v43, v43, v43
	v_mul_f32_e32 v49, v49, v49
	v_mul_f32_e32 v51, v51, v51
	v_lshlrev_b32_e32 v44, 16, v36
	v_and_b32_e32 v47, 0xffff0000, v37
	v_lshlrev_b32_e32 v52, 16, v40
	v_and_b32_e32 v55, 0xffff0000, v41
	v_mul_f32_e32 v45, v45, v45
	v_mul_f32_e32 v53, v53, v53
	v_fmac_f32_e32 v33, v32, v32
	v_fmac_f32_e32 v43, v42, v42
	v_fmac_f32_e32 v49, v48, v48
	v_fmac_f32_e32 v51, v50, v50
	v_lshlrev_b32_e32 v46, 16, v37
	v_lshlrev_b32_e32 v54, 16, v41
	v_mul_f32_e32 v47, v47, v47
	v_mul_f32_e32 v55, v55, v55
	v_fmac_f32_e32 v45, v44, v44
	v_fmac_f32_e32 v53, v52, v52
	v_add_f32_e32 v32, v33, v43
	v_add_f32_e32 v33, v49, v51
	v_fmac_f32_e32 v47, v46, v46
	v_fmac_f32_e32 v55, v54, v54
	v_add_f32_e32 v32, v45, v32
	v_add_f32_e32 v33, v53, v33
	v_add_f32_e32 v32, v47, v32
	v_add_f32_e32 v33, v55, v33
	v_add_f32_e32 v32, v32, v33
	v_mov_b32_e32 v33, v32
	v_mov_b32_e32 v159, v32
	s_nop 1
	v_permlane16_swap_b32_e32 v33, v159
	global_store_dwordx4 v[56:57], v[34:37], off
	global_store_dwordx4 v[58:59], v[38:41], off offset:256
	s_waitcnt lgkmcnt(0)
	v_add_f32_e32 v32, v159, v33
	v_mov_b32_e32 v33, v32
	v_mov_b32_e32 v112, v32
	s_nop 1
	v_permlane32_swap_b32_e32 v33, v112
	s_and_saveexec_b64 s[38:39], s[8:9]
	s_cbranch_execz .LBB0_2317
	s_waitcnt lgkmcnt(0)
	v_add_f32_e32 v32, v112, v33
	ds_write_b32 v156, v32
.LBB0_2317:
	s_or_b64 exec, exec, s[38:39]
	s_waitcnt lgkmcnt(0)
	v_lshlrev_b64 v[32:33], 11, v[142:143]
	v_lshl_add_u64 v[32:33], s[48:49], 0, v[32:33]
	v_lshl_add_u64 v[32:33], v[140:141], 1, v[32:33]
	v_add_co_u32_e32 v42, vcc, 0x50000, v32
	v_lshl_add_u64 v[44:45], v[32:33], 0, s[22:23]
	s_nop 0
	v_addc_co_u32_e32 v43, vcc, 0, v33, vcc
	global_load_dwordx4 v[34:37], v[42:43], off
	global_load_dwordx4 v[38:41], v[44:45], off offset:256
	s_waitcnt vmcnt(1)
	v_lshlrev_b32_e32 v46, 16, v34
	v_and_b32_e32 v47, 0xffff0000, v34
	v_lshlrev_b32_e32 v34, 16, v35
	v_and_b32_e32 v35, 0xffff0000, v35
	s_waitcnt vmcnt(0)
	v_lshlrev_b32_e32 v50, 16, v38
	v_and_b32_e32 v51, 0xffff0000, v38
	v_lshlrev_b32_e32 v38, 16, v39
	v_and_b32_e32 v39, 0xffff0000, v39
	v_lshlrev_b32_e32 v48, 16, v36
	v_and_b32_e32 v49, 0xffff0000, v36
	v_lshlrev_b32_e32 v36, 16, v37
	v_and_b32_e32 v37, 0xffff0000, v37
	v_lshlrev_b32_e32 v52, 16, v40
	v_and_b32_e32 v53, 0xffff0000, v40
	v_lshlrev_b32_e32 v40, 16, v41
	v_and_b32_e32 v41, 0xffff0000, v41
	v_pk_add_f32 v[30:31], v[30:31], v[34:35]
	v_pk_add_f32 v[28:29], v[28:29], v[46:47]
	v_pk_add_f32 v[34:35], v[22:23], v[38:39]
	v_pk_add_f32 v[22:23], v[20:21], v[50:51]
	v_pk_add_f32 v[26:27], v[26:27], v[36:37]
	v_pk_add_f32 v[24:25], v[24:25], v[48:49]
	v_pk_add_f32 v[36:37], v[18:19], v[40:41]
	v_pk_add_f32 v[16:17], v[16:17], v[52:53]
	v_cvt_pk_bf16_f32 v18, v28, v29
	v_cvt_pk_bf16_f32 v19, v30, v31
	v_cvt_pk_bf16_f32 v22, v22, v23
	v_cvt_pk_bf16_f32 v23, v34, v35
	v_cvt_pk_bf16_f32 v20, v24, v25
	v_cvt_pk_bf16_f32 v21, v26, v27
	v_cvt_pk_bf16_f32 v24, v16, v17
	v_cvt_pk_bf16_f32 v25, v36, v37
	v_and_b32_e32 v17, 0xffff0000, v18
	v_and_b32_e32 v27, 0xffff0000, v19
	v_and_b32_e32 v35, 0xffff0000, v22
	v_and_b32_e32 v37, 0xffff0000, v23
	v_lshlrev_b32_e32 v16, 16, v18
	v_lshlrev_b32_e32 v26, 16, v19
	v_and_b32_e32 v29, 0xffff0000, v20
	v_lshlrev_b32_e32 v34, 16, v22
	v_lshlrev_b32_e32 v36, 16, v23
	v_and_b32_e32 v39, 0xffff0000, v24
	v_mul_f32_e32 v17, v17, v17
	v_mul_f32_e32 v27, v27, v27
	v_mul_f32_e32 v35, v35, v35
	v_mul_f32_e32 v37, v37, v37
	v_lshlrev_b32_e32 v28, 16, v20
	v_and_b32_e32 v31, 0xffff0000, v21
	v_lshlrev_b32_e32 v38, 16, v24
	v_and_b32_e32 v41, 0xffff0000, v25
	v_mul_f32_e32 v29, v29, v29
	v_mul_f32_e32 v39, v39, v39
	v_fmac_f32_e32 v17, v16, v16
	v_fmac_f32_e32 v27, v26, v26
	v_fmac_f32_e32 v35, v34, v34
	v_fmac_f32_e32 v37, v36, v36
	v_lshlrev_b32_e32 v30, 16, v21
	v_lshlrev_b32_e32 v40, 16, v25
	v_mul_f32_e32 v31, v31, v31
	v_mul_f32_e32 v41, v41, v41
	v_fmac_f32_e32 v29, v28, v28
	v_fmac_f32_e32 v39, v38, v38
	v_add_f32_e32 v16, v17, v27
	v_add_f32_e32 v17, v35, v37
	v_fmac_f32_e32 v31, v30, v30
	v_fmac_f32_e32 v41, v40, v40
	v_add_f32_e32 v16, v29, v16
	v_add_f32_e32 v17, v39, v17
	v_add_f32_e32 v16, v31, v16
	v_add_f32_e32 v17, v41, v17
	v_add_f32_e32 v16, v16, v17
	v_mov_b32_e32 v17, v16
	v_mov_b32_e32 v159, v16
	s_nop 1
	v_permlane16_swap_b32_e32 v17, v159
	global_store_dwordx4 v[42:43], v[18:21], off
	global_store_dwordx4 v[44:45], v[22:25], off offset:256
	s_waitcnt lgkmcnt(0)
	v_add_f32_e32 v16, v159, v17
	v_mov_b32_e32 v17, v16
	v_mov_b32_e32 v112, v16
	s_nop 1
	v_permlane32_swap_b32_e32 v17, v112
	s_and_saveexec_b64 s[38:39], s[8:9]
	s_cbranch_execz .LBB0_2319
	s_waitcnt lgkmcnt(0)
	v_add_f32_e32 v16, v112, v17
	ds_write_b32 v157, v16
.LBB0_2319:
	s_or_b64 exec, exec, s[38:39]
	v_add_co_u32_e32 v24, vcc, 0x58000, v32
	v_lshl_add_u64 v[26:27], v[32:33], 0, s[24:25]
	s_nop 0
	v_addc_co_u32_e32 v25, vcc, 0, v33, vcc
	s_waitcnt lgkmcnt(0)
	global_load_dwordx4 v[16:19], v[24:25], off
	global_load_dwordx4 v[20:23], v[26:27], off offset:256
	s_waitcnt vmcnt(1)
	v_lshlrev_b32_e32 v28, 16, v16
	v_and_b32_e32 v29, 0xffff0000, v16
	v_lshlrev_b32_e32 v16, 16, v17
	v_and_b32_e32 v17, 0xffff0000, v17
	s_waitcnt vmcnt(0)
	v_lshlrev_b32_e32 v32, 16, v20
	v_and_b32_e32 v33, 0xffff0000, v20
	v_lshlrev_b32_e32 v20, 16, v21
	v_and_b32_e32 v21, 0xffff0000, v21
	v_lshlrev_b32_e32 v30, 16, v18
	v_and_b32_e32 v31, 0xffff0000, v18
	v_lshlrev_b32_e32 v18, 16, v19
	v_and_b32_e32 v19, 0xffff0000, v19
	v_lshlrev_b32_e32 v34, 16, v22
	v_and_b32_e32 v35, 0xffff0000, v22
	v_lshlrev_b32_e32 v22, 16, v23
	v_and_b32_e32 v23, 0xffff0000, v23
	v_pk_add_f32 v[14:15], v[14:15], v[16:17]
	v_pk_add_f32 v[12:13], v[12:13], v[28:29]
	v_pk_add_f32 v[16:17], v[6:7], v[20:21]
	v_pk_add_f32 v[6:7], v[4:5], v[32:33]
	v_pk_add_f32 v[10:11], v[10:11], v[18:19]
	v_pk_add_f32 v[8:9], v[8:9], v[30:31]
	v_pk_add_f32 v[18:19], v[2:3], v[22:23]
	v_pk_add_f32 v[0:1], v[0:1], v[34:35]
	v_cvt_pk_bf16_f32 v2, v12, v13
	v_cvt_pk_bf16_f32 v3, v14, v15
	v_cvt_pk_bf16_f32 v6, v6, v7
	v_cvt_pk_bf16_f32 v7, v16, v17
	v_cvt_pk_bf16_f32 v4, v8, v9
	v_cvt_pk_bf16_f32 v5, v10, v11
	v_cvt_pk_bf16_f32 v8, v0, v1
	v_cvt_pk_bf16_f32 v9, v18, v19
	v_and_b32_e32 v1, 0xffff0000, v2
	v_and_b32_e32 v11, 0xffff0000, v3
	v_and_b32_e32 v17, 0xffff0000, v6
	v_and_b32_e32 v19, 0xffff0000, v7
	v_lshlrev_b32_e32 v0, 16, v2
	v_lshlrev_b32_e32 v10, 16, v3
	v_and_b32_e32 v13, 0xffff0000, v4
	v_lshlrev_b32_e32 v16, 16, v6
	v_lshlrev_b32_e32 v18, 16, v7
	v_and_b32_e32 v21, 0xffff0000, v8
	v_mul_f32_e32 v1, v1, v1
	v_mul_f32_e32 v11, v11, v11
	v_mul_f32_e32 v17, v17, v17
	v_mul_f32_e32 v19, v19, v19
	v_lshlrev_b32_e32 v12, 16, v4
	v_and_b32_e32 v15, 0xffff0000, v5
	v_lshlrev_b32_e32 v20, 16, v8
	v_and_b32_e32 v23, 0xffff0000, v9
	v_mul_f32_e32 v13, v13, v13
	v_mul_f32_e32 v21, v21, v21
	v_fmac_f32_e32 v1, v0, v0
	v_fmac_f32_e32 v11, v10, v10
	v_fmac_f32_e32 v17, v16, v16
	v_fmac_f32_e32 v19, v18, v18
	v_lshlrev_b32_e32 v14, 16, v5
	v_lshlrev_b32_e32 v22, 16, v9
	v_mul_f32_e32 v15, v15, v15
	v_mul_f32_e32 v23, v23, v23
	v_fmac_f32_e32 v13, v12, v12
	v_fmac_f32_e32 v21, v20, v20
	v_add_f32_e32 v0, v1, v11
	v_add_f32_e32 v1, v17, v19
	v_fmac_f32_e32 v15, v14, v14
	v_fmac_f32_e32 v23, v22, v22
	v_add_f32_e32 v0, v13, v0
	v_add_f32_e32 v1, v21, v1
	v_add_f32_e32 v0, v15, v0
	v_add_f32_e32 v1, v23, v1
	v_add_f32_e32 v0, v0, v1
	v_mov_b32_e32 v1, v0
	v_mov_b32_e32 v159, v0
	s_nop 1
	v_permlane16_swap_b32_e32 v1, v159
	global_store_dwordx4 v[24:25], v[2:5], off
	global_store_dwordx4 v[26:27], v[6:9], off offset:256
	s_waitcnt lgkmcnt(0)
	v_add_f32_e32 v0, v159, v1
	v_mov_b32_e32 v1, v0
	v_mov_b32_e32 v112, v0
	s_nop 1
	v_permlane32_swap_b32_e32 v1, v112
	s_and_saveexec_b64 s[38:39], s[8:9]
	s_cbranch_execz .LBB0_2321
	s_waitcnt lgkmcnt(0)
	v_add_f32_e32 v0, v112, v1
	ds_write_b32 v158, v0
